# removed post-prefetch vmcnt(0) in 7 GEMM k-loops so LDS-DMA of next stage overlaps MFMAs
# speedup vs baseline: 1.0647x; 1.0647x over previous
.LBB0_140:
	v_mov_b32_e32 v66, v182
	s_waitcnt vmcnt(0)
	s_waitcnt vmcnt(0) lgkmcnt(0)
	s_barrier
	s_add_i32 s4, s15, 0xffff8000
	v_ashrrev_i32_e32 v68, 3, v66
	v_lshrrev_b32_e32 v67, 4, v66
	v_add_u32_e32 v64, s14, v68
	s_and_b32 s16, s4, 0x8000
	s_and_b32 s4, s15, 0x8000
	v_ashrrev_i32_e32 v65, 31, v64
	v_bitop3_b32 v67, v67, 7, v66 bitop3:0x48
	v_lshlrev_b64 v[64:65], 11, v[64:65]
	v_lshlrev_b32_e32 v67, 4, v67
	s_add_u32 s10, s30, s8
	v_or_b32_e32 v64, v64, v67
	s_addc_u32 s11, s31, s9
	v_lshl_add_u32 v69, v66, 4, s4
	v_lshl_add_u64 v[64:65], s[10:11], 0, v[64:65]
	v_readfirstlane_b32 s5, v69
	v_add_u32_e32 v70, 0x100, v66
	v_lshl_add_u64 v[64:65], v[64:65], 0, s[90:91]
	s_mov_b32 m0, s5
	v_ashrrev_i32_e32 v71, 3, v70
	global_load_lds_dwordx4 v[64:65], off
	v_add_u32_e32 v64, s14, v71
	v_ashrrev_i32_e32 v65, 31, v64
	v_lshlrev_b64 v[64:65], 11, v[64:65]
	v_or_b32_e32 v64, v64, v67
	v_lshl_add_u32 v70, v70, 4, s4
	v_lshl_add_u64 v[64:65], s[10:11], 0, v[64:65]
	v_readfirstlane_b32 s5, v70
	v_add_u32_e32 v72, 0x200, v66
	v_lshl_add_u64 v[64:65], v[64:65], 0, s[90:91]
	s_mov_b32 m0, s5
	v_ashrrev_i32_e32 v73, 3, v72
	global_load_lds_dwordx4 v[64:65], off
	v_add_u32_e32 v64, s14, v73
	v_ashrrev_i32_e32 v65, 31, v64
	v_lshlrev_b64 v[64:65], 11, v[64:65]
	v_or_b32_e32 v64, v64, v67
	v_lshl_add_u32 v72, v72, 4, s4
	v_lshl_add_u64 v[64:65], s[10:11], 0, v[64:65]
	v_readfirstlane_b32 s5, v72
	v_add_u32_e32 v66, 0x300, v66
	v_lshl_add_u64 v[64:65], v[64:65], 0, s[90:91]
	s_mov_b32 m0, s5
	v_ashrrev_i32_e32 v74, 3, v66
	global_load_lds_dwordx4 v[64:65], off
	v_add_u32_e32 v64, s14, v74
	v_ashrrev_i32_e32 v65, 31, v64
	v_lshlrev_b64 v[64:65], 11, v[64:65]
	v_or_b32_e32 v64, v64, v67
	v_lshl_add_u32 v66, v66, 4, s4
	v_lshl_add_u64 v[64:65], s[10:11], 0, v[64:65]
	v_readfirstlane_b32 s4, v66
	v_lshl_add_u64 v[64:65], v[64:65], 0, s[90:91]
	s_mov_b32 m0, s4
	v_add_u32_e32 v66, 0x4000, v66
	global_load_lds_dwordx4 v[64:65], off
	v_add_u32_e32 v64, s0, v68
	v_ashrrev_i32_e32 v65, 31, v64
	v_lshlrev_b64 v[64:65], 11, v[64:65]
	v_or_b32_e32 v64, v64, v67
	v_add_u32_e32 v68, 0x4000, v69
	v_lshl_add_u64 v[64:65], s[10:11], 0, v[64:65]
	v_readfirstlane_b32 s4, v68
	v_lshl_add_u64 v[64:65], v[64:65], 0, s[72:73]
	s_mov_b32 m0, s4
	v_add_u32_e32 v68, 0x4000, v70
	global_load_lds_dwordx4 v[64:65], off
	v_add_u32_e32 v64, s0, v71
	v_ashrrev_i32_e32 v65, 31, v64
	v_lshlrev_b64 v[64:65], 11, v[64:65]
	v_or_b32_e32 v64, v64, v67
	v_lshl_add_u64 v[64:65], s[10:11], 0, v[64:65]
	v_readfirstlane_b32 s4, v68
	v_lshl_add_u64 v[64:65], v[64:65], 0, s[72:73]
	s_mov_b32 m0, s4
	v_add_u32_e32 v68, 0x4000, v72
	global_load_lds_dwordx4 v[64:65], off
	v_add_u32_e32 v64, s0, v73
	v_ashrrev_i32_e32 v65, 31, v64
	v_lshlrev_b64 v[64:65], 11, v[64:65]
	v_or_b32_e32 v64, v64, v67
	v_lshl_add_u64 v[64:65], s[10:11], 0, v[64:65]
	v_readfirstlane_b32 s4, v68
	v_lshl_add_u64 v[64:65], v[64:65], 0, s[72:73]
	s_mov_b32 m0, s4
	v_readfirstlane_b32 s4, v66
	global_load_lds_dwordx4 v[64:65], off
	v_add_u32_e32 v64, s0, v74
	v_ashrrev_i32_e32 v65, 31, v64
	v_lshlrev_b64 v[64:65], 11, v[64:65]
	v_or_b32_e32 v64, v64, v67
	v_lshl_add_u64 v[64:65], s[10:11], 0, v[64:65]
	v_lshl_add_u64 v[64:65], v[64:65], 0, s[72:73]
	s_mov_b32 m0, s4
	v_or_b32_e32 v91, s16, v84
	global_load_lds_dwordx4 v[64:65], off
	v_add3_u32 v64, v91, v85, v83
	v_add3_u32 v91, v91, v82, v83
	ds_read_b128 v[76:79], v64
	ds_read_b128 v[72:75], v64 offset:2048
	ds_read_b128 v[68:71], v64 offset:4096
	ds_read_b128 v[64:67], v64 offset:6144
	ds_read_b128 v[92:95], v91 offset:16384
	ds_read_b128 v[96:99], v91 offset:18432
	ds_read_b128 v[100:103], v91 offset:20480
	ds_read_b128 v[104:107], v91 offset:22528
	v_or_b32_e32 v91, s16, v81
	s_waitcnt lgkmcnt(0)
	v_mfma_f32_16x16x32_f16 v[60:63], v[76:79], v[92:95], v[60:63]
	s_add_u32 s8, s8, 0x80
	s_addc_u32 s9, s9, 0
	s_add_i32 s15, s15, 0x8000
	v_mfma_f32_16x16x32_f16 v[56:59], v[76:79], v[96:99], v[56:59]
	s_cmpk_eq_i32 s8, 0x780
	v_mfma_f32_16x16x32_f16 v[52:55], v[76:79], v[100:103], v[52:55]
	v_mfma_f32_16x16x32_f16 v[48:51], v[76:79], v[104:107], v[48:51]
	v_add3_u32 v76, v91, v85, v83
	v_add3_u32 v91, v91, v82, v83
	v_mfma_f32_16x16x32_f16 v[44:47], v[72:75], v[92:95], v[44:47]
	v_mfma_f32_16x16x32_f16 v[40:43], v[72:75], v[96:99], v[40:43]
	v_mfma_f32_16x16x32_f16 v[36:39], v[72:75], v[100:103], v[36:39]
	v_mfma_f32_16x16x32_f16 v[32:35], v[72:75], v[104:107], v[32:35]
	v_mfma_f32_16x16x32_f16 v[28:31], v[68:71], v[92:95], v[28:31]
	v_mfma_f32_16x16x32_f16 v[24:27], v[68:71], v[96:99], v[24:27]
	v_mfma_f32_16x16x32_f16 v[20:23], v[68:71], v[100:103], v[20:23]
	v_mfma_f32_16x16x32_f16 v[16:19], v[68:71], v[104:107], v[16:19]
	v_mfma_f32_16x16x32_f16 v[12:15], v[64:67], v[92:95], v[12:15]
	v_mfma_f32_16x16x32_f16 v[8:11], v[64:67], v[96:99], v[8:11]
	v_mfma_f32_16x16x32_f16 v[4:7], v[64:67], v[100:103], v[4:7]
	v_mfma_f32_16x16x32_f16 v[0:3], v[64:67], v[104:107], v[0:3]
	ds_read_b128 v[64:67], v76
	ds_read_b128 v[68:71], v76 offset:2048
	ds_read_b128 v[72:75], v76 offset:4096
	ds_read_b128 v[76:79], v76 offset:6144
	ds_read_b128 v[92:95], v91 offset:16384
	ds_read_b128 v[96:99], v91 offset:18432
	ds_read_b128 v[100:103], v91 offset:20480
	ds_read_b128 v[104:107], v91 offset:22528
	s_waitcnt lgkmcnt(3)
	v_mfma_f32_16x16x32_f16 v[60:63], v[64:67], v[92:95], v[60:63]
	s_waitcnt lgkmcnt(2)
	v_mfma_f32_16x16x32_f16 v[56:59], v[64:67], v[96:99], v[56:59]
	s_waitcnt lgkmcnt(1)
	v_mfma_f32_16x16x32_f16 v[52:55], v[64:67], v[100:103], v[52:55]
	s_waitcnt lgkmcnt(0)
	v_mfma_f32_16x16x32_f16 v[48:51], v[64:67], v[104:107], v[48:51]
	v_mfma_f32_16x16x32_f16 v[44:47], v[68:71], v[92:95], v[44:47]
	v_mfma_f32_16x16x32_f16 v[40:43], v[68:71], v[96:99], v[40:43]
	v_mfma_f32_16x16x32_f16 v[36:39], v[68:71], v[100:103], v[36:39]
	v_mfma_f32_16x16x32_f16 v[32:35], v[68:71], v[104:107], v[32:35]
	v_mfma_f32_16x16x32_f16 v[28:31], v[72:75], v[92:95], v[28:31]
	v_mfma_f32_16x16x32_f16 v[24:27], v[72:75], v[96:99], v[24:27]
	v_mfma_f32_16x16x32_f16 v[20:23], v[72:75], v[100:103], v[20:23]
	v_mfma_f32_16x16x32_f16 v[16:19], v[72:75], v[104:107], v[16:19]
	v_mfma_f32_16x16x32_f16 v[12:15], v[76:79], v[92:95], v[12:15]
	v_mfma_f32_16x16x32_f16 v[8:11], v[76:79], v[96:99], v[8:11]
	v_mfma_f32_16x16x32_f16 v[4:7], v[76:79], v[100:103], v[4:7]
	v_mfma_f32_16x16x32_f16 v[0:3], v[76:79], v[104:107], v[0:3]
	s_cbranch_scc0 .LBB0_140
	s_waitcnt vmcnt(0)
	s_barrier
	ds_read_b128 v[64:67], v90 offset:32768
	ds_read_b128 v[68:71], v89 offset:49152
	ds_read_b128 v[72:75], v89 offset:51200
	ds_read_b128 v[76:79], v89 offset:53248
	ds_read_b128 v[92:95], v89 offset:55296
	ds_read_b128 v[96:99], v90 offset:34816
	ds_read_b128 v[100:103], v88 offset:32768
	ds_read_b128 v[104:107], v88 offset:34816
	ds_read_b128 v[108:111], v87 offset:51200
	ds_read_b128 v[116:119], v87 offset:49152
	s_waitcnt lgkmcnt(8)
	v_mfma_f32_16x16x32_f16 v[60:63], v[64:67], v[68:71], v[60:63]
	ds_read_b128 v[124:127], v87 offset:55296
	ds_read_b128 v[128:131], v87 offset:53248
	ds_read_b128 v[132:135], v88 offset:38912
	ds_read_b128 v[136:139], v88 offset:36864
	s_add_i32 s12, s12, s60
	s_cmp_ge_i32 s12, s62
	s_waitcnt lgkmcnt(4)
	v_mfma_f32_16x16x32_f16 v[60:63], v[100:103], v[116:119], v[60:63]
	v_mfma_f32_16x16x32_f16 v[56:59], v[64:67], v[72:75], v[56:59]
	v_mfma_f32_16x16x32_f16 v[52:55], v[64:67], v[76:79], v[52:55]
	v_mfma_f32_16x16x32_f16 v[64:67], v[64:67], v[92:95], v[48:51]
	v_mfma_f32_16x16x32_f16 v[120:123], v[96:99], v[72:75], v[40:43]
	s_nop 2
	ds_read_b128 v[40:43], v90 offset:38912
	ds_read_b128 v[140:143], v90 offset:36864
	v_mul_f32_e32 v48, 0xbfb8aa3b, v60
	v_exp_f32_e32 v49, v48
	s_waitcnt lgkmcnt(0)
	v_mfma_f32_16x16x32_f16 v[28:31], v[140:143], v[68:71], v[28:31]
	v_add_f32_e32 v51, 1.0, v49
	v_lshl_or_b32 v48, s13, 6, v86
	v_add_u32_e32 v50, s14, v80
	v_mfma_f32_16x16x32_f16 v[144:147], v[140:143], v[72:75], v[24:27]
	v_ashrrev_i32_e32 v49, 31, v48
	v_lshl_add_u64 v[48:49], v[48:49], 1, s[30:31]
	v_mad_i64_i32 v[148:149], s[8:9], v50, s64, v[48:49]
	v_mfma_f32_16x16x32_f16 v[20:23], v[140:143], v[76:79], v[20:23]
	v_div_scale_f32 v24, vcc, v60, v51, v60
	v_mfma_f32_16x16x32_f16 v[140:143], v[140:143], v[92:95], v[16:19]
	s_nop 2
	v_mul_f32_e32 v17, 0xbfb8aa3b, v61
	v_mfma_f32_16x16x32_f16 v[44:47], v[96:99], v[68:71], v[44:47]
	v_exp_f32_e32 v17, v17
	v_mfma_f32_16x16x32_f16 v[36:39], v[96:99], v[76:79], v[36:39]
	v_mfma_f32_16x16x32_f16 v[96:99], v[96:99], v[92:95], v[32:35]
	s_nop 2
	v_div_scale_f32 v32, s[8:9], v51, v51, v60
	v_rcp_f32_e32 v33, v32
	v_mfma_f32_16x16x32_f16 v[12:15], v[40:43], v[68:71], v[12:15]
	v_fma_f32 v34, -v32, v33, 1.0
	v_mfma_f32_16x16x32_f16 v[68:71], v[40:43], v[72:75], v[8:11]
	v_fmac_f32_e32 v33, v34, v33
	v_mul_f32_e32 v25, v24, v33
	v_fma_f32 v26, -v32, v25, v24
	v_add_f32_e32 v8, 1.0, v17
	v_div_scale_f32 v9, s[8:9], v8, v8, v61
	v_rcp_f32_e32 v10, v9
	v_fmac_f32_e32 v25, v26, v33
	v_fma_f32 v16, -v32, v25, v24
	v_mfma_f32_16x16x32_f16 v[72:75], v[40:43], v[92:95], v[0:3]
	v_div_fmas_f32 v16, v16, v33, v25
	v_div_fixup_f32 v16, v16, v51, v60
	v_or_b32_e32 v51, 2, v50
	v_fma_f32 v1, -v9, v10, 1.0
	v_fmac_f32_e32 v10, v1, v10
	v_div_scale_f32 v1, vcc, v61, v8, v61
	v_mul_f32_e32 v2, v1, v10
	v_fma_f32 v3, -v9, v2, v1
	v_fmac_f32_e32 v2, v3, v10
	v_fma_f32 v1, -v9, v2, v1
	v_div_fmas_f32 v1, v1, v10, v2
	v_mul_f32_e32 v2, 0xbfb8aa3b, v62
	v_mfma_f32_16x16x32_f16 v[52:55], v[100:103], v[128:131], v[52:55]
	v_exp_f32_e32 v2, v2
	v_or_b32_e32 v0, 1, v50
	v_div_fixup_f32 v1, v1, v8, v61
	v_mfma_f32_16x16x32_f16 v[4:7], v[40:43], v[76:79], v[4:7]
	v_mfma_f32_16x16x32_f16 v[56:59], v[100:103], v[108:111], v[56:59]
	s_nop 2
	v_mul_f32_e32 v16, v52, v16
	v_mul_f32_e32 v1, v53, v1
	v_mad_i64_i32 v[52:53], s[8:9], v0, s64, v[48:49]
	v_add_f32_e32 v0, 1.0, v2
	v_med3_f32 v1, v1, s57, v194
	v_div_scale_f32 v2, s[8:9], v0, v0, v62
	v_cvt_f16_f32_e32 v1, v1
	v_rcp_f32_e32 v3, v2
	v_mfma_f32_16x16x32_f16 v[64:67], v[100:103], v[124:127], v[64:67]
	v_med3_f32 v16, v16, s57, v194
	global_store_short v[52:53], v1, off
	v_fma_f32 v1, -v2, v3, 1.0
	v_fmac_f32_e32 v3, v1, v3
	v_div_scale_f32 v1, vcc, v62, v0, v62
	v_mul_f32_e32 v60, v1, v3
	v_fma_f32 v8, -v2, v60, v1
	v_fmac_f32_e32 v60, v8, v3
	v_fma_f32 v1, -v2, v60, v1
	v_div_fmas_f32 v1, v1, v3, v60
	v_mfma_f32_16x16x32_f16 v[8:11], v[132:135], v[116:119], v[12:15]
	v_cvt_f16_f32_e32 v16, v16
	global_store_short v[148:149], v16, off
	s_nop 0
	v_div_fixup_f32 v12, v1, v0, v62
	v_mul_f32_e32 v54, v54, v12
	v_mul_f32_e32 v12, 0xbfb8aa3b, v63
	v_exp_f32_e32 v60, v12
	v_mfma_f32_16x16x32_f16 v[0:3], v[132:135], v[108:111], v[68:71]
	v_add_f32_e32 v62, 1.0, v60
	v_mfma_f32_16x16x32_f16 v[12:15], v[132:135], v[128:131], v[4:7]
	s_nop 0
	v_div_scale_f32 v68, s[8:9], v62, v62, v63
	v_rcp_f32_e32 v69, v68
	v_med3_f32 v4, v54, s57, v194
	v_cvt_f16_f32_e32 v54, v4
	v_mad_i64_i32 v[60:61], s[8:9], v51, s64, v[48:49]
	v_or_b32_e32 v51, 3, v50
	global_store_short v[60:61], v54, off
	v_fma_f32 v54, -v68, v69, 1.0
	v_fmac_f32_e32 v69, v54, v69
	v_div_scale_f32 v54, vcc, v63, v62, v63
	v_mul_f32_e32 v70, v54, v69
	v_fma_f32 v71, -v68, v70, v54
	v_fmac_f32_e32 v70, v71, v69
	v_fma_f32 v54, -v68, v70, v54
	v_mul_f32_e32 v68, 0xbfb8aa3b, v56
	v_exp_f32_e32 v68, v68
	v_div_fmas_f32 v54, v54, v69, v70
	v_div_fixup_f32 v54, v54, v62, v63
	v_mul_f32_e32 v54, v55, v54
	v_add_f32_e32 v62, 1.0, v68
	v_div_scale_f32 v63, s[8:9], v62, v62, v56
	v_rcp_f32_e32 v68, v63
	v_med3_f32 v54, v54, s57, v194
	v_cvt_f16_f32_e32 v69, v54
	v_mad_i64_i32 v[54:55], s[8:9], v51, s64, v[48:49]
	v_fma_f32 v51, -v63, v68, 1.0
	v_fmac_f32_e32 v68, v51, v68
	v_div_scale_f32 v51, vcc, v56, v62, v56
	v_mul_f32_e32 v70, v51, v68
	v_fma_f32 v71, -v63, v70, v51
	v_fmac_f32_e32 v70, v71, v68
	v_fma_f32 v51, -v63, v70, v51
	v_mul_f32_e32 v63, 0xbfb8aa3b, v57
	v_exp_f32_e32 v63, v63
	v_div_fmas_f32 v51, v51, v68, v70
	v_div_fixup_f32 v51, v51, v62, v56
	v_mul_f32_e32 v51, v64, v51
	v_add_f32_e32 v56, 1.0, v63
	v_div_scale_f32 v62, s[8:9], v56, v56, v57
	v_rcp_f32_e32 v63, v62
	v_med3_f32 v51, v51, s57, v194
	v_cvt_f16_f32_e32 v51, v51
	v_mfma_f32_16x16x32_f16 v[40:43], v[104:107], v[116:119], v[44:47]
	v_fma_f32 v64, -v62, v63, 1.0
	v_fmac_f32_e32 v63, v64, v63
	v_div_scale_f32 v64, vcc, v57, v56, v57
	v_mul_f32_e32 v68, v64, v63
	v_fma_f32 v70, -v62, v68, v64
	v_fmac_f32_e32 v68, v70, v63
	v_fma_f32 v62, -v62, v68, v64
	v_div_fmas_f32 v62, v62, v63, v68
	v_div_fixup_f32 v56, v62, v56, v57
	v_mul_f32_e32 v57, 0xbfb8aa3b, v58
	v_exp_f32_e32 v57, v57
	v_mul_f32_e32 v56, v65, v56
	v_med3_f32 v56, v56, s57, v194
	v_cvt_f16_f32_e32 v56, v56
	v_add_f32_e32 v57, 1.0, v57
	v_div_scale_f32 v62, s[8:9], v57, v57, v58
	v_rcp_f32_e32 v63, v62
	global_store_short v[54:55], v69, off
	global_store_short v[148:149], v51, off offset:32
	global_store_short v[52:53], v56, off offset:32
	v_mfma_f32_16x16x32_f16 v[44:47], v[104:107], v[128:131], v[36:39]
	v_fma_f32 v51, -v62, v63, 1.0
	v_fmac_f32_e32 v63, v51, v63
	v_div_scale_f32 v51, vcc, v58, v57, v58
	v_mul_f32_e32 v52, v51, v63
	v_fma_f32 v53, -v62, v52, v51
	v_fmac_f32_e32 v52, v53, v63
	v_mul_f32_e32 v53, 0xbfb8aa3b, v59
	v_exp_f32_e32 v53, v53
	v_fma_f32 v51, -v62, v52, v51
	v_div_fmas_f32 v51, v51, v63, v52
	v_div_fixup_f32 v51, v51, v57, v58
	v_add_f32_e32 v52, 1.0, v53
	v_div_scale_f32 v53, s[8:9], v52, v52, v59
	v_rcp_f32_e32 v56, v53
	v_mul_f32_e32 v51, v66, v51
	v_med3_f32 v51, v51, s57, v194
	v_cvt_f16_f32_e32 v51, v51
	v_fma_f32 v57, -v53, v56, 1.0
	v_fmac_f32_e32 v56, v57, v56
	v_div_scale_f32 v57, vcc, v59, v52, v59
	v_mul_f32_e32 v58, v57, v56
	v_fma_f32 v62, -v53, v58, v57
	v_fmac_f32_e32 v58, v62, v56
	v_fma_f32 v53, -v53, v58, v57
	v_div_fmas_f32 v53, v53, v56, v58
	v_div_fixup_f32 v52, v53, v52, v59
	v_mul_f32_e32 v53, 0xbfb8aa3b, v40
	v_exp_f32_e32 v53, v53
	v_mul_f32_e32 v52, v67, v52
	v_med3_f32 v52, v52, s57, v194
	v_cvt_f16_f32_e32 v52, v52
	v_add_f32_e32 v53, 1.0, v53
	v_div_scale_f32 v56, s[8:9], v53, v53, v40
	v_rcp_f32_e32 v57, v56
	global_store_short v[60:61], v51, off offset:32
	global_store_short v[54:55], v52, off offset:32
	v_or_b32_e32 v51, 16, v50
	v_mfma_f32_16x16x32_f16 v[32:35], v[104:107], v[108:111], v[120:123]
	v_fma_f32 v52, -v56, v57, 1.0
	v_fmac_f32_e32 v57, v52, v57
	v_div_scale_f32 v52, vcc, v40, v53, v40
	v_mul_f32_e32 v54, v52, v57
	v_fma_f32 v55, -v56, v54, v52
	v_fmac_f32_e32 v54, v55, v57
	v_fma_f32 v52, -v56, v54, v52
	v_div_fmas_f32 v52, v52, v57, v54
	v_div_fixup_f32 v40, v52, v53, v40
	v_mul_f32_e32 v52, 0xbfb8aa3b, v41
	v_exp_f32_e32 v52, v52
	v_mul_f32_e32 v40, v44, v40
	v_mfma_f32_16x16x32_f16 v[36:39], v[104:107], v[124:127], v[96:99]
	v_med3_f32 v40, v40, s57, v194
	v_add_f32_e32 v44, 1.0, v52
	v_div_scale_f32 v54, s[8:9], v44, v44, v41
	v_rcp_f32_e32 v55, v54
	v_mad_i64_i32 v[52:53], s[8:9], v51, s64, v[48:49]
	v_cvt_f16_f32_e32 v40, v40
	v_fma_f32 v51, -v54, v55, 1.0
	v_fmac_f32_e32 v55, v51, v55
	v_div_scale_f32 v51, vcc, v41, v44, v41
	v_mul_f32_e32 v56, v51, v55
	v_fma_f32 v57, -v54, v56, v51
	v_fmac_f32_e32 v56, v57, v55
	v_fma_f32 v51, -v54, v56, v51
	v_div_fmas_f32 v51, v51, v55, v56
	v_div_fixup_f32 v41, v51, v44, v41
	v_mul_f32_e32 v44, 0xbfb8aa3b, v42
	v_exp_f32_e32 v44, v44
	v_mul_f32_e32 v41, v45, v41
	v_med3_f32 v41, v41, s57, v194
	v_cvt_f16_f32_e32 v45, v41
	v_add_f32_e32 v44, 1.0, v44
	v_div_scale_f32 v51, s[8:9], v44, v44, v42
	v_rcp_f32_e32 v54, v51
	global_store_short v[52:53], v40, off
	v_or_b32_e32 v40, 17, v50
	v_mad_i64_i32 v[40:41], s[8:9], v40, s64, v[48:49]
	v_fma_f32 v55, -v51, v54, 1.0
	v_fmac_f32_e32 v54, v55, v54
	v_div_scale_f32 v55, vcc, v42, v44, v42
	v_mul_f32_e32 v56, v55, v54
	v_fma_f32 v57, -v51, v56, v55
	v_fmac_f32_e32 v56, v57, v54
	v_fma_f32 v51, -v51, v56, v55
	v_div_fmas_f32 v51, v51, v54, v56
	v_div_fixup_f32 v42, v51, v44, v42
	v_mul_f32_e32 v44, 0xbfb8aa3b, v43
	v_exp_f32_e32 v44, v44
	v_mul_f32_e32 v42, v46, v42
	v_med3_f32 v42, v42, s57, v194
	v_cvt_f16_f32_e32 v42, v42
	v_add_f32_e32 v46, 1.0, v44
	v_div_scale_f32 v51, s[8:9], v46, v46, v43
	v_rcp_f32_e32 v54, v51
	global_store_short v[40:41], v45, off
	v_or_b32_e32 v45, 18, v50
	v_mad_i64_i32 v[44:45], s[8:9], v45, s64, v[48:49]
	v_fma_f32 v55, -v51, v54, 1.0
	v_fmac_f32_e32 v54, v55, v54
	v_div_scale_f32 v55, vcc, v43, v46, v43
	v_mul_f32_e32 v56, v55, v54
	v_fma_f32 v57, -v51, v56, v55
	v_fmac_f32_e32 v56, v57, v54
	v_fma_f32 v51, -v51, v56, v55
	v_div_fmas_f32 v51, v51, v54, v56
	v_mul_f32_e32 v54, 0xbfb8aa3b, v32
	v_exp_f32_e32 v54, v54
	v_div_fixup_f32 v43, v51, v46, v43
	v_mul_f32_e32 v43, v47, v43
	v_med3_f32 v43, v43, s57, v194
	v_add_f32_e32 v46, 1.0, v54
	v_div_scale_f32 v47, s[8:9], v46, v46, v32
	v_rcp_f32_e32 v51, v47
	v_cvt_f16_f32_e32 v54, v43
	global_store_short v[44:45], v42, off
	v_or_b32_e32 v42, 19, v50
	v_fma_f32 v55, -v47, v51, 1.0
	v_fmac_f32_e32 v51, v55, v51
	v_div_scale_f32 v55, vcc, v32, v46, v32
	v_mul_f32_e32 v56, v55, v51
	v_fma_f32 v57, -v47, v56, v55
	v_fmac_f32_e32 v56, v57, v51
	v_fma_f32 v47, -v47, v56, v55
	v_mul_f32_e32 v55, 0xbfb8aa3b, v33
	v_exp_f32_e32 v55, v55
	v_div_fmas_f32 v47, v47, v51, v56
	v_div_fixup_f32 v32, v47, v46, v32
	v_mul_f32_e32 v32, v36, v32
	v_add_f32_e32 v46, 1.0, v55
	v_div_scale_f32 v47, s[8:9], v46, v46, v33
	v_rcp_f32_e32 v51, v47
	v_med3_f32 v32, v32, s57, v194
	v_cvt_f16_f32_e32 v32, v32
	v_mad_i64_i32 v[42:43], s[8:9], v42, s64, v[48:49]
	v_fma_f32 v36, -v47, v51, 1.0
	v_fmac_f32_e32 v51, v36, v51
	v_div_scale_f32 v36, vcc, v33, v46, v33
	v_mul_f32_e32 v55, v36, v51
	v_fma_f32 v56, -v47, v55, v36
	v_fmac_f32_e32 v55, v56, v51
	v_fma_f32 v36, -v47, v55, v36
	v_div_fmas_f32 v36, v36, v51, v55
	v_div_fixup_f32 v33, v36, v46, v33
	v_mul_f32_e32 v36, 0xbfb8aa3b, v34
	v_exp_f32_e32 v36, v36
	v_mul_f32_e32 v33, v37, v33
	v_med3_f32 v33, v33, s57, v194
	v_cvt_f16_f32_e32 v33, v33
	v_add_f32_e32 v36, 1.0, v36
	v_div_scale_f32 v37, s[8:9], v36, v36, v34
	v_rcp_f32_e32 v46, v37
	global_store_short v[42:43], v54, off
	global_store_short v[52:53], v32, off offset:32
	global_store_short v[40:41], v33, off offset:32
	v_mfma_f32_16x16x32_f16 v[24:27], v[136:139], v[116:119], v[28:31]
	v_fma_f32 v32, -v37, v46, 1.0
	v_fmac_f32_e32 v46, v32, v46
	v_div_scale_f32 v32, vcc, v34, v36, v34
	v_mul_f32_e32 v33, v32, v46
	v_fma_f32 v40, -v37, v33, v32
	v_fmac_f32_e32 v33, v40, v46
	v_fma_f32 v32, -v37, v33, v32
	v_mul_f32_e32 v37, 0xbfb8aa3b, v35
	v_exp_f32_e32 v37, v37
	v_div_fmas_f32 v32, v32, v46, v33
	v_div_fixup_f32 v32, v32, v36, v34
	v_mul_f32_e32 v32, v38, v32
	v_add_f32_e32 v33, 1.0, v37
	v_div_scale_f32 v34, s[8:9], v33, v33, v35
	v_rcp_f32_e32 v36, v34
	v_med3_f32 v32, v32, s57, v194
	v_cvt_f16_f32_e32 v32, v32
	v_mfma_f32_16x16x32_f16 v[28:31], v[136:139], v[128:131], v[20:23]
	v_fma_f32 v37, -v34, v36, 1.0
	v_fmac_f32_e32 v36, v37, v36
	v_div_scale_f32 v37, vcc, v35, v33, v35
	v_mul_f32_e32 v38, v37, v36
	v_fma_f32 v40, -v34, v38, v37
	v_fmac_f32_e32 v38, v40, v36
	v_fma_f32 v34, -v34, v38, v37
	v_div_fmas_f32 v34, v34, v36, v38
	v_div_fixup_f32 v33, v34, v33, v35
	v_mul_f32_e32 v34, 0xbfb8aa3b, v24
	v_exp_f32_e32 v34, v34
	v_mul_f32_e32 v33, v39, v33
	v_med3_f32 v33, v33, s57, v194
	v_cvt_f16_f32_e32 v33, v33
	v_add_f32_e32 v34, 1.0, v34
	v_div_scale_f32 v35, s[8:9], v34, v34, v24
	v_rcp_f32_e32 v36, v35
	global_store_short v[44:45], v32, off offset:32
	global_store_short v[42:43], v33, off offset:32
	v_mfma_f32_16x16x32_f16 v[16:19], v[136:139], v[108:111], v[144:147]
	v_or_b32_e32 v32, 32, v50
	v_fma_f32 v33, -v35, v36, 1.0
	v_fmac_f32_e32 v36, v33, v36
	v_div_scale_f32 v33, vcc, v24, v34, v24
	v_mul_f32_e32 v37, v33, v36
	v_fma_f32 v38, -v35, v37, v33
	v_fmac_f32_e32 v37, v38, v36
	v_fma_f32 v33, -v35, v37, v33
	v_div_fmas_f32 v33, v33, v36, v37
	v_div_fixup_f32 v24, v33, v34, v24
	v_mul_f32_e32 v33, 0xbfb8aa3b, v25
	v_exp_f32_e32 v33, v33
	v_mul_f32_e32 v24, v28, v24
	v_mfma_f32_16x16x32_f16 v[20:23], v[136:139], v[124:127], v[140:143]
	v_med3_f32 v24, v24, s57, v194
	v_add_f32_e32 v28, 1.0, v33
	v_div_scale_f32 v34, s[8:9], v28, v28, v25
	v_rcp_f32_e32 v35, v34
	v_cvt_f16_f32_e32 v24, v24
	v_mad_i64_i32 v[32:33], s[8:9], v32, s64, v[48:49]
	v_fma_f32 v36, -v34, v35, 1.0
	v_fmac_f32_e32 v35, v36, v35
	v_div_scale_f32 v36, vcc, v25, v28, v25
	v_mul_f32_e32 v37, v36, v35
	v_fma_f32 v38, -v34, v37, v36
	v_fmac_f32_e32 v37, v38, v35
	v_fma_f32 v34, -v34, v37, v36
	v_div_fmas_f32 v34, v34, v35, v37
	v_div_fixup_f32 v25, v34, v28, v25
	v_mul_f32_e32 v28, 0xbfb8aa3b, v26
	v_exp_f32_e32 v28, v28
	v_mul_f32_e32 v25, v29, v25
	v_med3_f32 v25, v25, s57, v194
	v_cvt_f16_f32_e32 v29, v25
	v_add_f32_e32 v28, 1.0, v28
	v_div_scale_f32 v34, s[8:9], v28, v28, v26
	v_rcp_f32_e32 v35, v34
	global_store_short v[32:33], v24, off
	v_or_b32_e32 v24, 33, v50
	v_mad_i64_i32 v[24:25], s[8:9], v24, s64, v[48:49]
	v_fma_f32 v36, -v34, v35, 1.0
	v_fmac_f32_e32 v35, v36, v35
	v_div_scale_f32 v36, vcc, v26, v28, v26
	v_mul_f32_e32 v37, v36, v35
	v_fma_f32 v38, -v34, v37, v36
	v_fmac_f32_e32 v37, v38, v35
	v_fma_f32 v34, -v34, v37, v36
	v_div_fmas_f32 v34, v34, v35, v37
	v_div_fixup_f32 v26, v34, v28, v26
	v_mul_f32_e32 v28, 0xbfb8aa3b, v27
	v_exp_f32_e32 v28, v28
	v_mul_f32_e32 v26, v30, v26
	v_med3_f32 v26, v26, s57, v194
	v_cvt_f16_f32_e32 v26, v26
	v_add_f32_e32 v30, 1.0, v28
	v_div_scale_f32 v34, s[8:9], v30, v30, v27
	v_rcp_f32_e32 v35, v34
	global_store_short v[24:25], v29, off
	v_or_b32_e32 v29, 34, v50
	v_mad_i64_i32 v[28:29], s[8:9], v29, s64, v[48:49]
	v_fma_f32 v36, -v34, v35, 1.0
	v_fmac_f32_e32 v35, v36, v35
	v_div_scale_f32 v36, vcc, v27, v30, v27
	v_mul_f32_e32 v37, v36, v35
	v_fma_f32 v38, -v34, v37, v36
	v_fmac_f32_e32 v37, v38, v35
	v_fma_f32 v34, -v34, v37, v36
	v_div_fmas_f32 v34, v34, v35, v37
	v_mul_f32_e32 v35, 0xbfb8aa3b, v16
	v_exp_f32_e32 v35, v35
	v_div_fixup_f32 v27, v34, v30, v27
	v_mul_f32_e32 v27, v31, v27
	v_med3_f32 v27, v27, s57, v194
	v_add_f32_e32 v30, 1.0, v35
	v_div_scale_f32 v31, s[8:9], v30, v30, v16
	v_rcp_f32_e32 v34, v31
	v_cvt_f16_f32_e32 v35, v27
	global_store_short v[28:29], v26, off
	v_or_b32_e32 v26, 35, v50
	v_fma_f32 v36, -v31, v34, 1.0
	v_fmac_f32_e32 v34, v36, v34
	v_div_scale_f32 v36, vcc, v16, v30, v16
	v_mul_f32_e32 v37, v36, v34
	v_fma_f32 v38, -v31, v37, v36
	v_fmac_f32_e32 v37, v38, v34
	v_fma_f32 v31, -v31, v37, v36
	v_mul_f32_e32 v36, 0xbfb8aa3b, v17
	v_exp_f32_e32 v36, v36
	v_div_fmas_f32 v31, v31, v34, v37
	v_div_fixup_f32 v16, v31, v30, v16
	v_mul_f32_e32 v16, v20, v16
	v_add_f32_e32 v30, 1.0, v36
	v_div_scale_f32 v31, s[8:9], v30, v30, v17
	v_rcp_f32_e32 v34, v31
	v_med3_f32 v16, v16, s57, v194
	v_cvt_f16_f32_e32 v16, v16
	v_mad_i64_i32 v[26:27], s[8:9], v26, s64, v[48:49]
	v_fma_f32 v20, -v31, v34, 1.0
	v_fmac_f32_e32 v34, v20, v34
	v_div_scale_f32 v20, vcc, v17, v30, v17
	v_mul_f32_e32 v36, v20, v34
	v_fma_f32 v37, -v31, v36, v20
	v_fmac_f32_e32 v36, v37, v34
	v_fma_f32 v20, -v31, v36, v20
	v_div_fmas_f32 v20, v20, v34, v36
	v_div_fixup_f32 v17, v20, v30, v17
	v_mul_f32_e32 v20, 0xbfb8aa3b, v18
	v_exp_f32_e32 v20, v20
	v_mul_f32_e32 v17, v21, v17
	v_med3_f32 v17, v17, s57, v194
	v_cvt_f16_f32_e32 v17, v17
	v_add_f32_e32 v20, 1.0, v20
	v_div_scale_f32 v21, s[8:9], v20, v20, v18
	v_rcp_f32_e32 v30, v21
	global_store_short v[26:27], v35, off
	global_store_short v[32:33], v16, off offset:32
	global_store_short v[24:25], v17, off offset:32
	v_mfma_f32_16x16x32_f16 v[4:7], v[132:135], v[124:127], v[72:75]
	v_fma_f32 v16, -v21, v30, 1.0
	v_fmac_f32_e32 v30, v16, v30
	v_div_scale_f32 v16, vcc, v18, v20, v18
	v_mul_f32_e32 v17, v16, v30
	v_fma_f32 v24, -v21, v17, v16
	v_fmac_f32_e32 v17, v24, v30
	v_fma_f32 v16, -v21, v17, v16
	v_mul_f32_e32 v21, 0xbfb8aa3b, v19
	v_exp_f32_e32 v21, v21
	v_div_fmas_f32 v16, v16, v30, v17
	v_div_fixup_f32 v16, v16, v20, v18
	v_mul_f32_e32 v16, v22, v16
	v_add_f32_e32 v17, 1.0, v21
	v_div_scale_f32 v18, s[8:9], v17, v17, v19
	v_rcp_f32_e32 v20, v18
	v_med3_f32 v16, v16, s57, v194
	v_cvt_f16_f32_e32 v16, v16
	v_fma_f32 v21, -v18, v20, 1.0
	v_fmac_f32_e32 v20, v21, v20
	v_div_scale_f32 v21, vcc, v19, v17, v19
	v_mul_f32_e32 v22, v21, v20
	v_fma_f32 v24, -v18, v22, v21
	v_fmac_f32_e32 v22, v24, v20
	v_fma_f32 v18, -v18, v22, v21
	v_div_fmas_f32 v18, v18, v20, v22
	v_div_fixup_f32 v17, v18, v17, v19
	v_mul_f32_e32 v18, 0xbfb8aa3b, v8
	v_exp_f32_e32 v18, v18
	v_mul_f32_e32 v17, v23, v17
	v_med3_f32 v17, v17, s57, v194
	v_cvt_f16_f32_e32 v17, v17
	v_add_f32_e32 v18, 1.0, v18
	v_div_scale_f32 v19, s[8:9], v18, v18, v8
	v_rcp_f32_e32 v20, v19
	global_store_short v[28:29], v16, off offset:32
	global_store_short v[26:27], v17, off offset:32
	v_or_b32_e32 v16, 48, v50
	v_fma_f32 v17, -v19, v20, 1.0
	v_fmac_f32_e32 v20, v17, v20
	v_div_scale_f32 v17, vcc, v8, v18, v8
	v_mul_f32_e32 v21, v17, v20
	v_fma_f32 v22, -v19, v21, v17
	v_fmac_f32_e32 v21, v22, v20
	v_fma_f32 v17, -v19, v21, v17
	v_div_fmas_f32 v17, v17, v20, v21
	v_div_fixup_f32 v8, v17, v18, v8
	v_mul_f32_e32 v17, 0xbfb8aa3b, v9
	v_exp_f32_e32 v17, v17
	v_mul_f32_e32 v8, v12, v8
	v_med3_f32 v8, v8, s57, v194
	v_cvt_f16_f32_e32 v8, v8
	v_add_f32_e32 v12, 1.0, v17
	v_div_scale_f32 v18, s[8:9], v12, v12, v9
	v_rcp_f32_e32 v19, v18
	v_mad_i64_i32 v[16:17], s[8:9], v16, s64, v[48:49]
	global_store_short v[16:17], v8, off
	v_fma_f32 v20, -v18, v19, 1.0
	v_fmac_f32_e32 v19, v20, v19
	v_div_scale_f32 v20, vcc, v9, v12, v9
	v_mul_f32_e32 v21, v20, v19
	v_fma_f32 v22, -v18, v21, v20
	v_fmac_f32_e32 v21, v22, v19
	v_fma_f32 v18, -v18, v21, v20
	v_div_fmas_f32 v18, v18, v19, v21
	v_div_fixup_f32 v9, v18, v12, v9
	v_mul_f32_e32 v12, 0xbfb8aa3b, v10
	v_exp_f32_e32 v12, v12
	v_mul_f32_e32 v9, v13, v9
	v_med3_f32 v9, v9, s57, v194
	v_cvt_f16_f32_e32 v13, v9
	v_add_f32_e32 v12, 1.0, v12
	v_div_scale_f32 v18, s[8:9], v12, v12, v10
	v_rcp_f32_e32 v19, v18
	v_or_b32_e32 v8, 49, v50
	v_mad_i64_i32 v[8:9], s[8:9], v8, s64, v[48:49]
	v_fma_f32 v20, -v18, v19, 1.0
	v_fmac_f32_e32 v19, v20, v19
	v_div_scale_f32 v20, vcc, v10, v12, v10
	v_mul_f32_e32 v21, v20, v19
	v_fma_f32 v22, -v18, v21, v20
	v_fmac_f32_e32 v21, v22, v19
	v_fma_f32 v18, -v18, v21, v20
	v_div_fmas_f32 v18, v18, v19, v21
	v_div_fixup_f32 v10, v18, v12, v10
	v_mul_f32_e32 v12, 0xbfb8aa3b, v11
	v_exp_f32_e32 v12, v12
	v_mul_f32_e32 v10, v14, v10
	v_med3_f32 v10, v10, s57, v194
	v_cvt_f16_f32_e32 v10, v10
	v_add_f32_e32 v14, 1.0, v12
	v_div_scale_f32 v18, s[8:9], v14, v14, v11
	v_rcp_f32_e32 v19, v18
	global_store_short v[8:9], v13, off
	v_or_b32_e32 v13, 50, v50
	v_mad_i64_i32 v[12:13], s[8:9], v13, s64, v[48:49]
	v_fma_f32 v20, -v18, v19, 1.0
	v_fmac_f32_e32 v19, v20, v19
	v_div_scale_f32 v20, vcc, v11, v14, v11
	v_mul_f32_e32 v21, v20, v19
	v_fma_f32 v22, -v18, v21, v20
	v_fmac_f32_e32 v21, v22, v19
	v_fma_f32 v18, -v18, v21, v20
	v_div_fmas_f32 v18, v18, v19, v21
	v_mul_f32_e32 v19, 0xbfb8aa3b, v0
	v_exp_f32_e32 v19, v19
	v_div_fixup_f32 v11, v18, v14, v11
	v_mul_f32_e32 v11, v15, v11
	v_med3_f32 v11, v11, s57, v194
	v_add_f32_e32 v14, 1.0, v19
	v_div_scale_f32 v15, s[8:9], v14, v14, v0
	v_rcp_f32_e32 v18, v15
	v_cvt_f16_f32_e32 v19, v11
	global_store_short v[12:13], v10, off
	v_or_b32_e32 v10, 51, v50
	v_fma_f32 v20, -v15, v18, 1.0
	v_fmac_f32_e32 v18, v20, v18
	v_div_scale_f32 v20, vcc, v0, v14, v0
	v_mul_f32_e32 v21, v20, v18
	v_fma_f32 v22, -v15, v21, v20
	v_fmac_f32_e32 v21, v22, v18
	v_fma_f32 v15, -v15, v21, v20
	v_mul_f32_e32 v20, 0xbfb8aa3b, v1
	v_exp_f32_e32 v20, v20
	v_div_fmas_f32 v15, v15, v18, v21
	v_div_fixup_f32 v0, v15, v14, v0
	v_mul_f32_e32 v0, v4, v0
	v_add_f32_e32 v14, 1.0, v20
	v_div_scale_f32 v15, s[8:9], v14, v14, v1
	v_rcp_f32_e32 v18, v15
	v_med3_f32 v0, v0, s57, v194
	v_cvt_f16_f32_e32 v0, v0
	v_mad_i64_i32 v[10:11], s[8:9], v10, s64, v[48:49]
	v_fma_f32 v4, -v15, v18, 1.0
	v_fmac_f32_e32 v18, v4, v18
	v_div_scale_f32 v4, vcc, v1, v14, v1
	v_mul_f32_e32 v20, v4, v18
	v_fma_f32 v21, -v15, v20, v4
	v_fmac_f32_e32 v20, v21, v18
	v_fma_f32 v4, -v15, v20, v4
	v_div_fmas_f32 v4, v4, v18, v20
	v_div_fixup_f32 v1, v4, v14, v1
	v_mul_f32_e32 v4, 0xbfb8aa3b, v2
	v_exp_f32_e32 v4, v4
	v_mul_f32_e32 v1, v5, v1
	v_med3_f32 v1, v1, s57, v194
	v_cvt_f16_f32_e32 v1, v1
	v_add_f32_e32 v4, 1.0, v4
	v_div_scale_f32 v5, s[8:9], v4, v4, v2
	v_rcp_f32_e32 v14, v5
	global_store_short v[10:11], v19, off
	global_store_short v[16:17], v0, off offset:32
	global_store_short v[8:9], v1, off offset:32
	v_fma_f32 v0, -v5, v14, 1.0
	v_fmac_f32_e32 v14, v0, v14
	v_div_scale_f32 v0, vcc, v2, v4, v2
	v_mul_f32_e32 v1, v0, v14
	v_fma_f32 v8, -v5, v1, v0
	v_fmac_f32_e32 v1, v8, v14
	v_fma_f32 v0, -v5, v1, v0
	v_mul_f32_e32 v5, 0xbfb8aa3b, v3
	v_exp_f32_e32 v5, v5
	v_div_fmas_f32 v0, v0, v14, v1
	v_div_fixup_f32 v0, v0, v4, v2
	v_mul_f32_e32 v0, v6, v0
	v_add_f32_e32 v1, 1.0, v5
	v_div_scale_f32 v2, s[8:9], v1, v1, v3
	v_rcp_f32_e32 v4, v2
	v_med3_f32 v0, v0, s57, v194
	v_cvt_f16_f32_e32 v0, v0
	v_fma_f32 v5, -v2, v4, 1.0
	v_fmac_f32_e32 v4, v5, v4
	v_div_scale_f32 v5, vcc, v3, v1, v3
	v_mul_f32_e32 v6, v5, v4
	v_fma_f32 v8, -v2, v6, v5
	v_fmac_f32_e32 v6, v8, v4
	v_fma_f32 v2, -v2, v6, v5
	v_div_fmas_f32 v2, v2, v4, v6
	v_div_fixup_f32 v1, v2, v1, v3
	v_mul_f32_e32 v1, v7, v1
	v_med3_f32 v1, v1, s57, v194
	v_cvt_f16_f32_e32 v1, v1
	global_store_short v[12:13], v0, off offset:32
	global_store_short v[10:11], v1, off offset:32
	s_cbranch_scc0 .LBB0_136

.LBB0_154:
	s_add_i32 s4, s15, 0xffff8000
	v_mov_b32_e32 v64, v182
	s_waitcnt vmcnt(0)
	s_waitcnt vmcnt(0) lgkmcnt(0)
	s_barrier
	s_and_b32 s16, s15, 0x8000
	s_and_b32 s17, s4, 0x8000
	v_or_b32_e32 v71, s17, v121
	v_lshrrev_b32_e32 v65, 4, v64
	v_ashrrev_i32_e32 v66, 3, v64
	v_add_u32_e32 v68, 0x100, v64
	v_lshl_add_u32 v67, v64, 4, s16
	v_add_u32_e32 v69, 0x200, v64
	v_add_u32_e32 v72, s0, v66
	v_bitop3_b32 v73, v65, 7, v64 bitop3:0x48
	v_ashrrev_i32_e32 v74, 3, v68
	s_add_u32 s10, s30, s8
	v_add_u32_e32 v70, 0x300, v64
	v_lshl_add_u32 v68, v68, 4, s16
	v_ashrrev_i32_e32 v75, 3, v69
	v_lshl_add_u32 v69, v69, 4, s16
	v_add_u32_e32 v77, 0x4000, v67
	v_add3_u32 v84, v71, v122, v123
	v_add3_u32 v80, v71, v124, v123
	v_mad_i64_i32 v[64:65], s[18:19], v72, s64, 0
	v_lshlrev_b32_e32 v81, 4, v73
	v_add_u32_e32 v71, s0, v74
	s_addc_u32 s11, s31, s9
	v_ashrrev_i32_e32 v76, 3, v70
	v_lshl_add_u32 v70, v70, 4, s16
	v_readfirstlane_b32 s5, v68
	v_add_u32_e32 v72, s0, v75
	v_readfirstlane_b32 s20, v69
	v_readfirstlane_b32 s22, v77
	v_add_u32_e32 v77, 0x4000, v68
	v_add_u32_e32 v79, 0x4000, v69
	v_or_b32_e32 v64, v64, v81
	v_mad_i64_i32 v[68:69], s[18:19], v71, s64, 0
	v_readfirstlane_b32 s4, v67
	v_add_u32_e32 v73, s0, v76
	v_readfirstlane_b32 s21, v70
	v_add_u32_e32 v83, 0x4000, v70
	v_mad_i64_i32 v[70:71], s[18:19], v72, s64, 0
	v_lshl_add_u64 v[64:65], s[10:11], 0, v[64:65]
	v_or_b32_e32 v68, v68, v81
	v_add_u32_e32 v66, s14, v66
	v_mad_i64_i32 v[72:73], s[18:19], v73, s64, 0
	v_or_b32_e32 v70, v70, v81
	v_lshl_add_u64 v[64:65], v[64:65], 0, s[88:89]
	v_lshl_add_u64 v[68:69], s[10:11], 0, v[68:69]
	s_mov_b32 m0, s4
	v_mad_i64_i32 v[66:67], s[18:19], v66, s64, 0
	v_add_u32_e32 v74, s14, v74
	v_or_b32_e32 v72, v72, v81
	v_lshl_add_u64 v[70:71], s[10:11], 0, v[70:71]
	global_load_lds_dwordx4 v[64:65], off
	v_lshl_add_u64 v[64:65], v[68:69], 0, s[88:89]
	s_mov_b32 m0, s5
	v_add_u32_e32 v78, s14, v75
	v_or_b32_e32 v66, v66, v81
	v_mad_i64_i32 v[74:75], s[18:19], v74, s64, 0
	v_lshl_add_u64 v[72:73], s[10:11], 0, v[72:73]
	v_lshl_add_u64 v[68:69], v[70:71], 0, s[88:89]
	global_load_lds_dwordx4 v[64:65], off
	s_mov_b32 m0, s20
	v_add_u32_e32 v82, s14, v76
	v_readfirstlane_b32 s23, v77
	v_mad_i64_i32 v[76:77], s[18:19], v78, s64, 0
	v_lshl_add_u64 v[66:67], s[10:11], 0, v[66:67]
	v_or_b32_e32 v74, v74, v81
	v_lshl_add_u64 v[70:71], v[72:73], 0, s[88:89]
	global_load_lds_dwordx4 v[68:69], off
	s_mov_b32 m0, s21
	v_readfirstlane_b32 s36, v79
	v_mad_i64_i32 v[78:79], s[18:19], v82, s64, 0
	v_or_b32_e32 v76, v76, v81
	v_lshl_add_u64 v[66:67], v[66:67], 0, s[78:79]
	v_lshl_add_u64 v[74:75], s[10:11], 0, v[74:75]
	global_load_lds_dwordx4 v[70:71], off
	s_mov_b32 m0, s22
	v_or_b32_e32 v78, v78, v81
	v_lshl_add_u64 v[76:77], s[10:11], 0, v[76:77]
	v_lshl_add_u64 v[72:73], v[74:75], 0, s[78:79]
	global_load_lds_dwordx4 v[66:67], off
	s_mov_b32 m0, s23
	v_readfirstlane_b32 s18, v83
	v_lshl_add_u64 v[78:79], s[10:11], 0, v[78:79]
	v_lshl_add_u64 v[74:75], v[76:77], 0, s[78:79]
	global_load_lds_dwordx4 v[72:73], off
	s_mov_b32 m0, s36
	v_lshl_add_u64 v[76:77], v[78:79], 0, s[78:79]
	global_load_lds_dwordx4 v[74:75], off
	s_mov_b32 m0, s18
	s_add_u32 s8, s8, 0x80
	global_load_lds_dwordx4 v[76:77], off
	ds_read_b128 v[64:67], v84
	ds_read_b128 v[68:71], v80 offset:16384
	ds_read_b128 v[72:75], v80 offset:18432
	ds_read_b128 v[76:79], v80 offset:20480
	ds_read_b128 v[80:83], v80 offset:22528
	s_waitcnt lgkmcnt(0)
	v_mfma_f32_16x16x32_f16 v[60:63], v[64:67], v[68:71], v[60:63]
	s_addc_u32 s9, s9, 0
	s_add_i32 s15, s15, 0x8000
	s_cmpk_eq_i32 s8, 0x1580
	v_mfma_f32_16x16x32_f16 v[56:59], v[64:67], v[72:75], v[56:59]
	v_mfma_f32_16x16x32_f16 v[52:55], v[64:67], v[76:79], v[52:55]
	v_mfma_f32_16x16x32_f16 v[48:51], v[64:67], v[80:83], v[48:51]
	ds_read_b128 v[64:67], v84 offset:2048
	s_waitcnt lgkmcnt(0)
	v_mfma_f32_16x16x32_f16 v[44:47], v[64:67], v[68:71], v[44:47]
	v_mfma_f32_16x16x32_f16 v[40:43], v[64:67], v[72:75], v[40:43]
	v_mfma_f32_16x16x32_f16 v[32:35], v[64:67], v[76:79], v[32:35]
	v_mfma_f32_16x16x32_f16 v[28:31], v[64:67], v[80:83], v[28:31]
	ds_read_b128 v[64:67], v84 offset:4096
	s_waitcnt lgkmcnt(0)
	v_mfma_f32_16x16x32_f16 v[24:27], v[64:67], v[68:71], v[24:27]
	v_mfma_f32_16x16x32_f16 v[20:23], v[64:67], v[72:75], v[20:23]
	v_mfma_f32_16x16x32_f16 v[16:19], v[64:67], v[76:79], v[16:19]
	v_mfma_f32_16x16x32_f16 v[12:15], v[64:67], v[80:83], v[12:15]
	ds_read_b128 v[64:67], v84 offset:6144
	s_waitcnt lgkmcnt(0)
	v_mfma_f32_16x16x32_f16 v[8:11], v[64:67], v[68:71], v[8:11]
	v_or_b32_e32 v68, s17, v125
	v_add3_u32 v84, v68, v122, v123
	v_add3_u32 v85, v68, v124, v123
	ds_read_b128 v[68:71], v84
	v_mfma_f32_16x16x32_f16 v[4:7], v[64:67], v[72:75], v[4:7]
	ds_read_b128 v[72:75], v85 offset:18432
	v_mfma_f32_16x16x32_f16 v[0:3], v[64:67], v[76:79], v[0:3]
	ds_read_b128 v[76:79], v85 offset:20480
	v_mfma_f32_16x16x32_f16 v[36:39], v[64:67], v[80:83], v[36:39]
	ds_read_b128 v[64:67], v85 offset:16384
	ds_read_b128 v[80:83], v85 offset:22528
	s_waitcnt lgkmcnt(1)
	v_mfma_f32_16x16x32_f16 v[60:63], v[68:71], v[64:67], v[60:63]
	v_mfma_f32_16x16x32_f16 v[56:59], v[68:71], v[72:75], v[56:59]
	v_mfma_f32_16x16x32_f16 v[52:55], v[68:71], v[76:79], v[52:55]
	s_waitcnt lgkmcnt(0)
	v_mfma_f32_16x16x32_f16 v[48:51], v[68:71], v[80:83], v[48:51]
	ds_read_b128 v[68:71], v84 offset:2048
	s_waitcnt lgkmcnt(0)
	v_mfma_f32_16x16x32_f16 v[44:47], v[68:71], v[64:67], v[44:47]
	v_mfma_f32_16x16x32_f16 v[40:43], v[68:71], v[72:75], v[40:43]
	v_mfma_f32_16x16x32_f16 v[32:35], v[68:71], v[76:79], v[32:35]
	v_mfma_f32_16x16x32_f16 v[28:31], v[68:71], v[80:83], v[28:31]
	ds_read_b128 v[68:71], v84 offset:4096
	s_waitcnt lgkmcnt(0)
	v_mfma_f32_16x16x32_f16 v[24:27], v[68:71], v[64:67], v[24:27]
	v_mfma_f32_16x16x32_f16 v[20:23], v[68:71], v[72:75], v[20:23]
	v_mfma_f32_16x16x32_f16 v[16:19], v[68:71], v[76:79], v[16:19]
	v_mfma_f32_16x16x32_f16 v[12:15], v[68:71], v[80:83], v[12:15]
	ds_read_b128 v[68:71], v84 offset:6144
	s_waitcnt lgkmcnt(0)
	v_mfma_f32_16x16x32_f16 v[8:11], v[68:71], v[64:67], v[8:11]
	v_mfma_f32_16x16x32_f16 v[4:7], v[68:71], v[72:75], v[4:7]
	v_mfma_f32_16x16x32_f16 v[0:3], v[68:71], v[76:79], v[0:3]
	v_mfma_f32_16x16x32_f16 v[36:39], v[68:71], v[80:83], v[36:39]
	s_cbranch_scc0 .LBB0_154
	v_add_u32_e32 v80, s16, v121
	v_add3_u32 v76, v80, v122, v123
	v_add3_u32 v92, v80, v124, v123
	s_waitcnt vmcnt(0)
	s_barrier
	ds_read_b128 v[64:67], v76
	ds_read_b128 v[68:71], v76 offset:2048
	ds_read_b128 v[72:75], v76 offset:4096
	ds_read_b128 v[76:79], v76 offset:6144
	ds_read_b128 v[80:83], v92 offset:16384
	ds_read_b128 v[84:87], v92 offset:18432
	ds_read_b128 v[88:91], v92 offset:20480
	ds_read_b128 v[92:95], v92 offset:22528
	s_waitcnt lgkmcnt(3)
	v_mfma_f32_16x16x32_f16 v[96:99], v[72:75], v[80:83], v[24:27]
	s_ashr_i32 s4, s0, 31
	s_lshr_b32 s4, s4, 19
	s_add_i32 s4, s0, s4
	s_waitcnt lgkmcnt(2)
	v_mfma_f32_16x16x32_f16 v[20:23], v[72:75], v[84:87], v[20:23]
	s_ashr_i32 s8, s4, 13
	s_add_i32 s4, s8, s12
	s_mul_hi_i32 s5, s4, 0x9000
	s_waitcnt lgkmcnt(1)
	v_mfma_f32_16x16x32_f16 v[16:19], v[72:75], v[88:91], v[16:19]
	s_mul_i32 s4, s4, 0x9000
	s_add_u32 s8, s50, s4
	s_addc_u32 s9, s51, s5
	s_waitcnt lgkmcnt(0)
	v_mfma_f32_16x16x32_f16 v[72:75], v[72:75], v[92:95], v[12:15]
	s_add_i32 s13, s13, s59
	s_cmpk_gt_i32 s13, 0x7ff
	s_nop 0
	v_add_u32_e32 v12, s16, v125
	v_add3_u32 v13, v12, v122, v123
	v_add3_u32 v12, v12, v124, v123
	v_mfma_f32_16x16x32_f16 v[60:63], v[64:67], v[80:83], v[60:63]
	v_mfma_f32_16x16x32_f16 v[56:59], v[64:67], v[84:87], v[56:59]
	v_mfma_f32_16x16x32_f16 v[52:55], v[64:67], v[88:91], v[52:55]
	v_mfma_f32_16x16x32_f16 v[48:51], v[64:67], v[92:95], v[48:51]
	v_mfma_f32_16x16x32_f16 v[64:67], v[68:71], v[80:83], v[44:47]
	v_mfma_f32_16x16x32_f16 v[40:43], v[68:71], v[84:87], v[40:43]
	v_mfma_f32_16x16x32_f16 v[32:35], v[68:71], v[88:91], v[32:35]
	v_mfma_f32_16x16x32_f16 v[68:71], v[68:71], v[92:95], v[28:31]
	v_mfma_f32_16x16x32_f16 v[80:83], v[76:79], v[80:83], v[8:11]
	v_mfma_f32_16x16x32_f16 v[84:87], v[76:79], v[84:87], v[4:7]
	v_mfma_f32_16x16x32_f16 v[0:3], v[76:79], v[88:91], v[0:3]
	v_mfma_f32_16x16x32_f16 v[76:79], v[76:79], v[92:95], v[36:39]
	s_nop 0
	ds_read_b128 v[4:7], v13
	ds_read_b128 v[8:11], v13 offset:2048
	ds_read_b128 v[88:91], v13 offset:4096
	ds_read_b128 v[92:95], v13 offset:6144
	ds_read_b128 v[100:103], v12 offset:16384
	ds_read_b128 v[104:107], v12 offset:18432
	ds_read_b128 v[108:111], v12 offset:20480
	ds_read_b128 v[116:119], v12 offset:22528
	s_waitcnt lgkmcnt(3)
	v_mfma_f32_16x16x32_f16 v[60:63], v[4:7], v[100:103], v[60:63]
	s_waitcnt lgkmcnt(2)
	v_mfma_f32_16x16x32_f16 v[44:47], v[4:7], v[104:107], v[56:59]
	s_waitcnt lgkmcnt(1)
	v_mfma_f32_16x16x32_f16 v[28:31], v[4:7], v[108:111], v[52:55]
	s_waitcnt lgkmcnt(0)
	v_mfma_f32_16x16x32_f16 v[12:15], v[4:7], v[116:119], v[48:51]
	v_mfma_f32_16x16x32_f16 v[52:55], v[88:91], v[100:103], v[96:99]
	v_mfma_f32_16x16x32_f16 v[36:39], v[88:91], v[104:107], v[20:23]
	v_mfma_f32_16x16x32_f16 v[20:23], v[88:91], v[108:111], v[16:19]
	v_mfma_f32_16x16x32_f16 v[4:7], v[88:91], v[116:119], v[72:75]
	v_add_u32_e32 v90, s0, v120
	v_or_b32_e32 v88, s14, v115
	v_ashrrev_i32_e32 v89, 31, v88
	v_mfma_f32_16x16x32_f16 v[56:59], v[8:11], v[100:103], v[64:67]
	v_ashrrev_i32_e32 v91, 31, v90
	v_or_b32_e32 v98, 33, v90
	v_ashrrev_i32_e32 v99, 31, v98
	v_or_b32_e32 v64, 48, v90
	v_ashrrev_i32_e32 v65, 31, v64
	v_mfma_f32_16x16x32_f16 v[40:43], v[8:11], v[104:107], v[40:43]
	v_lshlrev_b64 v[98:99], 10, v[98:99]
	v_lshl_add_u64 v[98:99], v[98:99], 0, v[88:89]
	v_mfma_f32_16x16x32_f16 v[24:27], v[8:11], v[108:111], v[32:35]
	v_mfma_f32_16x16x32_f16 v[32:35], v[92:95], v[104:107], v[84:87]
	v_lshlrev_b64 v[104:105], 10, v[64:65]
	v_lshl_add_u64 v[64:65], v[88:89], 2, s[8:9]
	v_add_co_u32_e32 v66, vcc, s48, v64
	v_mfma_f32_16x16x32_f16 v[8:11], v[8:11], v[116:119], v[68:71]
	s_nop 0
	v_addc_co_u32_e32 v67, vcc, 0, v65, vcc
	global_load_dword v64, v[66:67], off
	v_mfma_f32_16x16x32_f16 v[16:19], v[92:95], v[108:111], v[0:3]
	v_or_b32_e32 v106, 35, v90
	v_ashrrev_i32_e32 v107, 31, v106
	v_lshlrev_b64 v[106:107], 10, v[106:107]
	v_mfma_f32_16x16x32_f16 v[0:3], v[92:95], v[116:119], v[76:79]
	v_lshl_add_u64 v[106:107], v[106:107], 0, v[88:89]
	v_lshlrev_b64 v[108:109], 2, v[106:107]
	v_lshl_add_u64 v[106:107], s[2:3], 0, v[108:109]
	v_mfma_f32_16x16x32_f16 v[48:51], v[92:95], v[100:103], v[80:83]
	v_or_b32_e32 v92, 19, v90
	v_ashrrev_i32_e32 v93, 31, v92
	v_lshlrev_b64 v[92:93], 10, v[92:93]
	v_lshl_add_u64 v[92:93], v[92:93], 0, v[88:89]
	v_lshlrev_b64 v[94:95], 2, v[92:93]
	v_lshl_add_u64 v[92:93], s[2:3], 0, v[94:95]
	v_lshlrev_b64 v[100:101], 2, v[98:99]
	v_lshl_add_u64 v[98:99], s[2:3], 0, v[100:101]
	v_lshl_add_u64 v[104:105], v[104:105], 0, v[88:89]
	v_or_b32_e32 v110, 49, v90
	v_ashrrev_i32_e32 v111, 31, v110
	v_lshlrev_b64 v[110:111], 10, v[110:111]
	v_lshl_add_u64 v[110:111], v[110:111], 0, v[88:89]
	v_lshlrev_b64 v[116:117], 2, v[110:111]
	v_lshl_add_u64 v[110:111], s[2:3], 0, v[116:117]
	s_waitcnt vmcnt(0)
	v_add_f32_e32 v64, 1.0, v64
	v_mul_f32_e32 v112, 0.5, v64
	v_lshlrev_b64 v[64:65], 10, v[90:91]
	v_lshl_add_u64 v[64:65], v[64:65], 0, v[88:89]
	v_lshlrev_b64 v[64:65], 2, v[64:65]
	v_lshl_add_u64 v[68:69], s[2:3], 0, v[64:65]
	global_load_dword v70, v[68:69], off
	v_mul_f32_e32 v60, v60, v112
	v_lshl_add_u64 v[64:65], s[28:29], 0, v[64:65]
	s_waitcnt vmcnt(0)
	v_fmac_f32_e32 v60, 0x3fb504f3, v70
	v_or_b32_e32 v70, 1, v90
	v_ashrrev_i32_e32 v71, 31, v70
	v_lshlrev_b64 v[70:71], 10, v[70:71]
	v_lshl_add_u64 v[70:71], v[70:71], 0, v[88:89]
	v_lshlrev_b64 v[72:73], 2, v[70:71]
	global_store_dword v[64:65], v60, off
	v_lshl_add_u64 v[70:71], s[2:3], 0, v[72:73]
	global_load_dword v60, v[70:71], off
	s_waitcnt vmcnt(0)
	v_mul_f32_e32 v74, 0x3fb504f3, v60
	v_fmac_f32_e32 v74, v61, v112
	v_lshl_add_u64 v[60:61], s[28:29], 0, v[72:73]
	v_or_b32_e32 v72, 2, v90
	v_ashrrev_i32_e32 v73, 31, v72
	v_lshlrev_b64 v[72:73], 10, v[72:73]
	v_lshl_add_u64 v[72:73], v[72:73], 0, v[88:89]
	global_store_dword v[60:61], v74, off
	v_lshlrev_b64 v[74:75], 2, v[72:73]
	v_lshl_add_u64 v[72:73], s[2:3], 0, v[74:75]
	global_load_dword v76, v[72:73], off
	v_lshl_add_u64 v[74:75], s[28:29], 0, v[74:75]
	s_waitcnt vmcnt(0)
	v_mul_f32_e32 v76, 0x3fb504f3, v76
	v_fmac_f32_e32 v76, v62, v112
	global_store_dword v[74:75], v76, off
	v_or_b32_e32 v76, 3, v90
	v_ashrrev_i32_e32 v77, 31, v76
	v_lshlrev_b64 v[76:77], 10, v[76:77]
	v_lshl_add_u64 v[76:77], v[76:77], 0, v[88:89]
	v_lshlrev_b64 v[78:79], 2, v[76:77]
	v_lshl_add_u64 v[76:77], s[2:3], 0, v[78:79]
	global_load_dword v62, v[76:77], off
	s_waitcnt vmcnt(0)
	v_mul_f32_e32 v80, 0x3fb504f3, v62
	v_fmac_f32_e32 v80, v63, v112
	v_lshl_add_u64 v[62:63], s[28:29], 0, v[78:79]
	v_or_b32_e32 v78, 16, v90
	v_ashrrev_i32_e32 v79, 31, v78
	v_lshlrev_b64 v[78:79], 10, v[78:79]
	v_lshl_add_u64 v[78:79], v[78:79], 0, v[88:89]
	global_store_dword v[62:63], v80, off
	v_lshlrev_b64 v[80:81], 2, v[78:79]
	v_lshl_add_u64 v[78:79], s[2:3], 0, v[80:81]
	global_load_dword v82, v[78:79], off
	v_lshl_add_u64 v[80:81], s[28:29], 0, v[80:81]
	s_waitcnt vmcnt(0)
	v_mul_f32_e32 v82, 0x3fb504f3, v82
	v_fmac_f32_e32 v82, v56, v112
	global_store_dword v[80:81], v82, off
	v_or_b32_e32 v82, 17, v90
	v_ashrrev_i32_e32 v83, 31, v82
	v_lshlrev_b64 v[82:83], 10, v[82:83]
	v_lshl_add_u64 v[82:83], v[82:83], 0, v[88:89]
	v_lshlrev_b64 v[84:85], 2, v[82:83]
	v_lshl_add_u64 v[82:83], s[2:3], 0, v[84:85]
	global_load_dword v56, v[82:83], off
	s_waitcnt vmcnt(0)
	v_mul_f32_e32 v86, 0x3fb504f3, v56
	v_fmac_f32_e32 v86, v57, v112
	v_lshl_add_u64 v[56:57], s[28:29], 0, v[84:85]
	v_or_b32_e32 v84, 18, v90
	v_ashrrev_i32_e32 v85, 31, v84
	v_lshlrev_b64 v[84:85], 10, v[84:85]
	v_lshl_add_u64 v[84:85], v[84:85], 0, v[88:89]
	global_store_dword v[56:57], v86, off
	v_lshlrev_b64 v[86:87], 2, v[84:85]
	v_lshl_add_u64 v[84:85], s[2:3], 0, v[86:87]
	global_load_dword v91, v[84:85], off
	v_lshl_add_u64 v[86:87], s[28:29], 0, v[86:87]
	s_waitcnt vmcnt(0)
	v_mul_f32_e32 v91, 0x3fb504f3, v91
	v_fmac_f32_e32 v91, v58, v112
	global_store_dword v[86:87], v91, off
	global_load_dword v58, v[92:93], off
	s_waitcnt vmcnt(0)
	v_mul_f32_e32 v91, 0x3fb504f3, v58
	v_fmac_f32_e32 v91, v59, v112
	v_lshl_add_u64 v[58:59], s[28:29], 0, v[94:95]
	v_or_b32_e32 v94, 32, v90
	v_ashrrev_i32_e32 v95, 31, v94
	v_lshlrev_b64 v[94:95], 10, v[94:95]
	v_lshl_add_u64 v[94:95], v[94:95], 0, v[88:89]
	v_lshlrev_b64 v[96:97], 2, v[94:95]
	global_store_dword v[58:59], v91, off
	v_lshl_add_u64 v[94:95], s[2:3], 0, v[96:97]
	global_load_dword v91, v[94:95], off
	v_lshl_add_u64 v[96:97], s[28:29], 0, v[96:97]
	s_waitcnt vmcnt(0)
	v_mul_f32_e32 v91, 0x3fb504f3, v91
	v_fmac_f32_e32 v91, v52, v112
	global_store_dword v[96:97], v91, off
	global_load_dword v52, v[98:99], off
	s_waitcnt vmcnt(0)
	v_mul_f32_e32 v91, 0x3fb504f3, v52
	v_fmac_f32_e32 v91, v53, v112
	v_lshl_add_u64 v[52:53], s[28:29], 0, v[100:101]
	v_or_b32_e32 v100, 34, v90
	v_ashrrev_i32_e32 v101, 31, v100
	v_lshlrev_b64 v[100:101], 10, v[100:101]
	v_lshl_add_u64 v[100:101], v[100:101], 0, v[88:89]
	v_lshlrev_b64 v[102:103], 2, v[100:101]
	global_store_dword v[52:53], v91, off
	v_lshl_add_u64 v[100:101], s[2:3], 0, v[102:103]
	global_load_dword v91, v[100:101], off
	v_lshl_add_u64 v[102:103], s[28:29], 0, v[102:103]
	s_waitcnt vmcnt(0)
	v_mul_f32_e32 v91, 0x3fb504f3, v91
	v_fmac_f32_e32 v91, v54, v112
	global_store_dword v[102:103], v91, off
	global_load_dword v54, v[106:107], off
	s_waitcnt vmcnt(0)
	v_mul_f32_e32 v91, 0x3fb504f3, v54
	v_fmac_f32_e32 v91, v55, v112
	v_lshl_add_u64 v[54:55], s[28:29], 0, v[108:109]
	v_lshlrev_b64 v[108:109], 2, v[104:105]
	global_store_dword v[54:55], v91, off
	v_lshl_add_u64 v[104:105], s[2:3], 0, v[108:109]
	global_load_dword v91, v[104:105], off
	v_lshl_add_u64 v[108:109], s[28:29], 0, v[108:109]
	s_waitcnt vmcnt(0)
	v_mul_f32_e32 v91, 0x3fb504f3, v91
	v_fmac_f32_e32 v91, v48, v112
	global_store_dword v[108:109], v91, off
	global_load_dword v48, v[110:111], off
	s_waitcnt vmcnt(0)
	v_mul_f32_e32 v91, 0x3fb504f3, v48
	v_fmac_f32_e32 v91, v49, v112
	v_lshl_add_u64 v[48:49], s[28:29], 0, v[116:117]
	v_or_b32_e32 v116, 50, v90
	v_ashrrev_i32_e32 v117, 31, v116
	v_lshlrev_b64 v[116:117], 10, v[116:117]
	v_lshl_add_u64 v[116:117], v[116:117], 0, v[88:89]
	v_lshlrev_b64 v[118:119], 2, v[116:117]
	global_store_dword v[48:49], v91, off
	v_lshl_add_u64 v[116:117], s[2:3], 0, v[118:119]
	global_load_dword v91, v[116:117], off
	v_lshl_add_u64 v[118:119], s[28:29], 0, v[118:119]
	v_or_b32_e32 v90, 51, v90
	s_waitcnt vmcnt(0)
	v_mul_f32_e32 v91, 0x3fb504f3, v91
	v_fmac_f32_e32 v91, v50, v112
	global_store_dword v[118:119], v91, off
	v_ashrrev_i32_e32 v91, 31, v90
	v_lshlrev_b64 v[90:91], 10, v[90:91]
	v_lshl_add_u64 v[88:89], v[90:91], 0, v[88:89]
	v_lshlrev_b64 v[90:91], 2, v[88:89]
	v_lshl_add_u64 v[88:89], s[2:3], 0, v[90:91]
	global_load_dword v50, v[88:89], off
	s_waitcnt vmcnt(0)
	v_mul_f32_e32 v126, 0x3fb504f3, v50
	v_fmac_f32_e32 v126, v51, v112
	v_lshl_add_u64 v[50:51], s[28:29], 0, v[90:91]
	global_store_dword v[50:51], v126, off
	global_load_dword v90, v[66:67], off offset:64
	global_load_dword v91, v[68:69], off offset:64
	s_waitcnt vmcnt(1)
	v_add_f32_e32 v90, 1.0, v90
	v_mul_f32_e32 v90, 0.5, v90
	v_mul_f32_e32 v44, v44, v90
	s_waitcnt vmcnt(0)
	v_fmac_f32_e32 v44, 0x3fb504f3, v91
	global_store_dword v[64:65], v44, off offset:64
	global_load_dword v44, v[70:71], off offset:64
	s_waitcnt vmcnt(0)
	v_mul_f32_e32 v44, 0x3fb504f3, v44
	v_fmac_f32_e32 v44, v45, v90
	global_store_dword v[60:61], v44, off offset:64
	global_load_dword v44, v[72:73], off offset:64
	s_waitcnt vmcnt(0)
	v_mul_f32_e32 v44, 0x3fb504f3, v44
	v_fmac_f32_e32 v44, v46, v90
	global_store_dword v[74:75], v44, off offset:64
	global_load_dword v44, v[76:77], off offset:64
	s_waitcnt vmcnt(0)
	v_mul_f32_e32 v44, 0x3fb504f3, v44
	v_fmac_f32_e32 v44, v47, v90
	global_store_dword v[62:63], v44, off offset:64
	global_load_dword v44, v[78:79], off offset:64
	s_waitcnt vmcnt(0)
	v_mul_f32_e32 v44, 0x3fb504f3, v44
	v_fmac_f32_e32 v44, v40, v90
	global_store_dword v[80:81], v44, off offset:64
	global_load_dword v40, v[82:83], off offset:64
	s_waitcnt vmcnt(0)
	v_mul_f32_e32 v40, 0x3fb504f3, v40
	v_fmac_f32_e32 v40, v41, v90
	global_store_dword v[56:57], v40, off offset:64
	global_load_dword v40, v[84:85], off offset:64
	s_waitcnt vmcnt(0)
	v_mul_f32_e32 v40, 0x3fb504f3, v40
	v_fmac_f32_e32 v40, v42, v90
	global_store_dword v[86:87], v40, off offset:64
	global_load_dword v40, v[92:93], off offset:64
	s_waitcnt vmcnt(0)
	v_mul_f32_e32 v40, 0x3fb504f3, v40
	v_fmac_f32_e32 v40, v43, v90
	global_store_dword v[58:59], v40, off offset:64
	global_load_dword v40, v[94:95], off offset:64
	s_waitcnt vmcnt(0)
	v_mul_f32_e32 v40, 0x3fb504f3, v40
	v_fmac_f32_e32 v40, v36, v90
	global_store_dword v[96:97], v40, off offset:64
	global_load_dword v36, v[98:99], off offset:64
	s_waitcnt vmcnt(0)
	v_mul_f32_e32 v36, 0x3fb504f3, v36
	v_fmac_f32_e32 v36, v37, v90
	global_store_dword v[52:53], v36, off offset:64
	global_load_dword v36, v[100:101], off offset:64
	s_waitcnt vmcnt(0)
	v_mul_f32_e32 v36, 0x3fb504f3, v36
	v_fmac_f32_e32 v36, v38, v90
	global_store_dword v[102:103], v36, off offset:64
	global_load_dword v36, v[106:107], off offset:64
	s_waitcnt vmcnt(0)
	v_mul_f32_e32 v36, 0x3fb504f3, v36
	v_fmac_f32_e32 v36, v39, v90
	global_store_dword v[54:55], v36, off offset:64
	global_load_dword v36, v[104:105], off offset:64
	s_waitcnt vmcnt(0)
	v_mul_f32_e32 v36, 0x3fb504f3, v36
	v_fmac_f32_e32 v36, v32, v90
	global_store_dword v[108:109], v36, off offset:64
	global_load_dword v32, v[110:111], off offset:64
	s_waitcnt vmcnt(0)
	v_mul_f32_e32 v32, 0x3fb504f3, v32
	v_fmac_f32_e32 v32, v33, v90
	global_store_dword v[48:49], v32, off offset:64
	global_load_dword v32, v[116:117], off offset:64
	s_waitcnt vmcnt(0)
	v_mul_f32_e32 v32, 0x3fb504f3, v32
	v_fmac_f32_e32 v32, v34, v90
	global_store_dword v[118:119], v32, off offset:64
	global_load_dword v32, v[88:89], off offset:64
	s_waitcnt vmcnt(0)
	v_mul_f32_e32 v32, 0x3fb504f3, v32
	v_fmac_f32_e32 v32, v35, v90
	global_store_dword v[50:51], v32, off offset:64
	global_load_dword v32, v[66:67], off offset:128
	s_waitcnt vmcnt(0)
	v_add_f32_e32 v32, 1.0, v32
	global_load_dword v33, v[68:69], off offset:128
	v_mul_f32_e32 v32, 0.5, v32
	v_mul_f32_e32 v28, v28, v32
	s_waitcnt vmcnt(0)
	v_fmac_f32_e32 v28, 0x3fb504f3, v33
	global_store_dword v[64:65], v28, off offset:128
	global_load_dword v28, v[70:71], off offset:128
	s_waitcnt vmcnt(0)
	v_mul_f32_e32 v28, 0x3fb504f3, v28
	v_fmac_f32_e32 v28, v29, v32
	global_store_dword v[60:61], v28, off offset:128
	global_load_dword v28, v[72:73], off offset:128
	s_waitcnt vmcnt(0)
	v_mul_f32_e32 v28, 0x3fb504f3, v28
	v_fmac_f32_e32 v28, v30, v32
	global_store_dword v[74:75], v28, off offset:128
	global_load_dword v28, v[76:77], off offset:128
	s_waitcnt vmcnt(0)
	v_mul_f32_e32 v28, 0x3fb504f3, v28
	v_fmac_f32_e32 v28, v31, v32
	global_store_dword v[62:63], v28, off offset:128
	global_load_dword v28, v[78:79], off offset:128
	s_waitcnt vmcnt(0)
	v_mul_f32_e32 v28, 0x3fb504f3, v28
	v_fmac_f32_e32 v28, v24, v32
	global_store_dword v[80:81], v28, off offset:128
	global_load_dword v24, v[82:83], off offset:128
	s_waitcnt vmcnt(0)
	v_mul_f32_e32 v24, 0x3fb504f3, v24
	v_fmac_f32_e32 v24, v25, v32
	global_store_dword v[56:57], v24, off offset:128
	global_load_dword v24, v[84:85], off offset:128
	s_waitcnt vmcnt(0)
	v_mul_f32_e32 v24, 0x3fb504f3, v24
	v_fmac_f32_e32 v24, v26, v32
	global_store_dword v[86:87], v24, off offset:128
	global_load_dword v24, v[92:93], off offset:128
	s_waitcnt vmcnt(0)
	v_mul_f32_e32 v24, 0x3fb504f3, v24
	v_fmac_f32_e32 v24, v27, v32
	global_store_dword v[58:59], v24, off offset:128
	global_load_dword v24, v[94:95], off offset:128
	s_waitcnt vmcnt(0)
	v_mul_f32_e32 v24, 0x3fb504f3, v24
	v_fmac_f32_e32 v24, v20, v32
	global_store_dword v[96:97], v24, off offset:128
	global_load_dword v20, v[98:99], off offset:128
	s_waitcnt vmcnt(0)
	v_mul_f32_e32 v20, 0x3fb504f3, v20
	v_fmac_f32_e32 v20, v21, v32
	global_store_dword v[52:53], v20, off offset:128
	global_load_dword v20, v[100:101], off offset:128
	s_waitcnt vmcnt(0)
	v_mul_f32_e32 v20, 0x3fb504f3, v20
	v_fmac_f32_e32 v20, v22, v32
	global_store_dword v[102:103], v20, off offset:128
	global_load_dword v20, v[106:107], off offset:128
	s_waitcnt vmcnt(0)
	v_mul_f32_e32 v20, 0x3fb504f3, v20
	v_fmac_f32_e32 v20, v23, v32
	global_store_dword v[54:55], v20, off offset:128
	global_load_dword v20, v[104:105], off offset:128
	s_waitcnt vmcnt(0)
	v_mul_f32_e32 v20, 0x3fb504f3, v20
	v_fmac_f32_e32 v20, v16, v32
	global_store_dword v[108:109], v20, off offset:128
	global_load_dword v16, v[110:111], off offset:128
	s_waitcnt vmcnt(0)
	v_mul_f32_e32 v16, 0x3fb504f3, v16
	v_fmac_f32_e32 v16, v17, v32
	global_store_dword v[48:49], v16, off offset:128
	global_load_dword v16, v[116:117], off offset:128
	s_waitcnt vmcnt(0)
	v_mul_f32_e32 v16, 0x3fb504f3, v16
	v_fmac_f32_e32 v16, v18, v32
	global_store_dword v[118:119], v16, off offset:128
	global_load_dword v16, v[88:89], off offset:128
	s_waitcnt vmcnt(0)
	v_mul_f32_e32 v16, 0x3fb504f3, v16
	v_fmac_f32_e32 v16, v19, v32
	global_store_dword v[50:51], v16, off offset:128
	global_load_dword v16, v[66:67], off offset:192
	s_waitcnt vmcnt(0)
	v_add_f32_e32 v16, 1.0, v16
	global_load_dword v17, v[68:69], off offset:192
	v_mul_f32_e32 v16, 0.5, v16
	v_mul_f32_e32 v12, v12, v16
	s_waitcnt vmcnt(0)
	v_fmac_f32_e32 v12, 0x3fb504f3, v17
	global_store_dword v[64:65], v12, off offset:192
	global_load_dword v12, v[70:71], off offset:192
	s_waitcnt vmcnt(0)
	v_mul_f32_e32 v12, 0x3fb504f3, v12
	v_fmac_f32_e32 v12, v13, v16
	global_store_dword v[60:61], v12, off offset:192
	global_load_dword v12, v[72:73], off offset:192
	s_waitcnt vmcnt(0)
	v_mul_f32_e32 v12, 0x3fb504f3, v12
	v_fmac_f32_e32 v12, v14, v16
	global_store_dword v[74:75], v12, off offset:192
	global_load_dword v12, v[76:77], off offset:192
	s_waitcnt vmcnt(0)
	v_mul_f32_e32 v12, 0x3fb504f3, v12
	v_fmac_f32_e32 v12, v15, v16
	global_store_dword v[62:63], v12, off offset:192
	global_load_dword v12, v[78:79], off offset:192
	s_waitcnt vmcnt(0)
	v_mul_f32_e32 v12, 0x3fb504f3, v12
	v_fmac_f32_e32 v12, v8, v16
	global_store_dword v[80:81], v12, off offset:192
	global_load_dword v8, v[82:83], off offset:192
	s_waitcnt vmcnt(0)
	v_mul_f32_e32 v8, 0x3fb504f3, v8
	v_fmac_f32_e32 v8, v9, v16
	global_store_dword v[56:57], v8, off offset:192
	global_load_dword v8, v[84:85], off offset:192
	s_waitcnt vmcnt(0)
	v_mul_f32_e32 v8, 0x3fb504f3, v8
	v_fmac_f32_e32 v8, v10, v16
	global_store_dword v[86:87], v8, off offset:192
	global_load_dword v8, v[92:93], off offset:192
	s_waitcnt vmcnt(0)
	v_mul_f32_e32 v8, 0x3fb504f3, v8
	v_fmac_f32_e32 v8, v11, v16
	global_store_dword v[58:59], v8, off offset:192
	global_load_dword v8, v[94:95], off offset:192
	s_waitcnt vmcnt(0)
	v_mul_f32_e32 v8, 0x3fb504f3, v8
	v_fmac_f32_e32 v8, v4, v16
	global_store_dword v[96:97], v8, off offset:192
	global_load_dword v4, v[98:99], off offset:192
	s_waitcnt vmcnt(0)
	v_mul_f32_e32 v4, 0x3fb504f3, v4
	v_fmac_f32_e32 v4, v5, v16
	global_store_dword v[52:53], v4, off offset:192
	global_load_dword v4, v[100:101], off offset:192
	s_waitcnt vmcnt(0)
	v_mul_f32_e32 v4, 0x3fb504f3, v4
	v_fmac_f32_e32 v4, v6, v16
	global_store_dword v[102:103], v4, off offset:192
	global_load_dword v4, v[106:107], off offset:192
	s_waitcnt vmcnt(0)
	v_mul_f32_e32 v4, 0x3fb504f3, v4
	v_fmac_f32_e32 v4, v7, v16
	global_store_dword v[54:55], v4, off offset:192
	global_load_dword v4, v[104:105], off offset:192
	s_waitcnt vmcnt(0)
	v_mul_f32_e32 v4, 0x3fb504f3, v4
	v_fmac_f32_e32 v4, v0, v16
	global_store_dword v[108:109], v4, off offset:192
	global_load_dword v0, v[110:111], off offset:192
	s_waitcnt vmcnt(0)
	v_mul_f32_e32 v0, 0x3fb504f3, v0
	v_fmac_f32_e32 v0, v1, v16
	global_store_dword v[48:49], v0, off offset:192
	global_load_dword v0, v[116:117], off offset:192
	s_waitcnt vmcnt(0)
	v_mul_f32_e32 v0, 0x3fb504f3, v0
	v_fmac_f32_e32 v0, v2, v16
	global_store_dword v[118:119], v0, off offset:192
	global_load_dword v0, v[88:89], off offset:192
	s_waitcnt vmcnt(0)
	v_mul_f32_e32 v0, 0x3fb504f3, v0
	v_fmac_f32_e32 v0, v3, v16
	global_store_dword v[50:51], v0, off offset:192
	s_cbranch_scc0 .LBB0_153

.LBB0_224:
	s_and_b32 s45, s38, 0x8000
	s_lshr_b32 s4, s42, 4
	s_cmp_eq_u32 s4, 1
	s_cselect_b32 s5, s19, s41
	s_cselect_b32 s36, s18, s40
	s_cmp_eq_u32 s4, 2
	v_mov_b32_e32 v68, v182
	s_waitcnt vmcnt(0)
	s_waitcnt vmcnt(0) lgkmcnt(0)
	s_barrier
	s_cselect_b32 s4, s15, s17
	s_cselect_b32 s37, s14, s16
	s_add_i32 s38, s38, 0x8000
	s_and_b32 s46, s39, 0x3c0
	v_lshrrev_b32_e32 v64, 4, v68
	s_and_b32 s43, s38, 0x8000
	v_xor_b32_e32 v64, v64, v68
	s_lshl_b32 s46, s46, 1
	v_ashrrev_i32_e32 v69, 3, v68
	s_add_u32 s48, s36, s46
	v_lshlrev_b32_e32 v64, 4, v64
	v_add_u32_e32 v66, s3, v69
	s_addc_u32 s49, s5, 0
	v_and_b32_e32 v112, 0x70, v64
	v_ashrrev_i32_e32 v67, 31, v66
	v_lshl_add_u32 v70, v68, 4, s43
	v_lshl_add_u64 v[64:65], s[48:49], 0, v[112:113]
	v_lshlrev_b64 v[66:67], 11, v[66:67]
	v_readfirstlane_b32 s5, v70
	v_add_u32_e32 v71, 0x100, v68
	v_lshl_add_u64 v[66:67], v[64:65], 0, v[66:67]
	s_mov_b32 m0, s5
	v_ashrrev_i32_e32 v72, 3, v71
	global_load_lds_dwordx4 v[66:67], off
	v_add_u32_e32 v66, s3, v72
	v_ashrrev_i32_e32 v67, 31, v66
	v_lshl_add_u32 v71, v71, 4, s43
	v_lshlrev_b64 v[66:67], 11, v[66:67]
	v_readfirstlane_b32 s5, v71
	v_add_u32_e32 v73, 0x200, v68
	v_lshl_add_u64 v[66:67], v[64:65], 0, v[66:67]
	s_mov_b32 m0, s5
	v_ashrrev_i32_e32 v74, 3, v73
	global_load_lds_dwordx4 v[66:67], off
	v_add_u32_e32 v66, s3, v74
	v_ashrrev_i32_e32 v67, 31, v66
	v_lshl_add_u32 v73, v73, 4, s43
	v_lshlrev_b64 v[66:67], 11, v[66:67]
	v_readfirstlane_b32 s5, v73
	v_add_u32_e32 v68, 0x300, v68
	v_lshl_add_u64 v[66:67], v[64:65], 0, v[66:67]
	s_mov_b32 m0, s5
	v_ashrrev_i32_e32 v75, 3, v68
	global_load_lds_dwordx4 v[66:67], off
	v_add_u32_e32 v66, s3, v75
	v_ashrrev_i32_e32 v67, 31, v66
	v_lshlrev_b64 v[66:67], 11, v[66:67]
	v_lshl_add_u32 v68, v68, 4, s43
	v_lshl_add_u64 v[64:65], v[64:65], 0, v[66:67]
	v_readfirstlane_b32 s5, v68
	s_add_u32 s48, s37, s46
	v_add_u32_e32 v66, s44, v69
	s_mov_b32 m0, s5
	s_addc_u32 s49, s4, 0
	v_ashrrev_i32_e32 v67, 31, v66
	v_add_u32_e32 v69, 0x4000, v70
	global_load_lds_dwordx4 v[64:65], off
	v_lshl_add_u64 v[64:65], s[48:49], 0, v[112:113]
	v_lshlrev_b64 v[66:67], 11, v[66:67]
	v_readfirstlane_b32 s4, v69
	v_lshl_add_u64 v[66:67], v[64:65], 0, v[66:67]
	s_mov_b32 m0, s4
	v_add_u32_e32 v69, 0x4000, v71
	global_load_lds_dwordx4 v[66:67], off
	v_add_u32_e32 v66, s44, v72
	v_ashrrev_i32_e32 v67, 31, v66
	v_lshlrev_b64 v[66:67], 11, v[66:67]
	v_readfirstlane_b32 s4, v69
	v_lshl_add_u64 v[66:67], v[64:65], 0, v[66:67]
	s_mov_b32 m0, s4
	v_add_u32_e32 v69, 0x4000, v73
	global_load_lds_dwordx4 v[66:67], off
	v_add_u32_e32 v66, s44, v74
	v_ashrrev_i32_e32 v67, 31, v66
	v_lshlrev_b64 v[66:67], 11, v[66:67]
	v_readfirstlane_b32 s4, v69
	v_lshl_add_u64 v[66:67], v[64:65], 0, v[66:67]
	s_mov_b32 m0, s4
	v_or_b32_e32 v87, s45, v106
	global_load_lds_dwordx4 v[66:67], off
	v_add_u32_e32 v66, s44, v75
	v_ashrrev_i32_e32 v67, 31, v66
	v_lshlrev_b64 v[66:67], 11, v[66:67]
	v_lshl_add_u64 v[64:65], v[64:65], 0, v[66:67]
	v_add_u32_e32 v66, 0x4000, v68
	s_add_i32 s39, s39, 64
	v_readfirstlane_b32 s4, v66
	s_mov_b32 m0, s4
	s_add_i32 s42, s42, 1
	global_load_lds_dwordx4 v[64:65], off
	v_add3_u32 v64, v87, v107, v108
	v_add3_u32 v87, v87, v109, v108
	ds_read_b128 v[76:79], v64
	ds_read_b128 v[72:75], v64 offset:2048
	ds_read_b128 v[68:71], v64 offset:4096
	ds_read_b128 v[64:67], v64 offset:6144
	ds_read_b128 v[88:91], v87 offset:16384
	ds_read_b128 v[92:95], v87 offset:18432
	ds_read_b128 v[96:99], v87 offset:20480
	ds_read_b128 v[100:103], v87 offset:22528
	v_or_b32_e32 v87, s45, v110
	s_waitcnt lgkmcnt(0)
	v_mfma_f32_16x16x32_f16 v[60:63], v[76:79], v[88:91], v[60:63]
	s_cmp_eq_u32 s0, s38
	v_mfma_f32_16x16x32_f16 v[56:59], v[76:79], v[92:95], v[56:59]
	v_mfma_f32_16x16x32_f16 v[52:55], v[76:79], v[96:99], v[52:55]
	v_mfma_f32_16x16x32_f16 v[48:51], v[76:79], v[100:103], v[48:51]
	v_add3_u32 v76, v87, v107, v108
	v_add3_u32 v87, v87, v109, v108
	v_mfma_f32_16x16x32_f16 v[44:47], v[72:75], v[88:91], v[44:47]
	v_mfma_f32_16x16x32_f16 v[40:43], v[72:75], v[92:95], v[40:43]
	v_mfma_f32_16x16x32_f16 v[36:39], v[72:75], v[96:99], v[36:39]
	v_mfma_f32_16x16x32_f16 v[32:35], v[72:75], v[100:103], v[32:35]
	v_mfma_f32_16x16x32_f16 v[28:31], v[68:71], v[88:91], v[28:31]
	v_mfma_f32_16x16x32_f16 v[24:27], v[68:71], v[92:95], v[24:27]
	v_mfma_f32_16x16x32_f16 v[20:23], v[68:71], v[96:99], v[20:23]
	v_mfma_f32_16x16x32_f16 v[16:19], v[68:71], v[100:103], v[16:19]
	v_mfma_f32_16x16x32_f16 v[12:15], v[64:67], v[88:91], v[12:15]
	v_mfma_f32_16x16x32_f16 v[8:11], v[64:67], v[92:95], v[8:11]
	v_mfma_f32_16x16x32_f16 v[4:7], v[64:67], v[96:99], v[4:7]
	v_mfma_f32_16x16x32_f16 v[0:3], v[64:67], v[100:103], v[0:3]
	ds_read_b128 v[64:67], v76
	ds_read_b128 v[68:71], v76 offset:2048
	ds_read_b128 v[72:75], v76 offset:4096
	ds_read_b128 v[76:79], v76 offset:6144
	ds_read_b128 v[88:91], v87 offset:16384
	ds_read_b128 v[92:95], v87 offset:18432
	ds_read_b128 v[96:99], v87 offset:20480
	ds_read_b128 v[100:103], v87 offset:22528
	s_waitcnt lgkmcnt(3)
	v_mfma_f32_16x16x32_f16 v[60:63], v[64:67], v[88:91], v[60:63]
	s_waitcnt lgkmcnt(2)
	v_mfma_f32_16x16x32_f16 v[56:59], v[64:67], v[92:95], v[56:59]
	s_waitcnt lgkmcnt(1)
	v_mfma_f32_16x16x32_f16 v[52:55], v[64:67], v[96:99], v[52:55]
	s_waitcnt lgkmcnt(0)
	v_mfma_f32_16x16x32_f16 v[48:51], v[64:67], v[100:103], v[48:51]
	v_mfma_f32_16x16x32_f16 v[44:47], v[68:71], v[88:91], v[44:47]
	v_mfma_f32_16x16x32_f16 v[40:43], v[68:71], v[92:95], v[40:43]
	v_mfma_f32_16x16x32_f16 v[36:39], v[68:71], v[96:99], v[36:39]
	v_mfma_f32_16x16x32_f16 v[32:35], v[68:71], v[100:103], v[32:35]
	v_mfma_f32_16x16x32_f16 v[28:31], v[72:75], v[88:91], v[28:31]
	v_mfma_f32_16x16x32_f16 v[24:27], v[72:75], v[92:95], v[24:27]
	v_mfma_f32_16x16x32_f16 v[20:23], v[72:75], v[96:99], v[20:23]
	v_mfma_f32_16x16x32_f16 v[16:19], v[72:75], v[100:103], v[16:19]
	v_mfma_f32_16x16x32_f16 v[12:15], v[76:79], v[88:91], v[12:15]
	v_mfma_f32_16x16x32_f16 v[8:11], v[76:79], v[92:95], v[8:11]
	v_mfma_f32_16x16x32_f16 v[4:7], v[76:79], v[96:99], v[4:7]
	v_mfma_f32_16x16x32_f16 v[0:3], v[76:79], v[100:103], v[0:3]
	s_cbranch_scc0 .LBB0_224
	v_add_u32_e32 v68, s43, v106
	v_add3_u32 v87, v68, v107, v108
	s_waitcnt vmcnt(0)
	s_barrier
	ds_read_b128 v[64:67], v87
	v_add3_u32 v88, v68, v109, v108
	ds_read_b128 v[68:71], v88 offset:16384
	ds_read_b128 v[72:75], v88 offset:18432
	ds_read_b128 v[76:79], v88 offset:20480
	ds_read_b128 v[88:91], v88 offset:22528
	s_waitcnt lgkmcnt(3)
	v_mfma_f32_16x16x32_f16 v[60:63], v[64:67], v[68:71], v[60:63]
	s_mov_b64 s[14:15], -1
	s_and_b64 vcc, exec, s[12:13]
	s_mov_b32 s39, s1
	s_waitcnt lgkmcnt(2)
	v_mfma_f32_16x16x32_f16 v[56:59], v[64:67], v[72:75], v[56:59]
	s_mov_b32 s46, 0x9000
	s_movk_i32 s48, 0x2000
	s_mov_b32 s49, 0x800000
	s_waitcnt lgkmcnt(1)
	v_mfma_f32_16x16x32_f16 v[52:55], v[64:67], v[76:79], v[52:55]
	s_movk_i32 s44, 0x3c60
	s_movk_i32 s45, 0x104
	s_waitcnt lgkmcnt(0)
	v_mfma_f32_16x16x32_f16 v[48:51], v[64:67], v[88:91], v[48:51]
	ds_read_b128 v[64:67], v87 offset:2048
	s_waitcnt lgkmcnt(0)
	v_mfma_f32_16x16x32_f16 v[92:95], v[64:67], v[76:79], v[36:39]
	s_nop 2
	ds_read_b128 v[36:39], v87 offset:4096
	s_waitcnt lgkmcnt(0)
	v_mfma_f32_16x16x32_f16 v[96:99], v[36:39], v[76:79], v[20:23]
	s_nop 2
	ds_read_b128 v[20:23], v87 offset:6144
	v_mfma_f32_16x16x32_f16 v[44:47], v[64:67], v[68:71], v[44:47]
	v_mfma_f32_16x16x32_f16 v[40:43], v[64:67], v[72:75], v[40:43]
	v_mfma_f32_16x16x32_f16 v[32:35], v[64:67], v[88:91], v[32:35]
	v_mfma_f32_16x16x32_f16 v[64:67], v[36:39], v[72:75], v[24:27]
	s_waitcnt lgkmcnt(0)
	v_mfma_f32_16x16x32_f16 v[72:75], v[20:23], v[72:75], v[8:11]
	s_nop 2
	v_add_u32_e32 v8, s43, v110
	v_add3_u32 v87, v8, v107, v108
	v_mfma_f32_16x16x32_f16 v[76:79], v[20:23], v[76:79], v[4:7]
	v_readlane_b32 s42, v249, 24
	v_readlane_b32 s43, v249, 25
	s_nop 0
	ds_read_b128 v[4:7], v87
	v_mfma_f32_16x16x32_f16 v[16:19], v[36:39], v[88:91], v[16:19]
	v_mfma_f32_16x16x32_f16 v[88:91], v[20:23], v[88:91], v[0:3]
	s_nop 2
	v_add3_u32 v0, v8, v109, v108
	ds_read_b128 v[100:103], v0 offset:16384
	ds_read_b128 v[116:119], v0 offset:18432
	ds_read_b128 v[120:123], v0 offset:20480
	ds_read_b128 v[124:127], v0 offset:22528
	v_mfma_f32_16x16x32_f16 v[28:31], v[36:39], v[68:71], v[28:31]
	v_mfma_f32_16x16x32_f16 v[68:71], v[20:23], v[68:71], v[12:15]
	s_nop 2
	ds_read_b128 v[12:15], v87 offset:4096
	s_waitcnt lgkmcnt(4)
	v_mfma_f32_16x16x32_f16 v[60:63], v[4:7], v[100:103], v[60:63]
	s_waitcnt lgkmcnt(3)
	v_mfma_f32_16x16x32_f16 v[20:23], v[4:7], v[116:119], v[56:59]
	s_waitcnt lgkmcnt(2)
	v_mfma_f32_16x16x32_f16 v[8:11], v[4:7], v[120:123], v[52:55]
	s_waitcnt lgkmcnt(1)
	v_mfma_f32_16x16x32_f16 v[0:3], v[4:7], v[124:127], v[48:51]
	ds_read_b128 v[4:7], v87 offset:2048
	s_waitcnt lgkmcnt(0)
	v_mfma_f32_16x16x32_f16 v[36:39], v[4:7], v[116:119], v[40:43]
	v_mfma_f32_16x16x32_f16 v[52:55], v[12:15], v[100:103], v[28:31]
	v_mfma_f32_16x16x32_f16 v[40:43], v[12:15], v[116:119], v[64:67]
	v_mfma_f32_16x16x32_f16 v[28:31], v[12:15], v[120:123], v[96:99]
	v_mfma_f32_16x16x32_f16 v[12:15], v[12:15], v[124:127], v[16:19]
	s_nop 2
	ds_read_b128 v[16:19], v87 offset:6144
	v_mfma_f32_16x16x32_f16 v[56:59], v[4:7], v[100:103], v[44:47]
	v_mfma_f32_16x16x32_f16 v[24:27], v[4:7], v[120:123], v[92:95]
	v_mfma_f32_16x16x32_f16 v[4:7], v[4:7], v[124:127], v[32:35]
	s_waitcnt lgkmcnt(0)
	v_mfma_f32_16x16x32_f16 v[48:51], v[16:19], v[100:103], v[68:71]
	v_mfma_f32_16x16x32_f16 v[44:47], v[16:19], v[116:119], v[72:75]
	v_mfma_f32_16x16x32_f16 v[32:35], v[16:19], v[120:123], v[76:79]
	v_mfma_f32_16x16x32_f16 v[16:19], v[16:19], v[124:127], v[88:91]
	s_cbranch_vccz .LBB0_237
	s_mov_b64 s[16:17], -1
	s_mov_b64 s[12:13], 0
	s_cmp_lt_i32 s22, 20
	s_cbranch_scc1 .LBB0_238
	s_cmp_gt_i32 s22, 29
	s_mov_b64 s[14:15], 0
	s_cbranch_scc0 .LBB0_234
	s_cmp_eq_u32 s22, 30
	s_mov_b64 s[14:15], -1
	s_cbranch_scc0 .LBB0_246
	v_add_u32_e32 v79, s3, v105
	v_or_b32_e32 v78, 1, v79
	v_or_b32_e32 v77, 2, v79
	v_or_b32_e32 v76, 3, v79
	v_or_b32_e32 v75, 16, v79
	v_or_b32_e32 v74, 17, v79
	v_or_b32_e32 v73, 18, v79
	v_or_b32_e32 v72, 19, v79
	v_or_b32_e32 v71, 32, v79
	v_or_b32_e32 v70, 33, v79
	v_or_b32_e32 v69, 34, v79
	v_or_b32_e32 v68, 35, v79
	v_or_b32_e32 v67, 48, v79
	v_or_b32_e32 v66, 49, v79
	v_or_b32_e32 v65, 50, v79
	v_or_b32_e32 v64, 51, v79
	s_and_saveexec_b64 s[14:15], s[8:9]
	s_cbranch_execz .LBB0_231
	s_movk_i32 s0, 0x60
	v_mad_i64_i32 v[88:89], s[16:17], v79, s0, v[80:81]
	global_store_dword v[88:89], v60, off
	v_mad_i64_i32 v[88:89], s[16:17], v78, s0, v[80:81]
	global_store_dword v[88:89], v61, off
	v_mad_i64_i32 v[88:89], s[16:17], v77, s0, v[80:81]
	global_store_dword v[88:89], v62, off
	v_mad_i64_i32 v[88:89], s[16:17], v76, s0, v[80:81]
	global_store_dword v[88:89], v63, off
	v_mad_i64_i32 v[88:89], s[16:17], v75, s0, v[80:81]
	global_store_dword v[88:89], v56, off
	v_mad_i64_i32 v[88:89], s[16:17], v74, s0, v[80:81]
	global_store_dword v[88:89], v57, off
	v_mad_i64_i32 v[88:89], s[16:17], v73, s0, v[80:81]
	global_store_dword v[88:89], v58, off
	v_mad_i64_i32 v[88:89], s[16:17], v72, s0, v[80:81]
	global_store_dword v[88:89], v59, off
	v_mad_i64_i32 v[88:89], s[16:17], v71, s0, v[80:81]
	global_store_dword v[88:89], v52, off
	v_mad_i64_i32 v[88:89], s[16:17], v70, s0, v[80:81]
	global_store_dword v[88:89], v53, off
	v_mad_i64_i32 v[88:89], s[16:17], v69, s0, v[80:81]
	global_store_dword v[88:89], v54, off
	v_mad_i64_i32 v[88:89], s[16:17], v68, s0, v[80:81]
	global_store_dword v[88:89], v55, off
	v_mad_i64_i32 v[88:89], s[16:17], v67, s0, v[80:81]
	global_store_dword v[88:89], v48, off
	v_mad_i64_i32 v[88:89], s[16:17], v66, s0, v[80:81]
	global_store_dword v[88:89], v49, off
	v_mad_i64_i32 v[88:89], s[16:17], v65, s0, v[80:81]
	global_store_dword v[88:89], v50, off
	v_mad_i64_i32 v[88:89], s[16:17], v64, s0, v[80:81]
	global_store_dword v[88:89], v51, off

.LBB0_250:
	s_add_i32 s4, s13, 0xffff8000
	s_lshr_b32 s14, s11, 4
	s_and_b32 s15, s4, 0x8000
	v_mov_b32_e32 v83, v182
	s_cmp_eq_u32 s14, 1
	s_waitcnt vmcnt(0)
	s_waitcnt vmcnt(0) lgkmcnt(0)
	s_barrier
	s_cselect_b32 s4, s35, s41
	v_lshrrev_b32_e32 v73, 4, v83
	s_cselect_b32 s5, s34, s40
	s_cmp_eq_u32 s14, 2
	v_xor_b32_e32 v77, v73, v83
	s_cselect_b32 s18, s9, s3
	s_cselect_b32 s19, s8, s2
	s_and_b32 s16, s12, 0x3c0
	v_ashrrev_i32_e32 v72, 3, v83
	v_add_u32_e32 v85, 0x100, v83
	v_add_u32_e32 v88, 0x300, v83
	s_and_b32 s14, s13, 0x8000
	v_lshlrev_b32_e32 v89, 4, v77
	s_lshl_b32 s20, s16, 1
	v_add_u32_e32 v87, 0x200, v83
	v_or_b32_e32 v75, s15, v67
	v_add_u32_e32 v74, s0, v72
	v_ashrrev_i32_e32 v76, 3, v85
	v_ashrrev_i32_e32 v80, 3, v88
	v_and_b32_e32 v112, 0x70, v89
	v_lshl_add_u32 v89, v83, 4, s14
	v_lshl_add_u32 v88, v88, 4, s14
	s_add_u32 s16, s5, s20
	v_ashrrev_i32_e32 v78, 3, v87
	v_add3_u32 v92, v75, v68, v69
	v_add3_u32 v90, v75, v70, v69
	v_ashrrev_i32_e32 v75, 31, v74
	v_add_u32_e32 v82, s0, v76
	v_readfirstlane_b32 s5, v89
	v_readfirstlane_b32 s23, v88
	v_add_u32_e32 v89, 0x4000, v89
	v_add_u32_e32 v88, 0x4000, v88
	s_addc_u32 s17, s4, 0
	v_add_u32_e32 v84, s0, v78
	v_lshlrev_b64 v[74:75], 11, v[74:75]
	v_ashrrev_i32_e32 v83, 31, v82
	v_lshl_add_u32 v91, v85, 4, s14
	v_readfirstlane_b32 s4, v89
	v_readfirstlane_b32 s38, v88
	v_lshl_add_u64 v[88:89], s[16:17], 0, v[112:113]
	v_add_u32_e32 v86, s0, v80
	v_ashrrev_i32_e32 v85, 31, v84
	v_lshl_add_u32 v93, v87, 4, s14
	v_lshlrev_b64 v[82:83], 11, v[82:83]
	v_readfirstlane_b32 s21, v91
	v_lshl_add_u64 v[74:75], v[88:89], 0, v[74:75]
	s_mov_b32 m0, s5
	v_ashrrev_i32_e32 v87, 31, v86
	v_lshlrev_b64 v[84:85], 11, v[84:85]
	v_readfirstlane_b32 s22, v93
	s_add_u32 s16, s19, s20
	v_lshl_add_u64 v[82:83], v[88:89], 0, v[82:83]
	global_load_lds_dwordx4 v[74:75], off
	s_mov_b32 m0, s21
	v_ashrrev_i32_e32 v73, 31, v72
	v_lshlrev_b64 v[86:87], 11, v[86:87]
	v_lshl_add_u64 v[84:85], v[88:89], 0, v[84:85]
	s_addc_u32 s17, s18, 0
	global_load_lds_dwordx4 v[82:83], off
	s_mov_b32 m0, s22
	v_lshlrev_b64 v[72:73], 11, v[72:73]
	v_ashrrev_i32_e32 v77, 31, v76
	v_add_u32_e32 v91, 0x4000, v91
	v_lshl_add_u64 v[86:87], v[88:89], 0, v[86:87]
	v_lshl_add_u64 v[74:75], s[16:17], 0, v[112:113]
	global_load_lds_dwordx4 v[84:85], off
	s_mov_b32 m0, s23
	v_ashrrev_i32_e32 v79, 31, v78
	v_lshlrev_b64 v[76:77], 11, v[76:77]
	v_add_u32_e32 v93, 0x4000, v93
	v_readfirstlane_b32 s36, v91
	v_lshl_add_u64 v[72:73], v[74:75], 0, v[72:73]
	global_load_lds_dwordx4 v[86:87], off
	s_mov_b32 m0, s4
	v_ashrrev_i32_e32 v81, 31, v80
	v_lshlrev_b64 v[78:79], 11, v[78:79]
	v_readfirstlane_b32 s37, v93
	v_lshl_add_u64 v[76:77], v[74:75], 0, v[76:77]
	global_load_lds_dwordx4 v[72:73], off
	s_mov_b32 m0, s36
	v_lshlrev_b64 v[80:81], 11, v[80:81]
	v_lshl_add_u64 v[78:79], v[74:75], 0, v[78:79]
	global_load_lds_dwordx4 v[76:77], off
	s_mov_b32 m0, s37
	v_lshl_add_u64 v[74:75], v[74:75], 0, v[80:81]
	global_load_lds_dwordx4 v[78:79], off
	s_mov_b32 m0, s38
	s_add_i32 s11, s11, 1
	global_load_lds_dwordx4 v[74:75], off
	ds_read_b128 v[72:75], v92
	ds_read_b128 v[76:79], v90 offset:16384
	ds_read_b128 v[80:83], v90 offset:18432
	ds_read_b128 v[84:87], v90 offset:20480
	ds_read_b128 v[88:91], v90 offset:22528
	s_waitcnt lgkmcnt(0)
	v_mfma_f32_16x16x32_f16 v[60:63], v[72:75], v[76:79], v[60:63]
	s_add_i32 s12, s12, 64
	s_add_i32 s13, s13, 0x8000
	s_cmp_eq_u32 s11, 48
	v_mfma_f32_16x16x32_f16 v[56:59], v[72:75], v[80:83], v[56:59]
	v_mfma_f32_16x16x32_f16 v[52:55], v[72:75], v[84:87], v[52:55]
	v_mfma_f32_16x16x32_f16 v[48:51], v[72:75], v[88:91], v[48:51]
	ds_read_b128 v[72:75], v92 offset:2048
	s_waitcnt lgkmcnt(0)
	v_mfma_f32_16x16x32_f16 v[44:47], v[72:75], v[76:79], v[44:47]
	v_mfma_f32_16x16x32_f16 v[40:43], v[72:75], v[80:83], v[40:43]
	v_mfma_f32_16x16x32_f16 v[36:39], v[72:75], v[84:87], v[36:39]
	v_mfma_f32_16x16x32_f16 v[28:31], v[72:75], v[88:91], v[28:31]
	ds_read_b128 v[72:75], v92 offset:4096
	s_waitcnt lgkmcnt(0)
	v_mfma_f32_16x16x32_f16 v[24:27], v[72:75], v[76:79], v[24:27]
	v_mfma_f32_16x16x32_f16 v[20:23], v[72:75], v[80:83], v[20:23]
	v_mfma_f32_16x16x32_f16 v[16:19], v[72:75], v[84:87], v[16:19]
	v_mfma_f32_16x16x32_f16 v[12:15], v[72:75], v[88:91], v[12:15]
	ds_read_b128 v[72:75], v92 offset:6144
	s_waitcnt lgkmcnt(0)
	v_mfma_f32_16x16x32_f16 v[8:11], v[72:75], v[76:79], v[8:11]
	v_or_b32_e32 v76, s15, v71
	v_add3_u32 v92, v76, v68, v69
	v_add3_u32 v93, v76, v70, v69
	ds_read_b128 v[76:79], v92
	v_mfma_f32_16x16x32_f16 v[4:7], v[72:75], v[80:83], v[4:7]
	ds_read_b128 v[80:83], v93 offset:18432
	v_mfma_f32_16x16x32_f16 v[0:3], v[72:75], v[84:87], v[0:3]
	ds_read_b128 v[84:87], v93 offset:20480
	v_mfma_f32_16x16x32_f16 v[32:35], v[72:75], v[88:91], v[32:35]
	ds_read_b128 v[72:75], v93 offset:16384
	ds_read_b128 v[88:91], v93 offset:22528
	s_waitcnt lgkmcnt(1)
	v_mfma_f32_16x16x32_f16 v[60:63], v[76:79], v[72:75], v[60:63]
	v_mfma_f32_16x16x32_f16 v[56:59], v[76:79], v[80:83], v[56:59]
	v_mfma_f32_16x16x32_f16 v[52:55], v[76:79], v[84:87], v[52:55]
	s_waitcnt lgkmcnt(0)
	v_mfma_f32_16x16x32_f16 v[48:51], v[76:79], v[88:91], v[48:51]
	ds_read_b128 v[76:79], v92 offset:2048
	s_waitcnt lgkmcnt(0)
	v_mfma_f32_16x16x32_f16 v[44:47], v[76:79], v[72:75], v[44:47]
	v_mfma_f32_16x16x32_f16 v[40:43], v[76:79], v[80:83], v[40:43]
	v_mfma_f32_16x16x32_f16 v[36:39], v[76:79], v[84:87], v[36:39]
	v_mfma_f32_16x16x32_f16 v[28:31], v[76:79], v[88:91], v[28:31]
	ds_read_b128 v[76:79], v92 offset:4096
	s_waitcnt lgkmcnt(0)
	v_mfma_f32_16x16x32_f16 v[24:27], v[76:79], v[72:75], v[24:27]
	v_mfma_f32_16x16x32_f16 v[20:23], v[76:79], v[80:83], v[20:23]
	v_mfma_f32_16x16x32_f16 v[16:19], v[76:79], v[84:87], v[16:19]
	v_mfma_f32_16x16x32_f16 v[12:15], v[76:79], v[88:91], v[12:15]
	ds_read_b128 v[76:79], v92 offset:6144
	s_waitcnt lgkmcnt(0)
	v_mfma_f32_16x16x32_f16 v[8:11], v[76:79], v[72:75], v[8:11]
	v_mfma_f32_16x16x32_f16 v[4:7], v[76:79], v[80:83], v[4:7]
	v_mfma_f32_16x16x32_f16 v[0:3], v[76:79], v[84:87], v[0:3]
	v_mfma_f32_16x16x32_f16 v[32:35], v[76:79], v[88:91], v[32:35]
	s_cbranch_scc0 .LBB0_250
	v_add_u32_e32 v88, s14, v67
	v_add3_u32 v84, v88, v68, v69
	v_add3_u32 v100, v88, v70, v69
	s_waitcnt vmcnt(0)
	s_barrier
	ds_read_b128 v[72:75], v84
	ds_read_b128 v[76:79], v84 offset:2048
	ds_read_b128 v[80:83], v84 offset:4096
	ds_read_b128 v[84:87], v84 offset:6144
	ds_read_b128 v[88:91], v100 offset:16384
	ds_read_b128 v[92:95], v100 offset:18432
	ds_read_b128 v[96:99], v100 offset:20480
	ds_read_b128 v[100:103], v100 offset:22528
	s_waitcnt lgkmcnt(3)
	v_mfma_f32_16x16x32_f16 v[44:47], v[76:79], v[88:91], v[44:47]
	s_add_i32 s10, s10, s59
	s_cmpk_gt_i32 s10, 0xff
	s_waitcnt lgkmcnt(2)
	v_mfma_f32_16x16x32_f16 v[40:43], v[76:79], v[92:95], v[40:43]
	s_waitcnt lgkmcnt(1)
	v_mfma_f32_16x16x32_f16 v[36:39], v[76:79], v[96:99], v[36:39]
	s_waitcnt lgkmcnt(0)
	v_mfma_f32_16x16x32_f16 v[28:31], v[76:79], v[100:103], v[28:31]
	v_mfma_f32_16x16x32_f16 v[76:79], v[80:83], v[96:99], v[16:19]
	s_nop 2
	v_add_u32_e32 v16, s14, v71
	v_add3_u32 v17, v16, v68, v69
	v_add3_u32 v16, v16, v70, v69
	v_mfma_f32_16x16x32_f16 v[60:63], v[72:75], v[88:91], v[60:63]
	v_mfma_f32_16x16x32_f16 v[56:59], v[72:75], v[92:95], v[56:59]
	v_mfma_f32_16x16x32_f16 v[52:55], v[72:75], v[96:99], v[52:55]
	v_mfma_f32_16x16x32_f16 v[48:51], v[72:75], v[100:103], v[48:51]
	v_mfma_f32_16x16x32_f16 v[24:27], v[80:83], v[88:91], v[24:27]
	v_mfma_f32_16x16x32_f16 v[72:75], v[80:83], v[92:95], v[20:23]
	v_mfma_f32_16x16x32_f16 v[12:15], v[80:83], v[100:103], v[12:15]
	v_mfma_f32_16x16x32_f16 v[80:83], v[84:87], v[88:91], v[8:11]
	v_mfma_f32_16x16x32_f16 v[88:91], v[84:87], v[92:95], v[4:7]
	v_mfma_f32_16x16x32_f16 v[92:95], v[84:87], v[96:99], v[0:3]
	v_mfma_f32_16x16x32_f16 v[32:35], v[84:87], v[100:103], v[32:35]
	s_nop 1
	ds_read_b128 v[0:3], v17
	ds_read_b128 v[4:7], v17 offset:2048
	ds_read_b128 v[8:11], v17 offset:4096
	ds_read_b128 v[84:87], v17 offset:6144
	ds_read_b128 v[96:99], v16 offset:16384
	ds_read_b128 v[100:103], v16 offset:18432
	ds_read_b128 v[104:107], v16 offset:20480
	ds_read_b128 v[108:111], v16 offset:22528
	s_waitcnt lgkmcnt(3)
	v_mfma_f32_16x16x32_f16 v[60:63], v[0:3], v[96:99], v[60:63]
	s_waitcnt lgkmcnt(2)
	v_mfma_f32_16x16x32_f16 v[56:59], v[0:3], v[100:103], v[56:59]
	s_waitcnt lgkmcnt(1)
	v_mfma_f32_16x16x32_f16 v[16:19], v[0:3], v[104:107], v[52:55]
	s_waitcnt lgkmcnt(0)
	v_mfma_f32_16x16x32_f16 v[0:3], v[0:3], v[108:111], v[48:51]
	v_mfma_f32_16x16x32_f16 v[20:23], v[4:7], v[104:107], v[36:39]
	v_mfma_f32_16x16x32_f16 v[36:39], v[8:11], v[96:99], v[24:27]
	v_mfma_f32_16x16x32_f16 v[48:51], v[8:11], v[100:103], v[72:75]
	v_mfma_f32_16x16x32_f16 v[24:27], v[8:11], v[104:107], v[76:79]
	v_mfma_f32_16x16x32_f16 v[8:11], v[8:11], v[108:111], v[12:15]
	v_mfma_f32_16x16x32_f16 v[12:15], v[84:87], v[108:111], v[32:35]
	s_nop 2
	v_add_u32_e32 v32, s0, v66
	v_ashrrev_i32_e32 v33, 31, v32
	v_or_b32_e32 v76, 1, v32
	v_lshlrev_b64 v[34:35], 9, v[32:33]
	v_ashrrev_i32_e32 v77, 31, v76
	v_lshl_add_u64 v[34:35], v[64:65], 0, v[34:35]
	v_lshlrev_b64 v[76:77], 9, v[76:77]
	global_store_dword v[34:35], v60, off
	v_lshl_add_u64 v[76:77], v[64:65], 0, v[76:77]
	v_or_b32_e32 v60, 2, v32
	global_store_dword v[76:77], v61, off
	v_ashrrev_i32_e32 v61, 31, v60
	v_or_b32_e32 v78, 3, v32
	v_lshlrev_b64 v[60:61], 9, v[60:61]
	v_ashrrev_i32_e32 v79, 31, v78
	v_lshl_add_u64 v[60:61], v[64:65], 0, v[60:61]
	v_lshlrev_b64 v[78:79], 9, v[78:79]
	v_mfma_f32_16x16x32_f16 v[44:47], v[4:7], v[96:99], v[44:47]
	global_store_dword v[60:61], v62, off
	v_lshl_add_u64 v[78:79], v[64:65], 0, v[78:79]
	v_or_b32_e32 v62, 16, v32
	v_mfma_f32_16x16x32_f16 v[52:55], v[84:87], v[96:99], v[80:83]
	global_store_dword v[78:79], v63, off
	v_ashrrev_i32_e32 v63, 31, v62
	v_lshlrev_b64 v[62:63], 9, v[62:63]
	v_or_b32_e32 v80, 17, v32
	v_ashrrev_i32_e32 v81, 31, v80
	v_lshl_add_u64 v[62:63], v[64:65], 0, v[62:63]
	v_lshlrev_b64 v[80:81], 9, v[80:81]
	global_store_dword v[62:63], v44, off
	v_lshl_add_u64 v[80:81], v[64:65], 0, v[80:81]
	v_or_b32_e32 v44, 18, v32
	global_store_dword v[80:81], v45, off
	v_ashrrev_i32_e32 v45, 31, v44
	v_or_b32_e32 v82, 19, v32
	v_lshlrev_b64 v[44:45], 9, v[44:45]
	v_ashrrev_i32_e32 v83, 31, v82
	v_lshl_add_u64 v[44:45], v[64:65], 0, v[44:45]
	v_lshlrev_b64 v[82:83], 9, v[82:83]
	global_store_dword v[44:45], v46, off
	v_lshl_add_u64 v[82:83], v[64:65], 0, v[82:83]
	v_or_b32_e32 v46, 32, v32
	v_mfma_f32_16x16x32_f16 v[40:43], v[4:7], v[100:103], v[40:43]
	global_store_dword v[82:83], v47, off
	v_ashrrev_i32_e32 v47, 31, v46
	v_lshlrev_b64 v[46:47], 9, v[46:47]
	v_mfma_f32_16x16x32_f16 v[4:7], v[4:7], v[108:111], v[28:31]
	v_lshl_add_u64 v[46:47], v[64:65], 0, v[46:47]
	global_store_dword v[46:47], v36, off
	v_or_b32_e32 v36, 34, v32
	v_mfma_f32_16x16x32_f16 v[72:75], v[84:87], v[100:103], v[88:91]
	v_mfma_f32_16x16x32_f16 v[28:31], v[84:87], v[104:107], v[92:95]
	v_or_b32_e32 v84, 33, v32
	v_ashrrev_i32_e32 v85, 31, v84
	v_lshlrev_b64 v[84:85], 9, v[84:85]
	v_lshl_add_u64 v[84:85], v[64:65], 0, v[84:85]
	global_store_dword v[84:85], v37, off
	v_ashrrev_i32_e32 v37, 31, v36
	v_or_b32_e32 v86, 35, v32
	v_lshlrev_b64 v[36:37], 9, v[36:37]
	v_ashrrev_i32_e32 v87, 31, v86
	v_lshl_add_u64 v[36:37], v[64:65], 0, v[36:37]
	v_lshlrev_b64 v[86:87], 9, v[86:87]
	global_store_dword v[36:37], v38, off
	v_lshl_add_u64 v[86:87], v[64:65], 0, v[86:87]
	v_or_b32_e32 v38, 48, v32
	global_store_dword v[86:87], v39, off
	v_ashrrev_i32_e32 v39, 31, v38
	v_or_b32_e32 v88, 49, v32
	v_lshlrev_b64 v[38:39], 9, v[38:39]
	v_ashrrev_i32_e32 v89, 31, v88
	v_lshl_add_u64 v[38:39], v[64:65], 0, v[38:39]
	v_lshlrev_b64 v[88:89], 9, v[88:89]
	global_store_dword v[38:39], v52, off
	v_lshl_add_u64 v[88:89], v[64:65], 0, v[88:89]
	v_or_b32_e32 v52, 50, v32
	v_or_b32_e32 v32, 51, v32
	global_store_dword v[88:89], v53, off
	v_ashrrev_i32_e32 v53, 31, v52
	v_ashrrev_i32_e32 v33, 31, v32
	v_lshlrev_b64 v[52:53], 9, v[52:53]
	v_lshlrev_b64 v[32:33], 9, v[32:33]
	v_lshl_add_u64 v[52:53], v[64:65], 0, v[52:53]
	v_lshl_add_u64 v[32:33], v[64:65], 0, v[32:33]
	global_store_dword v[52:53], v54, off
	global_store_dword v[32:33], v55, off
	global_store_dword v[34:35], v56, off offset:64
	global_store_dword v[76:77], v57, off offset:64
	global_store_dword v[60:61], v58, off offset:64
	global_store_dword v[78:79], v59, off offset:64
	global_store_dword v[62:63], v40, off offset:64
	global_store_dword v[80:81], v41, off offset:64
	global_store_dword v[44:45], v42, off offset:64
	global_store_dword v[82:83], v43, off offset:64
	global_store_dword v[46:47], v48, off offset:64
	global_store_dword v[84:85], v49, off offset:64
	global_store_dword v[36:37], v50, off offset:64
	global_store_dword v[86:87], v51, off offset:64
	global_store_dword v[38:39], v72, off offset:64
	global_store_dword v[88:89], v73, off offset:64
	global_store_dword v[52:53], v74, off offset:64
	global_store_dword v[32:33], v75, off offset:64
	global_store_dword v[34:35], v16, off offset:128
	global_store_dword v[76:77], v17, off offset:128
	global_store_dword v[60:61], v18, off offset:128
	global_store_dword v[78:79], v19, off offset:128
	global_store_dword v[62:63], v20, off offset:128
	global_store_dword v[80:81], v21, off offset:128
	global_store_dword v[44:45], v22, off offset:128
	global_store_dword v[82:83], v23, off offset:128
	global_store_dword v[46:47], v24, off offset:128
	global_store_dword v[84:85], v25, off offset:128
	global_store_dword v[36:37], v26, off offset:128
	global_store_dword v[86:87], v27, off offset:128
	global_store_dword v[38:39], v28, off offset:128
	global_store_dword v[88:89], v29, off offset:128
	global_store_dword v[52:53], v30, off offset:128
	global_store_dword v[32:33], v31, off offset:128
	global_store_dword v[34:35], v0, off offset:192
	global_store_dword v[76:77], v1, off offset:192
	global_store_dword v[60:61], v2, off offset:192
	global_store_dword v[78:79], v3, off offset:192
	global_store_dword v[62:63], v4, off offset:192
	global_store_dword v[80:81], v5, off offset:192
	global_store_dword v[44:45], v6, off offset:192
	global_store_dword v[82:83], v7, off offset:192
	global_store_dword v[46:47], v8, off offset:192
	global_store_dword v[84:85], v9, off offset:192
	global_store_dword v[36:37], v10, off offset:192
	global_store_dword v[86:87], v11, off offset:192
	global_store_dword v[38:39], v12, off offset:192
	global_store_dword v[88:89], v13, off offset:192
	global_store_dword v[52:53], v14, off offset:192
	global_store_dword v[32:33], v15, off offset:192
	s_cbranch_scc0 .LBB0_249
	s_mov_b32 s39, s45
	s_movk_i32 s44, 0x3c60
	s_movk_i32 s45, 0x104

.LBB0_601:
	s_add_i32 s4, s13, 0xffff8000
	v_mov_b32_e32 v64, v182
	s_waitcnt vmcnt(0)
	s_waitcnt vmcnt(0) lgkmcnt(0)
	s_barrier
	s_and_b32 s14, s13, 0x8000
	s_and_b32 s15, s4, 0x8000
	v_or_b32_e32 v71, s15, v86
	v_lshrrev_b32_e32 v65, 4, v64
	v_ashrrev_i32_e32 v66, 3, v64
	v_add_u32_e32 v68, 0x100, v64
	v_lshl_add_u32 v67, v64, 4, s14
	v_add_u32_e32 v69, 0x200, v64
	v_add_u32_e32 v72, s0, v66
	v_bitop3_b32 v65, v65, 7, v64 bitop3:0x48
	v_ashrrev_i32_e32 v73, 3, v68
	s_add_u32 s8, s30, s2
	v_add_u32_e32 v70, 0x300, v64
	v_readfirstlane_b32 s16, v67
	v_lshl_add_u32 v74, v68, 4, s14
	v_ashrrev_i32_e32 v75, 3, v69
	v_add_u32_e32 v64, s12, v66
	v_add_u32_e32 v68, 0x4000, v67
	v_add3_u32 v91, v71, v87, v88
	v_add3_u32 v80, v71, v89, v88
	v_mad_i64_i32 v[66:67], s[4:5], v72, s63, 0
	v_lshlrev_b32_e32 v81, 4, v65
	v_add_u32_e32 v71, s0, v73
	s_addc_u32 s9, s31, s3
	v_ashrrev_i32_e32 v76, 3, v70
	v_lshl_add_u32 v77, v70, 4, s14
	v_readfirstlane_b32 s17, v74
	v_add_u32_e32 v78, s0, v75
	v_readfirstlane_b32 s20, v68
	v_add_u32_e32 v68, s12, v73
	v_add_u32_e32 v73, 0x4000, v74
	v_add_u32_e32 v70, s12, v75
	v_or_b32_e32 v66, v66, v81
	v_mad_i64_i32 v[74:75], s[4:5], v71, s63, 0
	v_add_u32_e32 v79, s0, v76
	v_readfirstlane_b32 s19, v77
	v_add_u32_e32 v72, s12, v76
	v_add_u32_e32 v83, 0x4000, v77
	v_mad_i64_i32 v[76:77], s[4:5], v78, s63, 0
	v_lshl_add_u64 v[66:67], s[8:9], 0, v[66:67]
	v_or_b32_e32 v74, v74, v81
	v_lshl_add_u32 v69, v69, 4, s14
	v_ashrrev_i32_e32 v65, 31, v64
	v_mad_i64_i32 v[78:79], s[4:5], v79, s63, 0
	v_or_b32_e32 v76, v76, v81
	v_lshl_add_u64 v[66:67], v[66:67], 0, s[80:81]
	v_lshl_add_u64 v[74:75], s[8:9], 0, v[74:75]
	s_mov_b32 m0, s16
	v_readfirstlane_b32 s18, v69
	v_add_u32_e32 v82, 0x4000, v69
	v_lshlrev_b64 v[64:65], 11, v[64:65]
	v_ashrrev_i32_e32 v69, 31, v68
	v_or_b32_e32 v78, v78, v81
	v_lshl_add_u64 v[76:77], s[8:9], 0, v[76:77]
	global_load_lds_dwordx4 v[66:67], off
	v_lshl_add_u64 v[66:67], v[74:75], 0, s[80:81]
	s_mov_b32 m0, s17
	v_ashrrev_i32_e32 v71, 31, v70
	v_or_b32_e32 v64, v64, v81
	v_lshlrev_b64 v[68:69], 11, v[68:69]
	v_lshl_add_u64 v[78:79], s[8:9], 0, v[78:79]
	v_lshl_add_u64 v[74:75], v[76:77], 0, s[80:81]
	global_load_lds_dwordx4 v[66:67], off
	s_mov_b32 m0, s18
	v_readfirstlane_b32 s4, v73
	v_ashrrev_i32_e32 v73, 31, v72
	v_lshlrev_b64 v[70:71], 11, v[70:71]
	v_lshl_add_u64 v[64:65], s[8:9], 0, v[64:65]
	v_or_b32_e32 v68, v68, v81
	v_lshl_add_u64 v[76:77], v[78:79], 0, s[80:81]
	global_load_lds_dwordx4 v[74:75], off
	s_mov_b32 m0, s19
	v_lshlrev_b64 v[72:73], 11, v[72:73]
	v_or_b32_e32 v70, v70, v81
	v_lshl_add_u64 v[64:65], v[64:65], 0, s[82:83]
	v_lshl_add_u64 v[68:69], s[8:9], 0, v[68:69]
	global_load_lds_dwordx4 v[76:77], off
	s_mov_b32 m0, s20
	v_readfirstlane_b32 s5, v82
	v_or_b32_e32 v72, v72, v81
	v_lshl_add_u64 v[70:71], s[8:9], 0, v[70:71]
	v_lshl_add_u64 v[66:67], v[68:69], 0, s[82:83]
	global_load_lds_dwordx4 v[64:65], off
	s_mov_b32 m0, s4
	v_readfirstlane_b32 s21, v83
	v_lshl_add_u64 v[72:73], s[8:9], 0, v[72:73]
	v_lshl_add_u64 v[68:69], v[70:71], 0, s[82:83]
	global_load_lds_dwordx4 v[66:67], off
	s_mov_b32 m0, s5
	v_lshl_add_u64 v[70:71], v[72:73], 0, s[82:83]
	global_load_lds_dwordx4 v[68:69], off
	s_mov_b32 m0, s21
	s_add_u32 s2, s2, 0x80
	global_load_lds_dwordx4 v[70:71], off
	ds_read_b128 v[64:67], v91
	ds_read_b128 v[68:71], v80 offset:16384
	ds_read_b128 v[72:75], v80 offset:18432
	ds_read_b128 v[76:79], v80 offset:20480
	ds_read_b128 v[80:83], v80 offset:22528
	s_waitcnt lgkmcnt(0)
	v_mfma_f32_16x16x32_f16 v[60:63], v[64:67], v[68:71], v[60:63]
	s_addc_u32 s3, s3, 0
	s_add_i32 s13, s13, 0x8000
	s_cmpk_eq_i32 s2, 0x780
	v_mfma_f32_16x16x32_f16 v[56:59], v[64:67], v[72:75], v[56:59]
	v_mfma_f32_16x16x32_f16 v[52:55], v[64:67], v[76:79], v[52:55]
	v_mfma_f32_16x16x32_f16 v[48:51], v[64:67], v[80:83], v[48:51]
	ds_read_b128 v[64:67], v91 offset:2048
	s_waitcnt lgkmcnt(0)
	v_mfma_f32_16x16x32_f16 v[44:47], v[64:67], v[68:71], v[44:47]
	v_mfma_f32_16x16x32_f16 v[40:43], v[64:67], v[72:75], v[40:43]
	v_mfma_f32_16x16x32_f16 v[36:39], v[64:67], v[76:79], v[36:39]
	v_mfma_f32_16x16x32_f16 v[32:35], v[64:67], v[80:83], v[32:35]
	ds_read_b128 v[64:67], v91 offset:4096
	s_waitcnt lgkmcnt(0)
	v_mfma_f32_16x16x32_f16 v[24:27], v[64:67], v[68:71], v[24:27]
	v_mfma_f32_16x16x32_f16 v[20:23], v[64:67], v[72:75], v[20:23]
	v_mfma_f32_16x16x32_f16 v[16:19], v[64:67], v[76:79], v[16:19]
	v_mfma_f32_16x16x32_f16 v[12:15], v[64:67], v[80:83], v[12:15]
	ds_read_b128 v[64:67], v91 offset:6144
	s_waitcnt lgkmcnt(0)
	v_mfma_f32_16x16x32_f16 v[8:11], v[64:67], v[68:71], v[8:11]
	v_or_b32_e32 v68, s15, v90
	v_add3_u32 v91, v68, v87, v88
	v_add3_u32 v92, v68, v89, v88
	ds_read_b128 v[68:71], v91
	v_mfma_f32_16x16x32_f16 v[4:7], v[64:67], v[72:75], v[4:7]
	ds_read_b128 v[72:75], v92 offset:18432
	v_mfma_f32_16x16x32_f16 v[0:3], v[64:67], v[76:79], v[0:3]
	ds_read_b128 v[76:79], v92 offset:20480
	v_mfma_f32_16x16x32_f16 v[28:31], v[64:67], v[80:83], v[28:31]
	ds_read_b128 v[64:67], v92 offset:16384
	ds_read_b128 v[80:83], v92 offset:22528
	s_waitcnt lgkmcnt(1)
	v_mfma_f32_16x16x32_f16 v[60:63], v[68:71], v[64:67], v[60:63]
	v_mfma_f32_16x16x32_f16 v[56:59], v[68:71], v[72:75], v[56:59]
	v_mfma_f32_16x16x32_f16 v[52:55], v[68:71], v[76:79], v[52:55]
	s_waitcnt lgkmcnt(0)
	v_mfma_f32_16x16x32_f16 v[48:51], v[68:71], v[80:83], v[48:51]
	ds_read_b128 v[68:71], v91 offset:2048
	s_waitcnt lgkmcnt(0)
	v_mfma_f32_16x16x32_f16 v[44:47], v[68:71], v[64:67], v[44:47]
	v_mfma_f32_16x16x32_f16 v[40:43], v[68:71], v[72:75], v[40:43]
	v_mfma_f32_16x16x32_f16 v[36:39], v[68:71], v[76:79], v[36:39]
	v_mfma_f32_16x16x32_f16 v[32:35], v[68:71], v[80:83], v[32:35]
	ds_read_b128 v[68:71], v91 offset:4096
	s_waitcnt lgkmcnt(0)
	v_mfma_f32_16x16x32_f16 v[24:27], v[68:71], v[64:67], v[24:27]
	v_mfma_f32_16x16x32_f16 v[20:23], v[68:71], v[72:75], v[20:23]
	v_mfma_f32_16x16x32_f16 v[16:19], v[68:71], v[76:79], v[16:19]
	v_mfma_f32_16x16x32_f16 v[12:15], v[68:71], v[80:83], v[12:15]
	ds_read_b128 v[68:71], v91 offset:6144
	s_waitcnt lgkmcnt(0)
	v_mfma_f32_16x16x32_f16 v[8:11], v[68:71], v[64:67], v[8:11]
	v_mfma_f32_16x16x32_f16 v[4:7], v[68:71], v[72:75], v[4:7]
	v_mfma_f32_16x16x32_f16 v[0:3], v[68:71], v[76:79], v[0:3]
	v_mfma_f32_16x16x32_f16 v[28:31], v[68:71], v[80:83], v[28:31]
	s_cbranch_scc0 .LBB0_601
	v_add_u32_e32 v80, s14, v86
	v_add3_u32 v76, v80, v87, v88
	v_add3_u32 v91, v80, v89, v88
	s_waitcnt vmcnt(0)
	s_barrier
	ds_read_b128 v[64:67], v76
	ds_read_b128 v[68:71], v76 offset:2048
	ds_read_b128 v[72:75], v76 offset:4096
	ds_read_b128 v[76:79], v76 offset:6144
	ds_read_b128 v[80:83], v91 offset:16384
	ds_read_b128 v[92:95], v91 offset:18432
	ds_read_b128 v[96:99], v91 offset:20480
	ds_read_b128 v[100:103], v91 offset:22528
	s_waitcnt lgkmcnt(3)
	v_mfma_f32_16x16x32_f16 v[60:63], v[64:67], v[80:83], v[60:63]
	s_ashr_i32 s2, s0, 31
	s_lshr_b32 s2, s2, 19
	s_add_i32 s2, s0, s2
	s_waitcnt lgkmcnt(2)
	v_mfma_f32_16x16x32_f16 v[56:59], v[64:67], v[92:95], v[56:59]
	s_ashr_i32 s2, s2, 13
	s_add_i32 s2, s2, s10
	s_mul_hi_i32 s3, s2, 0x9000
	s_waitcnt lgkmcnt(1)
	v_mfma_f32_16x16x32_f16 v[52:55], v[64:67], v[96:99], v[52:55]
	s_mul_i32 s2, s2, 0x9000
	s_add_u32 s2, s50, s2
	s_addc_u32 s3, s51, s3
	s_waitcnt lgkmcnt(0)
	v_mfma_f32_16x16x32_f16 v[48:51], v[64:67], v[100:103], v[48:51]
	s_add_i32 s11, s11, s59
	s_cmpk_gt_i32 s11, 0x7ff
	v_mfma_f32_16x16x32_f16 v[64:67], v[68:71], v[80:83], v[44:47]
	v_mfma_f32_16x16x32_f16 v[40:43], v[68:71], v[92:95], v[40:43]
	v_mfma_f32_16x16x32_f16 v[36:39], v[68:71], v[96:99], v[36:39]
	v_mfma_f32_16x16x32_f16 v[32:35], v[68:71], v[100:103], v[32:35]
	v_mfma_f32_16x16x32_f16 v[68:71], v[72:75], v[80:83], v[24:27]
	v_mfma_f32_16x16x32_f16 v[20:23], v[72:75], v[92:95], v[20:23]
	v_mfma_f32_16x16x32_f16 v[16:19], v[72:75], v[96:99], v[16:19]
	v_mfma_f32_16x16x32_f16 v[72:75], v[72:75], v[100:103], v[12:15]
	s_nop 2
	v_add_u32_e32 v12, s14, v90
	v_add3_u32 v13, v12, v87, v88
	v_add3_u32 v12, v12, v89, v88
	v_mfma_f32_16x16x32_f16 v[80:83], v[76:79], v[80:83], v[8:11]
	v_mfma_f32_16x16x32_f16 v[92:95], v[76:79], v[92:95], v[4:7]
	v_mfma_f32_16x16x32_f16 v[0:3], v[76:79], v[96:99], v[0:3]
	v_mfma_f32_16x16x32_f16 v[76:79], v[76:79], v[100:103], v[28:31]
	s_nop 0
	ds_read_b128 v[4:7], v13
	ds_read_b128 v[8:11], v13 offset:2048
	ds_read_b128 v[96:99], v13 offset:4096
	ds_read_b128 v[100:103], v13 offset:6144
	ds_read_b128 v[104:107], v12 offset:16384
	ds_read_b128 v[108:111], v12 offset:18432
	ds_read_b128 v[116:119], v12 offset:20480
	ds_read_b128 v[120:123], v12 offset:22528
	s_waitcnt lgkmcnt(1)
	v_mfma_f32_16x16x32_f16 v[28:31], v[4:7], v[116:119], v[52:55]
	v_mfma_f32_16x16x32_f16 v[52:55], v[8:11], v[104:107], v[64:67]
	s_nop 2
	v_or_b32_e32 v64, s12, v84
	v_ashrrev_i32_e32 v65, 31, v64
	v_mfma_f32_16x16x32_f16 v[60:63], v[4:7], v[104:107], v[60:63]
	v_mfma_f32_16x16x32_f16 v[44:47], v[4:7], v[108:111], v[56:59]
	s_waitcnt lgkmcnt(0)
	v_mfma_f32_16x16x32_f16 v[12:15], v[4:7], v[120:123], v[48:51]
	v_mfma_f32_16x16x32_f16 v[24:27], v[8:11], v[116:119], v[36:39]
	v_mfma_f32_16x16x32_f16 v[56:59], v[96:99], v[104:107], v[68:71]
	v_mfma_f32_16x16x32_f16 v[36:39], v[96:99], v[108:111], v[20:23]
	v_mfma_f32_16x16x32_f16 v[20:23], v[96:99], v[116:119], v[16:19]
	v_mfma_f32_16x16x32_f16 v[4:7], v[96:99], v[120:123], v[72:75]
	v_lshlrev_b64 v[96:97], 2, v[64:65]
	v_lshl_add_u64 v[64:65], s[2:3], 0, v[96:97]
	v_mfma_f32_16x16x32_f16 v[40:43], v[8:11], v[108:111], v[40:43]
	v_mfma_f32_16x16x32_f16 v[8:11], v[8:11], v[120:123], v[32:35]
	v_mfma_f32_16x16x32_f16 v[32:35], v[100:103], v[108:111], v[92:95]
	s_nop 2
	v_add_u32_e32 v92, s0, v85
	s_movk_i32 s0, 0x5000
	v_mfma_f32_16x16x32_f16 v[48:51], v[100:103], v[104:107], v[80:83]
	v_ashrrev_i32_e32 v93, 31, v92
	v_or_b32_e32 v94, 48, v92
	v_ashrrev_i32_e32 v95, 31, v94
	v_add_co_u32_e32 v80, vcc, s0, v64
	v_mfma_f32_16x16x32_f16 v[16:19], v[100:103], v[116:119], v[0:3]
	s_nop 0
	v_addc_co_u32_e32 v81, vcc, 0, v65, vcc
	global_load_dword v64, v[80:81], off
	v_mfma_f32_16x16x32_f16 v[0:3], v[100:103], v[120:123], v[76:79]
	s_waitcnt vmcnt(0)
	v_add_f32_e32 v91, 1.0, v64
	v_lshlrev_b64 v[64:65], 12, v[92:93]
	v_lshl_add_u64 v[64:65], s[28:29], 0, v[64:65]
	v_lshl_add_u64 v[82:83], v[64:65], 0, v[96:97]
	global_load_dword v64, v[82:83], off
	v_mul_f32_e32 v60, v60, v91
	s_waitcnt vmcnt(0)
	v_fmac_f32_e32 v60, 0x3fb504f3, v64
	v_or_b32_e32 v64, 1, v92
	v_ashrrev_i32_e32 v65, 31, v64
	v_lshlrev_b64 v[64:65], 12, v[64:65]
	v_lshl_add_u64 v[64:65], s[28:29], 0, v[64:65]
	v_lshl_add_u64 v[76:77], v[64:65], 0, v[96:97]
	global_store_dword v[82:83], v60, off
	global_load_dword v60, v[76:77], off
	s_waitcnt vmcnt(0)
	v_mul_f32_e32 v60, 0x3fb504f3, v60
	v_fmac_f32_e32 v60, v61, v91
	global_store_dword v[76:77], v60, off
	v_or_b32_e32 v60, 2, v92
	v_ashrrev_i32_e32 v61, 31, v60
	v_lshlrev_b64 v[60:61], 12, v[60:61]
	v_lshl_add_u64 v[60:61], s[28:29], 0, v[60:61]
	v_lshl_add_u64 v[78:79], v[60:61], 0, v[96:97]
	global_load_dword v60, v[78:79], off
	s_waitcnt vmcnt(0)
	v_mul_f32_e32 v60, 0x3fb504f3, v60
	v_fmac_f32_e32 v60, v62, v91
	global_store_dword v[78:79], v60, off
	v_or_b32_e32 v60, 3, v92
	v_ashrrev_i32_e32 v61, 31, v60
	v_lshlrev_b64 v[60:61], 12, v[60:61]
	v_lshl_add_u64 v[60:61], s[28:29], 0, v[60:61]
	v_lshl_add_u64 v[72:73], v[60:61], 0, v[96:97]
	global_load_dword v60, v[72:73], off
	s_waitcnt vmcnt(0)
	v_mul_f32_e32 v60, 0x3fb504f3, v60
	v_fmac_f32_e32 v60, v63, v91
	global_store_dword v[72:73], v60, off
	v_or_b32_e32 v60, 16, v92
	v_ashrrev_i32_e32 v61, 31, v60
	v_lshlrev_b64 v[60:61], 12, v[60:61]
	v_lshl_add_u64 v[60:61], s[28:29], 0, v[60:61]
	v_lshl_add_u64 v[74:75], v[60:61], 0, v[96:97]
	global_load_dword v60, v[74:75], off
	s_waitcnt vmcnt(0)
	v_mul_f32_e32 v60, 0x3fb504f3, v60
	v_fmac_f32_e32 v60, v52, v91
	global_store_dword v[74:75], v60, off
	v_or_b32_e32 v60, 17, v92
	v_ashrrev_i32_e32 v61, 31, v60
	v_lshlrev_b64 v[60:61], 12, v[60:61]
	v_lshl_add_u64 v[60:61], s[28:29], 0, v[60:61]
	v_lshl_add_u64 v[68:69], v[60:61], 0, v[96:97]
	global_load_dword v52, v[68:69], off
	s_waitcnt vmcnt(0)
	v_mul_f32_e32 v52, 0x3fb504f3, v52
	v_fmac_f32_e32 v52, v53, v91
	global_store_dword v[68:69], v52, off
	v_or_b32_e32 v52, 18, v92
	v_ashrrev_i32_e32 v53, 31, v52
	v_lshlrev_b64 v[52:53], 12, v[52:53]
	v_lshl_add_u64 v[52:53], s[28:29], 0, v[52:53]
	v_lshl_add_u64 v[70:71], v[52:53], 0, v[96:97]
	global_load_dword v52, v[70:71], off
	s_waitcnt vmcnt(0)
	v_mul_f32_e32 v52, 0x3fb504f3, v52
	v_fmac_f32_e32 v52, v54, v91
	global_store_dword v[70:71], v52, off
	v_or_b32_e32 v52, 19, v92
	v_ashrrev_i32_e32 v53, 31, v52
	v_lshlrev_b64 v[52:53], 12, v[52:53]
	v_lshl_add_u64 v[52:53], s[28:29], 0, v[52:53]
	v_lshl_add_u64 v[64:65], v[52:53], 0, v[96:97]
	global_load_dword v52, v[64:65], off
	s_waitcnt vmcnt(0)
	v_mul_f32_e32 v52, 0x3fb504f3, v52
	v_fmac_f32_e32 v52, v55, v91
	global_store_dword v[64:65], v52, off
	v_or_b32_e32 v52, 32, v92
	v_ashrrev_i32_e32 v53, 31, v52
	v_lshlrev_b64 v[52:53], 12, v[52:53]
	v_lshl_add_u64 v[52:53], s[28:29], 0, v[52:53]
	v_lshl_add_u64 v[66:67], v[52:53], 0, v[96:97]
	global_load_dword v52, v[66:67], off
	s_waitcnt vmcnt(0)
	v_mul_f32_e32 v52, 0x3fb504f3, v52
	v_fmac_f32_e32 v52, v56, v91
	global_store_dword v[66:67], v52, off
	v_or_b32_e32 v52, 33, v92
	v_ashrrev_i32_e32 v53, 31, v52
	v_lshlrev_b64 v[52:53], 12, v[52:53]
	v_lshl_add_u64 v[52:53], s[28:29], 0, v[52:53]
	v_lshl_add_u64 v[60:61], v[52:53], 0, v[96:97]
	global_load_dword v52, v[60:61], off
	s_waitcnt vmcnt(0)
	v_mul_f32_e32 v52, 0x3fb504f3, v52
	v_fmac_f32_e32 v52, v57, v91
	global_store_dword v[60:61], v52, off
	v_or_b32_e32 v52, 34, v92
	v_ashrrev_i32_e32 v53, 31, v52
	v_lshlrev_b64 v[52:53], 12, v[52:53]
	v_lshl_add_u64 v[52:53], s[28:29], 0, v[52:53]
	v_lshl_add_u64 v[62:63], v[52:53], 0, v[96:97]
	global_load_dword v52, v[62:63], off
	s_waitcnt vmcnt(0)
	v_mul_f32_e32 v52, 0x3fb504f3, v52
	v_fmac_f32_e32 v52, v58, v91
	global_store_dword v[62:63], v52, off
	v_or_b32_e32 v52, 35, v92
	v_ashrrev_i32_e32 v53, 31, v52
	v_lshlrev_b64 v[52:53], 12, v[52:53]
	v_lshl_add_u64 v[52:53], s[28:29], 0, v[52:53]
	v_lshl_add_u64 v[56:57], v[52:53], 0, v[96:97]
	global_load_dword v52, v[56:57], off
	s_waitcnt vmcnt(0)
	v_mul_f32_e32 v52, 0x3fb504f3, v52
	v_fmac_f32_e32 v52, v59, v91
	global_store_dword v[56:57], v52, off
	v_lshlrev_b64 v[52:53], 12, v[94:95]
	v_lshl_add_u64 v[52:53], s[28:29], 0, v[52:53]
	v_lshl_add_u64 v[58:59], v[52:53], 0, v[96:97]
	global_load_dword v52, v[58:59], off
	s_waitcnt vmcnt(0)
	v_mul_f32_e32 v52, 0x3fb504f3, v52
	v_fmac_f32_e32 v52, v48, v91
	global_store_dword v[58:59], v52, off
	v_or_b32_e32 v52, 49, v92
	v_ashrrev_i32_e32 v53, 31, v52
	v_lshlrev_b64 v[52:53], 12, v[52:53]
	v_lshl_add_u64 v[52:53], s[28:29], 0, v[52:53]
	v_lshl_add_u64 v[52:53], v[52:53], 0, v[96:97]
	global_load_dword v48, v[52:53], off
	s_waitcnt vmcnt(0)
	v_mul_f32_e32 v48, 0x3fb504f3, v48
	v_fmac_f32_e32 v48, v49, v91
	global_store_dword v[52:53], v48, off
	v_or_b32_e32 v48, 50, v92
	v_ashrrev_i32_e32 v49, 31, v48
	v_lshlrev_b64 v[48:49], 12, v[48:49]
	v_lshl_add_u64 v[48:49], s[28:29], 0, v[48:49]
	v_lshl_add_u64 v[54:55], v[48:49], 0, v[96:97]
	global_load_dword v48, v[54:55], off
	s_waitcnt vmcnt(0)
	v_mul_f32_e32 v48, 0x3fb504f3, v48
	v_fmac_f32_e32 v48, v50, v91
	global_store_dword v[54:55], v48, off
	v_or_b32_e32 v48, 51, v92
	v_ashrrev_i32_e32 v49, 31, v48
	v_lshlrev_b64 v[48:49], 12, v[48:49]
	v_lshl_add_u64 v[48:49], s[28:29], 0, v[48:49]
	v_lshl_add_u64 v[48:49], v[48:49], 0, v[96:97]
	global_load_dword v50, v[48:49], off
	s_waitcnt vmcnt(0)
	v_mul_f32_e32 v50, 0x3fb504f3, v50
	v_fmac_f32_e32 v50, v51, v91
	global_store_dword v[48:49], v50, off
	global_load_dword v50, v[80:81], off offset:64
	s_waitcnt vmcnt(0)
	v_add_f32_e32 v50, 1.0, v50
	global_load_dword v51, v[82:83], off offset:64
	v_mul_f32_e32 v44, v44, v50
	s_waitcnt vmcnt(0)
	v_fmac_f32_e32 v44, 0x3fb504f3, v51
	global_store_dword v[82:83], v44, off offset:64
	global_load_dword v44, v[76:77], off offset:64
	s_waitcnt vmcnt(0)
	v_mul_f32_e32 v44, 0x3fb504f3, v44
	v_fmac_f32_e32 v44, v45, v50
	global_store_dword v[76:77], v44, off offset:64
	global_load_dword v44, v[78:79], off offset:64
	s_waitcnt vmcnt(0)
	v_mul_f32_e32 v44, 0x3fb504f3, v44
	v_fmac_f32_e32 v44, v46, v50
	global_store_dword v[78:79], v44, off offset:64
	global_load_dword v44, v[72:73], off offset:64
	s_waitcnt vmcnt(0)
	v_mul_f32_e32 v44, 0x3fb504f3, v44
	v_fmac_f32_e32 v44, v47, v50
	global_store_dword v[72:73], v44, off offset:64
	global_load_dword v44, v[74:75], off offset:64
	s_waitcnt vmcnt(0)
	v_mul_f32_e32 v44, 0x3fb504f3, v44
	v_fmac_f32_e32 v44, v40, v50
	global_load_dword v40, v[68:69], off offset:64
	s_waitcnt vmcnt(0)
	v_mul_f32_e32 v40, 0x3fb504f3, v40
	v_fmac_f32_e32 v40, v41, v50
	global_store_dword v[68:69], v40, off offset:64
	global_load_dword v40, v[70:71], off offset:64
	s_waitcnt vmcnt(0)
	v_mul_f32_e32 v40, 0x3fb504f3, v40
	v_fmac_f32_e32 v40, v42, v50
	global_store_dword v[70:71], v40, off offset:64
	global_load_dword v40, v[64:65], off offset:64
	s_waitcnt vmcnt(0)
	v_mul_f32_e32 v40, 0x3fb504f3, v40
	v_fmac_f32_e32 v40, v43, v50
	global_store_dword v[64:65], v40, off offset:64
	global_load_dword v40, v[66:67], off offset:64
	s_waitcnt vmcnt(0)
	v_mul_f32_e32 v40, 0x3fb504f3, v40
	v_fmac_f32_e32 v40, v36, v50
	global_load_dword v36, v[60:61], off offset:64
	s_waitcnt vmcnt(0)
	v_mul_f32_e32 v36, 0x3fb504f3, v36
	v_fmac_f32_e32 v36, v37, v50
	global_store_dword v[60:61], v36, off offset:64
	global_load_dword v36, v[62:63], off offset:64
	s_waitcnt vmcnt(0)
	v_mul_f32_e32 v36, 0x3fb504f3, v36
	v_fmac_f32_e32 v36, v38, v50
	global_store_dword v[62:63], v36, off offset:64
	global_load_dword v36, v[56:57], off offset:64
	s_waitcnt vmcnt(0)
	v_mul_f32_e32 v36, 0x3fb504f3, v36
	v_fmac_f32_e32 v36, v39, v50
	global_store_dword v[56:57], v36, off offset:64
	global_load_dword v36, v[58:59], off offset:64
	s_waitcnt vmcnt(0)
	v_mul_f32_e32 v36, 0x3fb504f3, v36
	v_fmac_f32_e32 v36, v32, v50
	global_load_dword v32, v[52:53], off offset:64
	s_waitcnt vmcnt(0)
	v_mul_f32_e32 v32, 0x3fb504f3, v32
	v_fmac_f32_e32 v32, v33, v50
	global_store_dword v[52:53], v32, off offset:64
	global_load_dword v32, v[54:55], off offset:64
	s_waitcnt vmcnt(0)
	v_mul_f32_e32 v32, 0x3fb504f3, v32
	v_fmac_f32_e32 v32, v34, v50
	global_store_dword v[54:55], v32, off offset:64
	global_load_dword v32, v[48:49], off offset:64
	s_nop 0
	global_load_dword v33, v[82:83], off offset:128
	s_waitcnt vmcnt(1)
	v_mul_f32_e32 v32, 0x3fb504f3, v32
	v_fmac_f32_e32 v32, v35, v50
	global_store_dword v[74:75], v44, off offset:64
	global_store_dword v[66:67], v40, off offset:64
	global_store_dword v[58:59], v36, off offset:64
	global_store_dword v[48:49], v32, off offset:64
	global_load_dword v32, v[80:81], off offset:128
	s_waitcnt vmcnt(0)
	v_add_f32_e32 v32, 1.0, v32
	v_mul_f32_e32 v28, v28, v32
	v_fmac_f32_e32 v28, 0x3fb504f3, v33
	global_store_dword v[82:83], v28, off offset:128
	global_load_dword v28, v[76:77], off offset:128
	s_waitcnt vmcnt(0)
	v_mul_f32_e32 v28, 0x3fb504f3, v28
	v_fmac_f32_e32 v28, v29, v32
	global_store_dword v[76:77], v28, off offset:128
	global_load_dword v28, v[78:79], off offset:128
	s_waitcnt vmcnt(0)
	v_mul_f32_e32 v28, 0x3fb504f3, v28
	v_fmac_f32_e32 v28, v30, v32
	global_store_dword v[78:79], v28, off offset:128
	global_load_dword v28, v[72:73], off offset:128
	s_waitcnt vmcnt(0)
	v_mul_f32_e32 v28, 0x3fb504f3, v28
	v_fmac_f32_e32 v28, v31, v32
	global_store_dword v[72:73], v28, off offset:128
	global_load_dword v28, v[74:75], off offset:128
	s_waitcnt vmcnt(0)
	v_mul_f32_e32 v28, 0x3fb504f3, v28
	v_fmac_f32_e32 v28, v24, v32
	global_load_dword v24, v[68:69], off offset:128
	s_waitcnt vmcnt(0)
	v_mul_f32_e32 v24, 0x3fb504f3, v24
	v_fmac_f32_e32 v24, v25, v32
	global_store_dword v[68:69], v24, off offset:128
	global_load_dword v24, v[70:71], off offset:128
	s_waitcnt vmcnt(0)
	v_mul_f32_e32 v24, 0x3fb504f3, v24
	v_fmac_f32_e32 v24, v26, v32
	global_store_dword v[70:71], v24, off offset:128
	global_load_dword v24, v[64:65], off offset:128
	s_waitcnt vmcnt(0)
	v_mul_f32_e32 v24, 0x3fb504f3, v24
	v_fmac_f32_e32 v24, v27, v32
	global_store_dword v[64:65], v24, off offset:128
	global_load_dword v24, v[66:67], off offset:128
	s_waitcnt vmcnt(0)
	v_mul_f32_e32 v24, 0x3fb504f3, v24
	v_fmac_f32_e32 v24, v20, v32
	global_load_dword v20, v[60:61], off offset:128
	s_waitcnt vmcnt(0)
	v_mul_f32_e32 v20, 0x3fb504f3, v20
	v_fmac_f32_e32 v20, v21, v32
	global_store_dword v[60:61], v20, off offset:128
	global_load_dword v20, v[62:63], off offset:128
	s_waitcnt vmcnt(0)
	v_mul_f32_e32 v20, 0x3fb504f3, v20
	v_fmac_f32_e32 v20, v22, v32
	global_store_dword v[62:63], v20, off offset:128
	global_load_dword v20, v[56:57], off offset:128
	s_waitcnt vmcnt(0)
	v_mul_f32_e32 v20, 0x3fb504f3, v20
	v_fmac_f32_e32 v20, v23, v32
	global_store_dword v[56:57], v20, off offset:128
	global_load_dword v20, v[58:59], off offset:128
	s_waitcnt vmcnt(0)
	v_mul_f32_e32 v20, 0x3fb504f3, v20
	v_fmac_f32_e32 v20, v16, v32
	global_load_dword v16, v[52:53], off offset:128
	s_waitcnt vmcnt(0)
	v_mul_f32_e32 v16, 0x3fb504f3, v16
	v_fmac_f32_e32 v16, v17, v32
	global_store_dword v[52:53], v16, off offset:128
	global_load_dword v16, v[54:55], off offset:128
	s_waitcnt vmcnt(0)
	v_mul_f32_e32 v16, 0x3fb504f3, v16
	v_fmac_f32_e32 v16, v18, v32
	global_store_dword v[54:55], v16, off offset:128
	global_load_dword v16, v[48:49], off offset:128
	s_nop 0
	global_load_dword v17, v[82:83], off offset:192
	s_waitcnt vmcnt(1)
	v_mul_f32_e32 v16, 0x3fb504f3, v16
	v_fmac_f32_e32 v16, v19, v32
	global_store_dword v[74:75], v28, off offset:128
	global_store_dword v[66:67], v24, off offset:128
	global_store_dword v[58:59], v20, off offset:128
	global_store_dword v[48:49], v16, off offset:128
	global_load_dword v16, v[80:81], off offset:192
	s_waitcnt vmcnt(0)
	v_add_f32_e32 v16, 1.0, v16
	v_mul_f32_e32 v12, v12, v16
	v_fmac_f32_e32 v12, 0x3fb504f3, v17
	global_store_dword v[82:83], v12, off offset:192
	global_load_dword v12, v[76:77], off offset:192
	s_waitcnt vmcnt(0)
	v_mul_f32_e32 v12, 0x3fb504f3, v12
	v_fmac_f32_e32 v12, v13, v16
	global_store_dword v[76:77], v12, off offset:192
	global_load_dword v12, v[78:79], off offset:192
	s_waitcnt vmcnt(0)
	v_mul_f32_e32 v12, 0x3fb504f3, v12
	v_fmac_f32_e32 v12, v14, v16
	global_store_dword v[78:79], v12, off offset:192
	global_load_dword v12, v[72:73], off offset:192
	s_waitcnt vmcnt(0)
	v_mul_f32_e32 v12, 0x3fb504f3, v12
	v_fmac_f32_e32 v12, v15, v16
	global_store_dword v[72:73], v12, off offset:192
	global_load_dword v12, v[74:75], off offset:192
	s_waitcnt vmcnt(0)
	v_mul_f32_e32 v12, 0x3fb504f3, v12
	v_fmac_f32_e32 v12, v8, v16
	global_load_dword v8, v[68:69], off offset:192
	s_waitcnt vmcnt(0)
	v_mul_f32_e32 v8, 0x3fb504f3, v8
	v_fmac_f32_e32 v8, v9, v16
	global_store_dword v[68:69], v8, off offset:192
	global_load_dword v8, v[70:71], off offset:192
	s_waitcnt vmcnt(0)
	v_mul_f32_e32 v8, 0x3fb504f3, v8
	v_fmac_f32_e32 v8, v10, v16
	global_store_dword v[70:71], v8, off offset:192
	global_load_dword v8, v[64:65], off offset:192
	s_waitcnt vmcnt(0)
	v_mul_f32_e32 v8, 0x3fb504f3, v8
	v_fmac_f32_e32 v8, v11, v16
	global_store_dword v[64:65], v8, off offset:192
	global_load_dword v8, v[66:67], off offset:192
	s_waitcnt vmcnt(0)
	v_mul_f32_e32 v8, 0x3fb504f3, v8
	v_fmac_f32_e32 v8, v4, v16
	global_load_dword v4, v[60:61], off offset:192
	s_waitcnt vmcnt(0)
	v_mul_f32_e32 v4, 0x3fb504f3, v4
	v_fmac_f32_e32 v4, v5, v16
	global_store_dword v[60:61], v4, off offset:192
	global_load_dword v4, v[62:63], off offset:192
	s_waitcnt vmcnt(0)
	v_mul_f32_e32 v4, 0x3fb504f3, v4
	v_fmac_f32_e32 v4, v6, v16
	global_store_dword v[62:63], v4, off offset:192
	global_load_dword v4, v[56:57], off offset:192
	s_waitcnt vmcnt(0)
	v_mul_f32_e32 v4, 0x3fb504f3, v4
	v_fmac_f32_e32 v4, v7, v16
	global_store_dword v[56:57], v4, off offset:192
	global_load_dword v4, v[58:59], off offset:192
	s_waitcnt vmcnt(0)
	v_mul_f32_e32 v4, 0x3fb504f3, v4
	v_fmac_f32_e32 v4, v0, v16
	global_load_dword v0, v[52:53], off offset:192
	s_waitcnt vmcnt(0)
	v_mul_f32_e32 v0, 0x3fb504f3, v0
	v_fmac_f32_e32 v0, v1, v16
	global_store_dword v[52:53], v0, off offset:192
	global_load_dword v0, v[54:55], off offset:192
	s_waitcnt vmcnt(0)
	v_mul_f32_e32 v0, 0x3fb504f3, v0
	v_fmac_f32_e32 v0, v2, v16
	global_store_dword v[54:55], v0, off offset:192
	global_load_dword v0, v[48:49], off offset:192
	s_waitcnt vmcnt(0)
	v_mul_f32_e32 v0, 0x3fb504f3, v0
	v_fmac_f32_e32 v0, v3, v16
	global_store_dword v[74:75], v12, off offset:192
	global_store_dword v[66:67], v8, off offset:192
	global_store_dword v[58:59], v4, off offset:192
	global_store_dword v[48:49], v0, off offset:192
	s_cbranch_scc0 .LBB0_600

.LBB0_635:
	v_mov_b32_e32 v66, v182
	s_waitcnt vmcnt(0)
	s_waitcnt vmcnt(0) lgkmcnt(0)
	s_barrier
	s_add_i32 s4, s13, 0xffff8000
	v_ashrrev_i32_e32 v68, 3, v66
	v_lshrrev_b32_e32 v67, 4, v66
	v_add_u32_e32 v64, s12, v68
	s_and_b32 s14, s4, 0x8000
	s_and_b32 s4, s13, 0x8000
	v_ashrrev_i32_e32 v65, 31, v64
	v_bitop3_b32 v67, v67, 7, v66 bitop3:0x48
	v_lshlrev_b64 v[64:65], 11, v[64:65]
	v_lshlrev_b32_e32 v67, 4, v67
	s_add_u32 s8, s30, s2
	v_or_b32_e32 v64, v64, v67
	s_addc_u32 s9, s31, s3
	v_lshl_add_u32 v69, v66, 4, s4
	v_lshl_add_u64 v[64:65], s[8:9], 0, v[64:65]
	v_readfirstlane_b32 s5, v69
	v_add_u32_e32 v70, 0x100, v66
	v_lshl_add_u64 v[64:65], v[64:65], 0, s[90:91]
	s_mov_b32 m0, s5
	v_ashrrev_i32_e32 v71, 3, v70
	global_load_lds_dwordx4 v[64:65], off
	v_add_u32_e32 v64, s12, v71
	v_ashrrev_i32_e32 v65, 31, v64
	v_lshlrev_b64 v[64:65], 11, v[64:65]
	v_or_b32_e32 v64, v64, v67
	v_lshl_add_u32 v70, v70, 4, s4
	v_lshl_add_u64 v[64:65], s[8:9], 0, v[64:65]
	v_readfirstlane_b32 s5, v70
	v_add_u32_e32 v72, 0x200, v66
	v_lshl_add_u64 v[64:65], v[64:65], 0, s[90:91]
	s_mov_b32 m0, s5
	v_ashrrev_i32_e32 v73, 3, v72
	global_load_lds_dwordx4 v[64:65], off
	v_add_u32_e32 v64, s12, v73
	v_ashrrev_i32_e32 v65, 31, v64
	v_lshlrev_b64 v[64:65], 11, v[64:65]
	v_or_b32_e32 v64, v64, v67
	v_lshl_add_u32 v72, v72, 4, s4
	v_lshl_add_u64 v[64:65], s[8:9], 0, v[64:65]
	v_readfirstlane_b32 s5, v72
	v_add_u32_e32 v66, 0x300, v66
	v_lshl_add_u64 v[64:65], v[64:65], 0, s[90:91]
	s_mov_b32 m0, s5
	v_ashrrev_i32_e32 v74, 3, v66
	global_load_lds_dwordx4 v[64:65], off
	v_add_u32_e32 v64, s12, v74
	v_ashrrev_i32_e32 v65, 31, v64
	v_lshlrev_b64 v[64:65], 11, v[64:65]
	v_or_b32_e32 v64, v64, v67
	v_lshl_add_u32 v66, v66, 4, s4
	v_lshl_add_u64 v[64:65], s[8:9], 0, v[64:65]
	v_readfirstlane_b32 s4, v66
	v_lshl_add_u64 v[64:65], v[64:65], 0, s[90:91]
	s_mov_b32 m0, s4
	v_add_u32_e32 v66, 0x4000, v66
	global_load_lds_dwordx4 v[64:65], off
	v_add_u32_e32 v64, s0, v68
	v_ashrrev_i32_e32 v65, 31, v64
	v_lshlrev_b64 v[64:65], 11, v[64:65]
	v_or_b32_e32 v64, v64, v67
	v_add_u32_e32 v68, 0x4000, v69
	v_lshl_add_u64 v[64:65], s[8:9], 0, v[64:65]
	v_readfirstlane_b32 s4, v68
	v_lshl_add_u64 v[64:65], v[64:65], 0, s[84:85]
	s_mov_b32 m0, s4
	v_add_u32_e32 v68, 0x4000, v70
	global_load_lds_dwordx4 v[64:65], off
	v_add_u32_e32 v64, s0, v71
	v_ashrrev_i32_e32 v65, 31, v64
	v_lshlrev_b64 v[64:65], 11, v[64:65]
	v_or_b32_e32 v64, v64, v67
	v_lshl_add_u64 v[64:65], s[8:9], 0, v[64:65]
	v_readfirstlane_b32 s4, v68
	v_lshl_add_u64 v[64:65], v[64:65], 0, s[84:85]
	s_mov_b32 m0, s4
	v_add_u32_e32 v68, 0x4000, v72
	global_load_lds_dwordx4 v[64:65], off
	v_add_u32_e32 v64, s0, v73
	v_ashrrev_i32_e32 v65, 31, v64
	v_lshlrev_b64 v[64:65], 11, v[64:65]
	v_or_b32_e32 v64, v64, v67
	v_lshl_add_u64 v[64:65], s[8:9], 0, v[64:65]
	v_readfirstlane_b32 s4, v68
	v_lshl_add_u64 v[64:65], v[64:65], 0, s[84:85]
	s_mov_b32 m0, s4
	v_readfirstlane_b32 s4, v66
	global_load_lds_dwordx4 v[64:65], off
	v_add_u32_e32 v64, s0, v74
	v_ashrrev_i32_e32 v65, 31, v64
	v_lshlrev_b64 v[64:65], 11, v[64:65]
	v_or_b32_e32 v64, v64, v67
	v_lshl_add_u64 v[64:65], s[8:9], 0, v[64:65]
	v_lshl_add_u64 v[64:65], v[64:65], 0, s[84:85]
	s_mov_b32 m0, s4
	v_or_b32_e32 v91, s14, v84
	global_load_lds_dwordx4 v[64:65], off
	v_add3_u32 v64, v91, v85, v83
	v_add3_u32 v91, v91, v82, v83
	ds_read_b128 v[76:79], v64
	ds_read_b128 v[72:75], v64 offset:2048
	ds_read_b128 v[68:71], v64 offset:4096
	ds_read_b128 v[64:67], v64 offset:6144
	ds_read_b128 v[92:95], v91 offset:16384
	ds_read_b128 v[96:99], v91 offset:18432
	ds_read_b128 v[100:103], v91 offset:20480
	ds_read_b128 v[104:107], v91 offset:22528
	v_or_b32_e32 v91, s14, v81
	s_waitcnt lgkmcnt(0)
	v_mfma_f32_16x16x32_f16 v[60:63], v[76:79], v[92:95], v[60:63]
	s_add_u32 s2, s2, 0x80
	s_addc_u32 s3, s3, 0
	s_add_i32 s13, s13, 0x8000
	v_mfma_f32_16x16x32_f16 v[56:59], v[76:79], v[96:99], v[56:59]
	s_cmpk_eq_i32 s2, 0x780
	v_mfma_f32_16x16x32_f16 v[52:55], v[76:79], v[100:103], v[52:55]
	v_mfma_f32_16x16x32_f16 v[48:51], v[76:79], v[104:107], v[48:51]
	v_add3_u32 v76, v91, v85, v83
	v_add3_u32 v91, v91, v82, v83
	v_mfma_f32_16x16x32_f16 v[44:47], v[72:75], v[92:95], v[44:47]
	v_mfma_f32_16x16x32_f16 v[40:43], v[72:75], v[96:99], v[40:43]
	v_mfma_f32_16x16x32_f16 v[36:39], v[72:75], v[100:103], v[36:39]
	v_mfma_f32_16x16x32_f16 v[32:35], v[72:75], v[104:107], v[32:35]
	v_mfma_f32_16x16x32_f16 v[28:31], v[68:71], v[92:95], v[28:31]
	v_mfma_f32_16x16x32_f16 v[24:27], v[68:71], v[96:99], v[24:27]
	v_mfma_f32_16x16x32_f16 v[20:23], v[68:71], v[100:103], v[20:23]
	v_mfma_f32_16x16x32_f16 v[16:19], v[68:71], v[104:107], v[16:19]
	v_mfma_f32_16x16x32_f16 v[12:15], v[64:67], v[92:95], v[12:15]
	v_mfma_f32_16x16x32_f16 v[8:11], v[64:67], v[96:99], v[8:11]
	v_mfma_f32_16x16x32_f16 v[4:7], v[64:67], v[100:103], v[4:7]
	v_mfma_f32_16x16x32_f16 v[0:3], v[64:67], v[104:107], v[0:3]
	ds_read_b128 v[64:67], v76
	ds_read_b128 v[68:71], v76 offset:2048
	ds_read_b128 v[72:75], v76 offset:4096
	ds_read_b128 v[76:79], v76 offset:6144
	ds_read_b128 v[92:95], v91 offset:16384
	ds_read_b128 v[96:99], v91 offset:18432
	ds_read_b128 v[100:103], v91 offset:20480
	ds_read_b128 v[104:107], v91 offset:22528
	s_waitcnt lgkmcnt(3)
	v_mfma_f32_16x16x32_f16 v[60:63], v[64:67], v[92:95], v[60:63]
	s_waitcnt lgkmcnt(2)
	v_mfma_f32_16x16x32_f16 v[56:59], v[64:67], v[96:99], v[56:59]
	s_waitcnt lgkmcnt(1)
	v_mfma_f32_16x16x32_f16 v[52:55], v[64:67], v[100:103], v[52:55]
	s_waitcnt lgkmcnt(0)
	v_mfma_f32_16x16x32_f16 v[48:51], v[64:67], v[104:107], v[48:51]
	v_mfma_f32_16x16x32_f16 v[44:47], v[68:71], v[92:95], v[44:47]
	v_mfma_f32_16x16x32_f16 v[40:43], v[68:71], v[96:99], v[40:43]
	v_mfma_f32_16x16x32_f16 v[36:39], v[68:71], v[100:103], v[36:39]
	v_mfma_f32_16x16x32_f16 v[32:35], v[68:71], v[104:107], v[32:35]
	v_mfma_f32_16x16x32_f16 v[28:31], v[72:75], v[92:95], v[28:31]
	v_mfma_f32_16x16x32_f16 v[24:27], v[72:75], v[96:99], v[24:27]
	v_mfma_f32_16x16x32_f16 v[20:23], v[72:75], v[100:103], v[20:23]
	v_mfma_f32_16x16x32_f16 v[16:19], v[72:75], v[104:107], v[16:19]
	v_mfma_f32_16x16x32_f16 v[12:15], v[76:79], v[92:95], v[12:15]
	v_mfma_f32_16x16x32_f16 v[8:11], v[76:79], v[96:99], v[8:11]
	v_mfma_f32_16x16x32_f16 v[4:7], v[76:79], v[100:103], v[4:7]
	v_mfma_f32_16x16x32_f16 v[0:3], v[76:79], v[104:107], v[0:3]
	s_cbranch_scc0 .LBB0_635
	s_waitcnt vmcnt(0)
	s_barrier
	ds_read_b128 v[64:67], v90 offset:32768
	ds_read_b128 v[68:71], v89 offset:49152
	ds_read_b128 v[72:75], v89 offset:51200
	ds_read_b128 v[76:79], v89 offset:53248
	ds_read_b128 v[92:95], v89 offset:55296
	ds_read_b128 v[96:99], v90 offset:34816
	ds_read_b128 v[100:103], v88 offset:32768
	ds_read_b128 v[104:107], v88 offset:34816
	ds_read_b128 v[108:111], v87 offset:51200
	ds_read_b128 v[116:119], v87 offset:49152
	s_waitcnt lgkmcnt(8)
	v_mfma_f32_16x16x32_f16 v[60:63], v[64:67], v[68:71], v[60:63]
	ds_read_b128 v[124:127], v87 offset:55296
	ds_read_b128 v[128:131], v87 offset:53248
	ds_read_b128 v[132:135], v88 offset:38912
	ds_read_b128 v[136:139], v88 offset:36864
	s_add_i32 s10, s10, s60
	s_cmp_ge_i32 s10, s62
	s_waitcnt lgkmcnt(4)
	v_mfma_f32_16x16x32_f16 v[60:63], v[100:103], v[116:119], v[60:63]
	v_mfma_f32_16x16x32_f16 v[56:59], v[64:67], v[72:75], v[56:59]
	v_mfma_f32_16x16x32_f16 v[52:55], v[64:67], v[76:79], v[52:55]
	v_mfma_f32_16x16x32_f16 v[64:67], v[64:67], v[92:95], v[48:51]
	v_mfma_f32_16x16x32_f16 v[120:123], v[96:99], v[72:75], v[40:43]
	s_nop 2
	ds_read_b128 v[40:43], v90 offset:38912
	ds_read_b128 v[140:143], v90 offset:36864
	v_mul_f32_e32 v48, 0xbfb8aa3b, v60
	v_exp_f32_e32 v49, v48
	s_waitcnt lgkmcnt(0)
	v_mfma_f32_16x16x32_f16 v[28:31], v[140:143], v[68:71], v[28:31]
	v_add_f32_e32 v51, 1.0, v49
	v_lshl_or_b32 v48, s11, 6, v86
	v_add_u32_e32 v50, s12, v80
	v_mfma_f32_16x16x32_f16 v[144:147], v[140:143], v[72:75], v[24:27]
	v_ashrrev_i32_e32 v49, 31, v48
	v_lshl_add_u64 v[48:49], v[48:49], 1, s[30:31]
	v_mad_i64_i32 v[148:149], s[2:3], v50, s64, v[48:49]
	v_mfma_f32_16x16x32_f16 v[20:23], v[140:143], v[76:79], v[20:23]
	v_div_scale_f32 v24, vcc, v60, v51, v60
	v_mfma_f32_16x16x32_f16 v[140:143], v[140:143], v[92:95], v[16:19]
	s_nop 2
	v_mul_f32_e32 v17, 0xbfb8aa3b, v61
	v_mfma_f32_16x16x32_f16 v[44:47], v[96:99], v[68:71], v[44:47]
	v_exp_f32_e32 v17, v17
	v_mfma_f32_16x16x32_f16 v[36:39], v[96:99], v[76:79], v[36:39]
	v_mfma_f32_16x16x32_f16 v[96:99], v[96:99], v[92:95], v[32:35]
	s_nop 2
	v_div_scale_f32 v32, s[2:3], v51, v51, v60
	v_rcp_f32_e32 v33, v32
	v_mfma_f32_16x16x32_f16 v[12:15], v[40:43], v[68:71], v[12:15]
	v_fma_f32 v34, -v32, v33, 1.0
	v_mfma_f32_16x16x32_f16 v[68:71], v[40:43], v[72:75], v[8:11]
	v_fmac_f32_e32 v33, v34, v33
	v_mul_f32_e32 v25, v24, v33
	v_fma_f32 v26, -v32, v25, v24
	v_add_f32_e32 v8, 1.0, v17
	v_div_scale_f32 v9, s[2:3], v8, v8, v61
	v_rcp_f32_e32 v10, v9
	v_fmac_f32_e32 v25, v26, v33
	v_fma_f32 v16, -v32, v25, v24
	v_mfma_f32_16x16x32_f16 v[72:75], v[40:43], v[92:95], v[0:3]
	v_div_fmas_f32 v16, v16, v33, v25
	v_div_fixup_f32 v16, v16, v51, v60
	v_or_b32_e32 v51, 2, v50
	v_fma_f32 v1, -v9, v10, 1.0
	v_fmac_f32_e32 v10, v1, v10
	v_div_scale_f32 v1, vcc, v61, v8, v61
	v_mul_f32_e32 v2, v1, v10
	v_fma_f32 v3, -v9, v2, v1
	v_fmac_f32_e32 v2, v3, v10
	v_fma_f32 v1, -v9, v2, v1
	v_div_fmas_f32 v1, v1, v10, v2
	v_mul_f32_e32 v2, 0xbfb8aa3b, v62
	v_mfma_f32_16x16x32_f16 v[52:55], v[100:103], v[128:131], v[52:55]
	v_exp_f32_e32 v2, v2
	v_or_b32_e32 v0, 1, v50
	v_div_fixup_f32 v1, v1, v8, v61
	v_mfma_f32_16x16x32_f16 v[4:7], v[40:43], v[76:79], v[4:7]
	v_mfma_f32_16x16x32_f16 v[56:59], v[100:103], v[108:111], v[56:59]
	s_nop 2
	v_mul_f32_e32 v16, v52, v16
	v_mul_f32_e32 v1, v53, v1
	v_mad_i64_i32 v[52:53], s[2:3], v0, s64, v[48:49]
	v_add_f32_e32 v0, 1.0, v2
	v_med3_f32 v1, v1, s57, v194
	v_div_scale_f32 v2, s[2:3], v0, v0, v62
	v_cvt_f16_f32_e32 v1, v1
	v_rcp_f32_e32 v3, v2
	v_mfma_f32_16x16x32_f16 v[64:67], v[100:103], v[124:127], v[64:67]
	v_med3_f32 v16, v16, s57, v194
	global_store_short v[52:53], v1, off
	v_fma_f32 v1, -v2, v3, 1.0
	v_fmac_f32_e32 v3, v1, v3
	v_div_scale_f32 v1, vcc, v62, v0, v62
	v_mul_f32_e32 v60, v1, v3
	v_fma_f32 v8, -v2, v60, v1
	v_fmac_f32_e32 v60, v8, v3
	v_fma_f32 v1, -v2, v60, v1
	v_div_fmas_f32 v1, v1, v3, v60
	v_mfma_f32_16x16x32_f16 v[8:11], v[132:135], v[116:119], v[12:15]
	v_cvt_f16_f32_e32 v16, v16
	global_store_short v[148:149], v16, off
	s_nop 0
	v_div_fixup_f32 v12, v1, v0, v62
	v_mul_f32_e32 v54, v54, v12
	v_mul_f32_e32 v12, 0xbfb8aa3b, v63
	v_exp_f32_e32 v60, v12
	v_mfma_f32_16x16x32_f16 v[0:3], v[132:135], v[108:111], v[68:71]
	v_add_f32_e32 v62, 1.0, v60
	v_mfma_f32_16x16x32_f16 v[12:15], v[132:135], v[128:131], v[4:7]
	s_nop 0
	v_div_scale_f32 v68, s[2:3], v62, v62, v63
	v_rcp_f32_e32 v69, v68
	v_med3_f32 v4, v54, s57, v194
	v_cvt_f16_f32_e32 v54, v4
	v_mad_i64_i32 v[60:61], s[2:3], v51, s64, v[48:49]
	v_or_b32_e32 v51, 3, v50
	global_store_short v[60:61], v54, off
	v_fma_f32 v54, -v68, v69, 1.0
	v_fmac_f32_e32 v69, v54, v69
	v_div_scale_f32 v54, vcc, v63, v62, v63
	v_mul_f32_e32 v70, v54, v69
	v_fma_f32 v71, -v68, v70, v54
	v_fmac_f32_e32 v70, v71, v69
	v_fma_f32 v54, -v68, v70, v54
	v_mul_f32_e32 v68, 0xbfb8aa3b, v56
	v_exp_f32_e32 v68, v68
	v_div_fmas_f32 v54, v54, v69, v70
	v_div_fixup_f32 v54, v54, v62, v63
	v_mul_f32_e32 v54, v55, v54
	v_add_f32_e32 v62, 1.0, v68
	v_div_scale_f32 v63, s[2:3], v62, v62, v56
	v_rcp_f32_e32 v68, v63
	v_med3_f32 v54, v54, s57, v194
	v_cvt_f16_f32_e32 v69, v54
	v_mad_i64_i32 v[54:55], s[2:3], v51, s64, v[48:49]
	v_fma_f32 v51, -v63, v68, 1.0
	v_fmac_f32_e32 v68, v51, v68
	v_div_scale_f32 v51, vcc, v56, v62, v56
	v_mul_f32_e32 v70, v51, v68
	v_fma_f32 v71, -v63, v70, v51
	v_fmac_f32_e32 v70, v71, v68
	v_fma_f32 v51, -v63, v70, v51
	v_mul_f32_e32 v63, 0xbfb8aa3b, v57
	v_exp_f32_e32 v63, v63
	v_div_fmas_f32 v51, v51, v68, v70
	v_div_fixup_f32 v51, v51, v62, v56
	v_mul_f32_e32 v51, v64, v51
	v_add_f32_e32 v56, 1.0, v63
	v_div_scale_f32 v62, s[2:3], v56, v56, v57
	v_rcp_f32_e32 v63, v62
	v_med3_f32 v51, v51, s57, v194
	v_cvt_f16_f32_e32 v51, v51
	v_mfma_f32_16x16x32_f16 v[40:43], v[104:107], v[116:119], v[44:47]
	v_fma_f32 v64, -v62, v63, 1.0
	v_fmac_f32_e32 v63, v64, v63
	v_div_scale_f32 v64, vcc, v57, v56, v57
	v_mul_f32_e32 v68, v64, v63
	v_fma_f32 v70, -v62, v68, v64
	v_fmac_f32_e32 v68, v70, v63
	v_fma_f32 v62, -v62, v68, v64
	v_div_fmas_f32 v62, v62, v63, v68
	v_div_fixup_f32 v56, v62, v56, v57
	v_mul_f32_e32 v57, 0xbfb8aa3b, v58
	v_exp_f32_e32 v57, v57
	v_mul_f32_e32 v56, v65, v56
	v_med3_f32 v56, v56, s57, v194
	v_cvt_f16_f32_e32 v56, v56
	v_add_f32_e32 v57, 1.0, v57
	v_div_scale_f32 v62, s[2:3], v57, v57, v58
	v_rcp_f32_e32 v63, v62
	global_store_short v[54:55], v69, off
	global_store_short v[148:149], v51, off offset:32
	global_store_short v[52:53], v56, off offset:32
	v_mfma_f32_16x16x32_f16 v[44:47], v[104:107], v[128:131], v[36:39]
	v_fma_f32 v51, -v62, v63, 1.0
	v_fmac_f32_e32 v63, v51, v63
	v_div_scale_f32 v51, vcc, v58, v57, v58
	v_mul_f32_e32 v52, v51, v63
	v_fma_f32 v53, -v62, v52, v51
	v_fmac_f32_e32 v52, v53, v63
	v_mul_f32_e32 v53, 0xbfb8aa3b, v59
	v_exp_f32_e32 v53, v53
	v_fma_f32 v51, -v62, v52, v51
	v_div_fmas_f32 v51, v51, v63, v52
	v_div_fixup_f32 v51, v51, v57, v58
	v_add_f32_e32 v52, 1.0, v53
	v_div_scale_f32 v53, s[2:3], v52, v52, v59
	v_rcp_f32_e32 v56, v53
	v_mul_f32_e32 v51, v66, v51
	v_med3_f32 v51, v51, s57, v194
	v_cvt_f16_f32_e32 v51, v51
	v_fma_f32 v57, -v53, v56, 1.0
	v_fmac_f32_e32 v56, v57, v56
	v_div_scale_f32 v57, vcc, v59, v52, v59
	v_mul_f32_e32 v58, v57, v56
	v_fma_f32 v62, -v53, v58, v57
	v_fmac_f32_e32 v58, v62, v56
	v_fma_f32 v53, -v53, v58, v57
	v_div_fmas_f32 v53, v53, v56, v58
	v_div_fixup_f32 v52, v53, v52, v59
	v_mul_f32_e32 v53, 0xbfb8aa3b, v40
	v_exp_f32_e32 v53, v53
	v_mul_f32_e32 v52, v67, v52
	v_med3_f32 v52, v52, s57, v194
	v_cvt_f16_f32_e32 v52, v52
	v_add_f32_e32 v53, 1.0, v53
	v_div_scale_f32 v56, s[2:3], v53, v53, v40
	v_rcp_f32_e32 v57, v56
	global_store_short v[60:61], v51, off offset:32
	global_store_short v[54:55], v52, off offset:32
	v_or_b32_e32 v51, 16, v50
	v_mfma_f32_16x16x32_f16 v[32:35], v[104:107], v[108:111], v[120:123]
	v_fma_f32 v52, -v56, v57, 1.0
	v_fmac_f32_e32 v57, v52, v57
	v_div_scale_f32 v52, vcc, v40, v53, v40
	v_mul_f32_e32 v54, v52, v57
	v_fma_f32 v55, -v56, v54, v52
	v_fmac_f32_e32 v54, v55, v57
	v_fma_f32 v52, -v56, v54, v52
	v_div_fmas_f32 v52, v52, v57, v54
	v_div_fixup_f32 v40, v52, v53, v40
	v_mul_f32_e32 v52, 0xbfb8aa3b, v41
	v_exp_f32_e32 v52, v52
	v_mul_f32_e32 v40, v44, v40
	v_mfma_f32_16x16x32_f16 v[36:39], v[104:107], v[124:127], v[96:99]
	v_med3_f32 v40, v40, s57, v194
	v_add_f32_e32 v44, 1.0, v52
	v_div_scale_f32 v54, s[2:3], v44, v44, v41
	v_rcp_f32_e32 v55, v54
	v_mad_i64_i32 v[52:53], s[2:3], v51, s64, v[48:49]
	v_cvt_f16_f32_e32 v40, v40
	v_fma_f32 v51, -v54, v55, 1.0
	v_fmac_f32_e32 v55, v51, v55
	v_div_scale_f32 v51, vcc, v41, v44, v41
	v_mul_f32_e32 v56, v51, v55
	v_fma_f32 v57, -v54, v56, v51
	v_fmac_f32_e32 v56, v57, v55
	v_fma_f32 v51, -v54, v56, v51
	v_div_fmas_f32 v51, v51, v55, v56
	v_div_fixup_f32 v41, v51, v44, v41
	v_mul_f32_e32 v44, 0xbfb8aa3b, v42
	v_exp_f32_e32 v44, v44
	v_mul_f32_e32 v41, v45, v41
	v_med3_f32 v41, v41, s57, v194
	v_cvt_f16_f32_e32 v45, v41
	v_add_f32_e32 v44, 1.0, v44
	v_div_scale_f32 v51, s[2:3], v44, v44, v42
	v_rcp_f32_e32 v54, v51
	global_store_short v[52:53], v40, off
	v_or_b32_e32 v40, 17, v50
	v_mad_i64_i32 v[40:41], s[2:3], v40, s64, v[48:49]
	v_fma_f32 v55, -v51, v54, 1.0
	v_fmac_f32_e32 v54, v55, v54
	v_div_scale_f32 v55, vcc, v42, v44, v42
	v_mul_f32_e32 v56, v55, v54
	v_fma_f32 v57, -v51, v56, v55
	v_fmac_f32_e32 v56, v57, v54
	v_fma_f32 v51, -v51, v56, v55
	v_div_fmas_f32 v51, v51, v54, v56
	v_div_fixup_f32 v42, v51, v44, v42
	v_mul_f32_e32 v44, 0xbfb8aa3b, v43
	v_exp_f32_e32 v44, v44
	v_mul_f32_e32 v42, v46, v42
	v_med3_f32 v42, v42, s57, v194
	v_cvt_f16_f32_e32 v42, v42
	v_add_f32_e32 v46, 1.0, v44
	v_div_scale_f32 v51, s[2:3], v46, v46, v43
	v_rcp_f32_e32 v54, v51
	global_store_short v[40:41], v45, off
	v_or_b32_e32 v45, 18, v50
	v_mad_i64_i32 v[44:45], s[2:3], v45, s64, v[48:49]
	v_fma_f32 v55, -v51, v54, 1.0
	v_fmac_f32_e32 v54, v55, v54
	v_div_scale_f32 v55, vcc, v43, v46, v43
	v_mul_f32_e32 v56, v55, v54
	v_fma_f32 v57, -v51, v56, v55
	v_fmac_f32_e32 v56, v57, v54
	v_fma_f32 v51, -v51, v56, v55
	v_div_fmas_f32 v51, v51, v54, v56
	v_mul_f32_e32 v54, 0xbfb8aa3b, v32
	v_exp_f32_e32 v54, v54
	v_div_fixup_f32 v43, v51, v46, v43
	v_mul_f32_e32 v43, v47, v43
	v_med3_f32 v43, v43, s57, v194
	v_add_f32_e32 v46, 1.0, v54
	v_div_scale_f32 v47, s[2:3], v46, v46, v32
	v_rcp_f32_e32 v51, v47
	v_cvt_f16_f32_e32 v54, v43
	global_store_short v[44:45], v42, off
	v_or_b32_e32 v42, 19, v50
	v_fma_f32 v55, -v47, v51, 1.0
	v_fmac_f32_e32 v51, v55, v51
	v_div_scale_f32 v55, vcc, v32, v46, v32
	v_mul_f32_e32 v56, v55, v51
	v_fma_f32 v57, -v47, v56, v55
	v_fmac_f32_e32 v56, v57, v51
	v_fma_f32 v47, -v47, v56, v55
	v_mul_f32_e32 v55, 0xbfb8aa3b, v33
	v_exp_f32_e32 v55, v55
	v_div_fmas_f32 v47, v47, v51, v56
	v_div_fixup_f32 v32, v47, v46, v32
	v_mul_f32_e32 v32, v36, v32
	v_add_f32_e32 v46, 1.0, v55
	v_div_scale_f32 v47, s[2:3], v46, v46, v33
	v_rcp_f32_e32 v51, v47
	v_med3_f32 v32, v32, s57, v194
	v_cvt_f16_f32_e32 v32, v32
	v_mad_i64_i32 v[42:43], s[2:3], v42, s64, v[48:49]
	v_fma_f32 v36, -v47, v51, 1.0
	v_fmac_f32_e32 v51, v36, v51
	v_div_scale_f32 v36, vcc, v33, v46, v33
	v_mul_f32_e32 v55, v36, v51
	v_fma_f32 v56, -v47, v55, v36
	v_fmac_f32_e32 v55, v56, v51
	v_fma_f32 v36, -v47, v55, v36
	v_div_fmas_f32 v36, v36, v51, v55
	v_div_fixup_f32 v33, v36, v46, v33
	v_mul_f32_e32 v36, 0xbfb8aa3b, v34
	v_exp_f32_e32 v36, v36
	v_mul_f32_e32 v33, v37, v33
	v_med3_f32 v33, v33, s57, v194
	v_cvt_f16_f32_e32 v33, v33
	v_add_f32_e32 v36, 1.0, v36
	v_div_scale_f32 v37, s[2:3], v36, v36, v34
	v_rcp_f32_e32 v46, v37
	global_store_short v[42:43], v54, off
	global_store_short v[52:53], v32, off offset:32
	global_store_short v[40:41], v33, off offset:32
	v_mfma_f32_16x16x32_f16 v[24:27], v[136:139], v[116:119], v[28:31]
	v_fma_f32 v32, -v37, v46, 1.0
	v_fmac_f32_e32 v46, v32, v46
	v_div_scale_f32 v32, vcc, v34, v36, v34
	v_mul_f32_e32 v33, v32, v46
	v_fma_f32 v40, -v37, v33, v32
	v_fmac_f32_e32 v33, v40, v46
	v_fma_f32 v32, -v37, v33, v32
	v_mul_f32_e32 v37, 0xbfb8aa3b, v35
	v_exp_f32_e32 v37, v37
	v_div_fmas_f32 v32, v32, v46, v33
	v_div_fixup_f32 v32, v32, v36, v34
	v_mul_f32_e32 v32, v38, v32
	v_add_f32_e32 v33, 1.0, v37
	v_div_scale_f32 v34, s[2:3], v33, v33, v35
	v_rcp_f32_e32 v36, v34
	v_med3_f32 v32, v32, s57, v194
	v_cvt_f16_f32_e32 v32, v32
	v_mfma_f32_16x16x32_f16 v[28:31], v[136:139], v[128:131], v[20:23]
	v_fma_f32 v37, -v34, v36, 1.0
	v_fmac_f32_e32 v36, v37, v36
	v_div_scale_f32 v37, vcc, v35, v33, v35
	v_mul_f32_e32 v38, v37, v36
	v_fma_f32 v40, -v34, v38, v37
	v_fmac_f32_e32 v38, v40, v36
	v_fma_f32 v34, -v34, v38, v37
	v_div_fmas_f32 v34, v34, v36, v38
	v_div_fixup_f32 v33, v34, v33, v35
	v_mul_f32_e32 v34, 0xbfb8aa3b, v24
	v_exp_f32_e32 v34, v34
	v_mul_f32_e32 v33, v39, v33
	v_med3_f32 v33, v33, s57, v194
	v_cvt_f16_f32_e32 v33, v33
	v_add_f32_e32 v34, 1.0, v34
	v_div_scale_f32 v35, s[2:3], v34, v34, v24
	v_rcp_f32_e32 v36, v35
	global_store_short v[44:45], v32, off offset:32
	global_store_short v[42:43], v33, off offset:32
	v_mfma_f32_16x16x32_f16 v[16:19], v[136:139], v[108:111], v[144:147]
	v_or_b32_e32 v32, 32, v50
	v_fma_f32 v33, -v35, v36, 1.0
	v_fmac_f32_e32 v36, v33, v36
	v_div_scale_f32 v33, vcc, v24, v34, v24
	v_mul_f32_e32 v37, v33, v36
	v_fma_f32 v38, -v35, v37, v33
	v_fmac_f32_e32 v37, v38, v36
	v_fma_f32 v33, -v35, v37, v33
	v_div_fmas_f32 v33, v33, v36, v37
	v_div_fixup_f32 v24, v33, v34, v24
	v_mul_f32_e32 v33, 0xbfb8aa3b, v25
	v_exp_f32_e32 v33, v33
	v_mul_f32_e32 v24, v28, v24
	v_mfma_f32_16x16x32_f16 v[20:23], v[136:139], v[124:127], v[140:143]
	v_med3_f32 v24, v24, s57, v194
	v_add_f32_e32 v28, 1.0, v33
	v_div_scale_f32 v34, s[2:3], v28, v28, v25
	v_rcp_f32_e32 v35, v34
	v_cvt_f16_f32_e32 v24, v24
	v_mad_i64_i32 v[32:33], s[2:3], v32, s64, v[48:49]
	v_fma_f32 v36, -v34, v35, 1.0
	v_fmac_f32_e32 v35, v36, v35
	v_div_scale_f32 v36, vcc, v25, v28, v25
	v_mul_f32_e32 v37, v36, v35
	v_fma_f32 v38, -v34, v37, v36
	v_fmac_f32_e32 v37, v38, v35
	v_fma_f32 v34, -v34, v37, v36
	v_div_fmas_f32 v34, v34, v35, v37
	v_div_fixup_f32 v25, v34, v28, v25
	v_mul_f32_e32 v28, 0xbfb8aa3b, v26
	v_exp_f32_e32 v28, v28
	v_mul_f32_e32 v25, v29, v25
	v_med3_f32 v25, v25, s57, v194
	v_cvt_f16_f32_e32 v29, v25
	v_add_f32_e32 v28, 1.0, v28
	v_div_scale_f32 v34, s[2:3], v28, v28, v26
	v_rcp_f32_e32 v35, v34
	global_store_short v[32:33], v24, off
	v_or_b32_e32 v24, 33, v50
	v_mad_i64_i32 v[24:25], s[2:3], v24, s64, v[48:49]
	v_fma_f32 v36, -v34, v35, 1.0
	v_fmac_f32_e32 v35, v36, v35
	v_div_scale_f32 v36, vcc, v26, v28, v26
	v_mul_f32_e32 v37, v36, v35
	v_fma_f32 v38, -v34, v37, v36
	v_fmac_f32_e32 v37, v38, v35
	v_fma_f32 v34, -v34, v37, v36
	v_div_fmas_f32 v34, v34, v35, v37
	v_div_fixup_f32 v26, v34, v28, v26
	v_mul_f32_e32 v28, 0xbfb8aa3b, v27
	v_exp_f32_e32 v28, v28
	v_mul_f32_e32 v26, v30, v26
	v_med3_f32 v26, v26, s57, v194
	v_cvt_f16_f32_e32 v26, v26
	v_add_f32_e32 v30, 1.0, v28
	v_div_scale_f32 v34, s[2:3], v30, v30, v27
	v_rcp_f32_e32 v35, v34
	global_store_short v[24:25], v29, off
	v_or_b32_e32 v29, 34, v50
	v_mad_i64_i32 v[28:29], s[2:3], v29, s64, v[48:49]
	v_fma_f32 v36, -v34, v35, 1.0
	v_fmac_f32_e32 v35, v36, v35
	v_div_scale_f32 v36, vcc, v27, v30, v27
	v_mul_f32_e32 v37, v36, v35
	v_fma_f32 v38, -v34, v37, v36
	v_fmac_f32_e32 v37, v38, v35
	v_fma_f32 v34, -v34, v37, v36
	v_div_fmas_f32 v34, v34, v35, v37
	v_mul_f32_e32 v35, 0xbfb8aa3b, v16
	v_exp_f32_e32 v35, v35
	v_div_fixup_f32 v27, v34, v30, v27
	v_mul_f32_e32 v27, v31, v27
	v_med3_f32 v27, v27, s57, v194
	v_add_f32_e32 v30, 1.0, v35
	v_div_scale_f32 v31, s[2:3], v30, v30, v16
	v_rcp_f32_e32 v34, v31
	v_cvt_f16_f32_e32 v35, v27
	global_store_short v[28:29], v26, off
	v_or_b32_e32 v26, 35, v50
	v_fma_f32 v36, -v31, v34, 1.0
	v_fmac_f32_e32 v34, v36, v34
	v_div_scale_f32 v36, vcc, v16, v30, v16
	v_mul_f32_e32 v37, v36, v34
	v_fma_f32 v38, -v31, v37, v36
	v_fmac_f32_e32 v37, v38, v34
	v_fma_f32 v31, -v31, v37, v36
	v_mul_f32_e32 v36, 0xbfb8aa3b, v17
	v_exp_f32_e32 v36, v36
	v_div_fmas_f32 v31, v31, v34, v37
	v_div_fixup_f32 v16, v31, v30, v16
	v_mul_f32_e32 v16, v20, v16
	v_add_f32_e32 v30, 1.0, v36
	v_div_scale_f32 v31, s[2:3], v30, v30, v17
	v_rcp_f32_e32 v34, v31
	v_med3_f32 v16, v16, s57, v194
	v_cvt_f16_f32_e32 v16, v16
	v_mad_i64_i32 v[26:27], s[2:3], v26, s64, v[48:49]
	v_fma_f32 v20, -v31, v34, 1.0
	v_fmac_f32_e32 v34, v20, v34
	v_div_scale_f32 v20, vcc, v17, v30, v17
	v_mul_f32_e32 v36, v20, v34
	v_fma_f32 v37, -v31, v36, v20
	v_fmac_f32_e32 v36, v37, v34
	v_fma_f32 v20, -v31, v36, v20
	v_div_fmas_f32 v20, v20, v34, v36
	v_div_fixup_f32 v17, v20, v30, v17
	v_mul_f32_e32 v20, 0xbfb8aa3b, v18
	v_exp_f32_e32 v20, v20
	v_mul_f32_e32 v17, v21, v17
	v_med3_f32 v17, v17, s57, v194
	v_cvt_f16_f32_e32 v17, v17
	v_add_f32_e32 v20, 1.0, v20
	v_div_scale_f32 v21, s[2:3], v20, v20, v18
	v_rcp_f32_e32 v30, v21
	global_store_short v[26:27], v35, off
	global_store_short v[32:33], v16, off offset:32
	global_store_short v[24:25], v17, off offset:32
	v_mfma_f32_16x16x32_f16 v[4:7], v[132:135], v[124:127], v[72:75]
	v_fma_f32 v16, -v21, v30, 1.0
	v_fmac_f32_e32 v30, v16, v30
	v_div_scale_f32 v16, vcc, v18, v20, v18
	v_mul_f32_e32 v17, v16, v30
	v_fma_f32 v24, -v21, v17, v16
	v_fmac_f32_e32 v17, v24, v30
	v_fma_f32 v16, -v21, v17, v16
	v_mul_f32_e32 v21, 0xbfb8aa3b, v19
	v_exp_f32_e32 v21, v21
	v_div_fmas_f32 v16, v16, v30, v17
	v_div_fixup_f32 v16, v16, v20, v18
	v_mul_f32_e32 v16, v22, v16
	v_add_f32_e32 v17, 1.0, v21
	v_div_scale_f32 v18, s[2:3], v17, v17, v19
	v_rcp_f32_e32 v20, v18
	v_med3_f32 v16, v16, s57, v194
	v_cvt_f16_f32_e32 v16, v16
	v_fma_f32 v21, -v18, v20, 1.0
	v_fmac_f32_e32 v20, v21, v20
	v_div_scale_f32 v21, vcc, v19, v17, v19
	v_mul_f32_e32 v22, v21, v20
	v_fma_f32 v24, -v18, v22, v21
	v_fmac_f32_e32 v22, v24, v20
	v_fma_f32 v18, -v18, v22, v21
	v_div_fmas_f32 v18, v18, v20, v22
	v_div_fixup_f32 v17, v18, v17, v19
	v_mul_f32_e32 v18, 0xbfb8aa3b, v8
	v_exp_f32_e32 v18, v18
	v_mul_f32_e32 v17, v23, v17
	v_med3_f32 v17, v17, s57, v194
	v_cvt_f16_f32_e32 v17, v17
	v_add_f32_e32 v18, 1.0, v18
	v_div_scale_f32 v19, s[2:3], v18, v18, v8
	v_rcp_f32_e32 v20, v19
	global_store_short v[28:29], v16, off offset:32
	global_store_short v[26:27], v17, off offset:32
	v_or_b32_e32 v16, 48, v50
	v_fma_f32 v17, -v19, v20, 1.0
	v_fmac_f32_e32 v20, v17, v20
	v_div_scale_f32 v17, vcc, v8, v18, v8
	v_mul_f32_e32 v21, v17, v20
	v_fma_f32 v22, -v19, v21, v17
	v_fmac_f32_e32 v21, v22, v20
	v_fma_f32 v17, -v19, v21, v17
	v_div_fmas_f32 v17, v17, v20, v21
	v_div_fixup_f32 v8, v17, v18, v8
	v_mul_f32_e32 v17, 0xbfb8aa3b, v9
	v_exp_f32_e32 v17, v17
	v_mul_f32_e32 v8, v12, v8
	v_med3_f32 v8, v8, s57, v194
	v_cvt_f16_f32_e32 v8, v8
	v_add_f32_e32 v12, 1.0, v17
	v_div_scale_f32 v18, s[2:3], v12, v12, v9
	v_rcp_f32_e32 v19, v18
	v_mad_i64_i32 v[16:17], s[2:3], v16, s64, v[48:49]
	global_store_short v[16:17], v8, off
	v_fma_f32 v20, -v18, v19, 1.0
	v_fmac_f32_e32 v19, v20, v19
	v_div_scale_f32 v20, vcc, v9, v12, v9
	v_mul_f32_e32 v21, v20, v19
	v_fma_f32 v22, -v18, v21, v20
	v_fmac_f32_e32 v21, v22, v19
	v_fma_f32 v18, -v18, v21, v20
	v_div_fmas_f32 v18, v18, v19, v21
	v_div_fixup_f32 v9, v18, v12, v9
	v_mul_f32_e32 v12, 0xbfb8aa3b, v10
	v_exp_f32_e32 v12, v12
	v_mul_f32_e32 v9, v13, v9
	v_med3_f32 v9, v9, s57, v194
	v_cvt_f16_f32_e32 v13, v9
	v_add_f32_e32 v12, 1.0, v12
	v_div_scale_f32 v18, s[2:3], v12, v12, v10
	v_rcp_f32_e32 v19, v18
	v_or_b32_e32 v8, 49, v50
	v_mad_i64_i32 v[8:9], s[2:3], v8, s64, v[48:49]
	v_fma_f32 v20, -v18, v19, 1.0
	v_fmac_f32_e32 v19, v20, v19
	v_div_scale_f32 v20, vcc, v10, v12, v10
	v_mul_f32_e32 v21, v20, v19
	v_fma_f32 v22, -v18, v21, v20
	v_fmac_f32_e32 v21, v22, v19
	v_fma_f32 v18, -v18, v21, v20
	v_div_fmas_f32 v18, v18, v19, v21
	v_div_fixup_f32 v10, v18, v12, v10
	v_mul_f32_e32 v12, 0xbfb8aa3b, v11
	v_exp_f32_e32 v12, v12
	v_mul_f32_e32 v10, v14, v10
	v_med3_f32 v10, v10, s57, v194
	v_cvt_f16_f32_e32 v10, v10
	v_add_f32_e32 v14, 1.0, v12
	v_div_scale_f32 v18, s[2:3], v14, v14, v11
	v_rcp_f32_e32 v19, v18
	global_store_short v[8:9], v13, off
	v_or_b32_e32 v13, 50, v50
	v_mad_i64_i32 v[12:13], s[2:3], v13, s64, v[48:49]
	v_fma_f32 v20, -v18, v19, 1.0
	v_fmac_f32_e32 v19, v20, v19
	v_div_scale_f32 v20, vcc, v11, v14, v11
	v_mul_f32_e32 v21, v20, v19
	v_fma_f32 v22, -v18, v21, v20
	v_fmac_f32_e32 v21, v22, v19
	v_fma_f32 v18, -v18, v21, v20
	v_div_fmas_f32 v18, v18, v19, v21
	v_mul_f32_e32 v19, 0xbfb8aa3b, v0
	v_exp_f32_e32 v19, v19
	v_div_fixup_f32 v11, v18, v14, v11
	v_mul_f32_e32 v11, v15, v11
	v_med3_f32 v11, v11, s57, v194
	v_add_f32_e32 v14, 1.0, v19
	v_div_scale_f32 v15, s[2:3], v14, v14, v0
	v_rcp_f32_e32 v18, v15
	v_cvt_f16_f32_e32 v19, v11
	global_store_short v[12:13], v10, off
	v_or_b32_e32 v10, 51, v50
	v_fma_f32 v20, -v15, v18, 1.0
	v_fmac_f32_e32 v18, v20, v18
	v_div_scale_f32 v20, vcc, v0, v14, v0
	v_mul_f32_e32 v21, v20, v18
	v_fma_f32 v22, -v15, v21, v20
	v_fmac_f32_e32 v21, v22, v18
	v_fma_f32 v15, -v15, v21, v20
	v_mul_f32_e32 v20, 0xbfb8aa3b, v1
	v_exp_f32_e32 v20, v20
	v_div_fmas_f32 v15, v15, v18, v21
	v_div_fixup_f32 v0, v15, v14, v0
	v_mul_f32_e32 v0, v4, v0
	v_add_f32_e32 v14, 1.0, v20
	v_div_scale_f32 v15, s[2:3], v14, v14, v1
	v_rcp_f32_e32 v18, v15
	v_med3_f32 v0, v0, s57, v194
	v_cvt_f16_f32_e32 v0, v0
	v_mad_i64_i32 v[10:11], s[2:3], v10, s64, v[48:49]
	v_fma_f32 v4, -v15, v18, 1.0
	v_fmac_f32_e32 v18, v4, v18
	v_div_scale_f32 v4, vcc, v1, v14, v1
	v_mul_f32_e32 v20, v4, v18
	v_fma_f32 v21, -v15, v20, v4
	v_fmac_f32_e32 v20, v21, v18
	v_fma_f32 v4, -v15, v20, v4
	v_div_fmas_f32 v4, v4, v18, v20
	v_div_fixup_f32 v1, v4, v14, v1
	v_mul_f32_e32 v4, 0xbfb8aa3b, v2
	v_exp_f32_e32 v4, v4
	v_mul_f32_e32 v1, v5, v1
	v_med3_f32 v1, v1, s57, v194
	v_cvt_f16_f32_e32 v1, v1
	v_add_f32_e32 v4, 1.0, v4
	v_div_scale_f32 v5, s[2:3], v4, v4, v2
	v_rcp_f32_e32 v14, v5
	global_store_short v[10:11], v19, off
	global_store_short v[16:17], v0, off offset:32
	global_store_short v[8:9], v1, off offset:32
	v_fma_f32 v0, -v5, v14, 1.0
	v_fmac_f32_e32 v14, v0, v14
	v_div_scale_f32 v0, vcc, v2, v4, v2
	v_mul_f32_e32 v1, v0, v14
	v_fma_f32 v8, -v5, v1, v0
	v_fmac_f32_e32 v1, v8, v14
	v_fma_f32 v0, -v5, v1, v0
	v_mul_f32_e32 v5, 0xbfb8aa3b, v3
	v_exp_f32_e32 v5, v5
	v_div_fmas_f32 v0, v0, v14, v1
	v_div_fixup_f32 v0, v0, v4, v2
	v_mul_f32_e32 v0, v6, v0
	v_add_f32_e32 v1, 1.0, v5
	v_div_scale_f32 v2, s[2:3], v1, v1, v3
	v_rcp_f32_e32 v4, v2
	v_med3_f32 v0, v0, s57, v194
	v_cvt_f16_f32_e32 v0, v0
	v_fma_f32 v5, -v2, v4, 1.0
	v_fmac_f32_e32 v4, v5, v4
	v_div_scale_f32 v5, vcc, v3, v1, v3
	v_mul_f32_e32 v6, v5, v4
	v_fma_f32 v8, -v2, v6, v5
	v_fmac_f32_e32 v6, v8, v4
	v_fma_f32 v2, -v2, v6, v5
	v_div_fmas_f32 v2, v2, v4, v6
	v_div_fixup_f32 v1, v2, v1, v3
	v_mul_f32_e32 v1, v7, v1
	v_med3_f32 v1, v1, s57, v194
	v_cvt_f16_f32_e32 v1, v1
	global_store_short v[12:13], v0, off offset:32
	global_store_short v[10:11], v1, off offset:32
	s_cbranch_scc0 .LBB0_631

.LBB0_650:
	s_add_i32 s4, s13, 0xffff8000
	v_mov_b32_e32 v64, v182
	s_waitcnt vmcnt(0)
	s_waitcnt vmcnt(0) lgkmcnt(0)
	s_barrier
	s_and_b32 s14, s13, 0x8000
	s_and_b32 s15, s4, 0x8000
	v_or_b32_e32 v71, s15, v86
	v_lshrrev_b32_e32 v65, 4, v64
	v_ashrrev_i32_e32 v66, 3, v64
	v_add_u32_e32 v68, 0x100, v64
	v_lshl_add_u32 v67, v64, 4, s14
	v_add_u32_e32 v69, 0x200, v64
	v_add_u32_e32 v72, s0, v66
	v_bitop3_b32 v73, v65, 7, v64 bitop3:0x48
	v_ashrrev_i32_e32 v74, 3, v68
	s_add_u32 s8, s30, s2
	v_add_u32_e32 v70, 0x300, v64
	v_lshl_add_u32 v68, v68, 4, s14
	v_ashrrev_i32_e32 v75, 3, v69
	v_lshl_add_u32 v69, v69, 4, s14
	v_add_u32_e32 v77, 0x4000, v67
	v_add3_u32 v91, v71, v87, v88
	v_add3_u32 v80, v71, v89, v88
	v_mad_i64_i32 v[64:65], s[4:5], v72, s64, 0
	v_lshlrev_b32_e32 v81, 4, v73
	v_add_u32_e32 v71, s0, v74
	s_addc_u32 s9, s31, s3
	v_ashrrev_i32_e32 v76, 3, v70
	v_lshl_add_u32 v70, v70, 4, s14
	v_readfirstlane_b32 s17, v68
	v_add_u32_e32 v72, s0, v75
	v_readfirstlane_b32 s18, v69
	v_readfirstlane_b32 s20, v77
	v_add_u32_e32 v77, 0x4000, v68
	v_add_u32_e32 v79, 0x4000, v69
	v_or_b32_e32 v64, v64, v81
	v_mad_i64_i32 v[68:69], s[4:5], v71, s64, 0
	v_readfirstlane_b32 s16, v67
	v_add_u32_e32 v73, s0, v76
	v_readfirstlane_b32 s19, v70
	v_add_u32_e32 v83, 0x4000, v70
	v_mad_i64_i32 v[70:71], s[4:5], v72, s64, 0
	v_lshl_add_u64 v[64:65], s[8:9], 0, v[64:65]
	v_or_b32_e32 v68, v68, v81
	v_add_u32_e32 v66, s12, v66
	v_mad_i64_i32 v[72:73], s[4:5], v73, s64, 0
	v_or_b32_e32 v70, v70, v81
	v_lshl_add_u64 v[64:65], v[64:65], 0, s[88:89]
	v_lshl_add_u64 v[68:69], s[8:9], 0, v[68:69]
	s_mov_b32 m0, s16
	v_mad_i64_i32 v[66:67], s[4:5], v66, s64, 0
	v_add_u32_e32 v74, s12, v74
	v_or_b32_e32 v72, v72, v81
	v_lshl_add_u64 v[70:71], s[8:9], 0, v[70:71]
	global_load_lds_dwordx4 v[64:65], off
	v_lshl_add_u64 v[64:65], v[68:69], 0, s[88:89]
	s_mov_b32 m0, s17
	v_add_u32_e32 v78, s12, v75
	v_or_b32_e32 v66, v66, v81
	v_mad_i64_i32 v[74:75], s[4:5], v74, s64, 0
	v_lshl_add_u64 v[72:73], s[8:9], 0, v[72:73]
	v_lshl_add_u64 v[68:69], v[70:71], 0, s[88:89]
	global_load_lds_dwordx4 v[64:65], off
	s_mov_b32 m0, s18
	v_add_u32_e32 v82, s12, v76
	v_readfirstlane_b32 s21, v77
	v_mad_i64_i32 v[76:77], s[4:5], v78, s64, 0
	v_lshl_add_u64 v[66:67], s[8:9], 0, v[66:67]
	v_or_b32_e32 v74, v74, v81
	v_lshl_add_u64 v[70:71], v[72:73], 0, s[88:89]
	global_load_lds_dwordx4 v[68:69], off
	s_mov_b32 m0, s19
	v_readfirstlane_b32 s22, v79
	v_mad_i64_i32 v[78:79], s[4:5], v82, s64, 0
	v_or_b32_e32 v76, v76, v81
	v_lshl_add_u64 v[66:67], v[66:67], 0, s[6:7]
	v_lshl_add_u64 v[74:75], s[8:9], 0, v[74:75]
	global_load_lds_dwordx4 v[70:71], off
	s_mov_b32 m0, s20
	v_or_b32_e32 v78, v78, v81
	v_lshl_add_u64 v[76:77], s[8:9], 0, v[76:77]
	v_lshl_add_u64 v[72:73], v[74:75], 0, s[6:7]
	global_load_lds_dwordx4 v[66:67], off
	s_mov_b32 m0, s21
	v_readfirstlane_b32 s4, v83
	v_lshl_add_u64 v[78:79], s[8:9], 0, v[78:79]
	v_lshl_add_u64 v[74:75], v[76:77], 0, s[6:7]
	global_load_lds_dwordx4 v[72:73], off
	s_mov_b32 m0, s22
	v_lshl_add_u64 v[76:77], v[78:79], 0, s[6:7]
	global_load_lds_dwordx4 v[74:75], off
	s_mov_b32 m0, s4
	s_add_u32 s2, s2, 0x80
	global_load_lds_dwordx4 v[76:77], off
	ds_read_b128 v[64:67], v91
	ds_read_b128 v[68:71], v80 offset:16384
	ds_read_b128 v[72:75], v80 offset:18432
	ds_read_b128 v[76:79], v80 offset:20480
	ds_read_b128 v[80:83], v80 offset:22528
	s_waitcnt lgkmcnt(0)
	v_mfma_f32_16x16x32_f16 v[60:63], v[64:67], v[68:71], v[60:63]
	s_addc_u32 s3, s3, 0
	s_add_i32 s13, s13, 0x8000
	s_cmpk_eq_i32 s2, 0x1580
	v_mfma_f32_16x16x32_f16 v[56:59], v[64:67], v[72:75], v[56:59]
	v_mfma_f32_16x16x32_f16 v[52:55], v[64:67], v[76:79], v[52:55]
	v_mfma_f32_16x16x32_f16 v[48:51], v[64:67], v[80:83], v[48:51]
	ds_read_b128 v[64:67], v91 offset:2048
	s_waitcnt lgkmcnt(0)
	v_mfma_f32_16x16x32_f16 v[44:47], v[64:67], v[68:71], v[44:47]
	v_mfma_f32_16x16x32_f16 v[40:43], v[64:67], v[72:75], v[40:43]
	v_mfma_f32_16x16x32_f16 v[36:39], v[64:67], v[76:79], v[36:39]
	v_mfma_f32_16x16x32_f16 v[32:35], v[64:67], v[80:83], v[32:35]
	ds_read_b128 v[64:67], v91 offset:4096
	s_waitcnt lgkmcnt(0)
	v_mfma_f32_16x16x32_f16 v[24:27], v[64:67], v[68:71], v[24:27]
	v_mfma_f32_16x16x32_f16 v[20:23], v[64:67], v[72:75], v[20:23]
	v_mfma_f32_16x16x32_f16 v[16:19], v[64:67], v[76:79], v[16:19]
	v_mfma_f32_16x16x32_f16 v[12:15], v[64:67], v[80:83], v[12:15]
	ds_read_b128 v[64:67], v91 offset:6144
	s_waitcnt lgkmcnt(0)
	v_mfma_f32_16x16x32_f16 v[8:11], v[64:67], v[68:71], v[8:11]
	v_or_b32_e32 v68, s15, v90
	v_add3_u32 v91, v68, v87, v88
	v_add3_u32 v92, v68, v89, v88
	ds_read_b128 v[68:71], v91
	v_mfma_f32_16x16x32_f16 v[4:7], v[64:67], v[72:75], v[4:7]
	ds_read_b128 v[72:75], v92 offset:18432
	v_mfma_f32_16x16x32_f16 v[0:3], v[64:67], v[76:79], v[0:3]
	ds_read_b128 v[76:79], v92 offset:20480
	v_mfma_f32_16x16x32_f16 v[28:31], v[64:67], v[80:83], v[28:31]
	ds_read_b128 v[64:67], v92 offset:16384
	ds_read_b128 v[80:83], v92 offset:22528
	s_waitcnt lgkmcnt(1)
	v_mfma_f32_16x16x32_f16 v[60:63], v[68:71], v[64:67], v[60:63]
	v_mfma_f32_16x16x32_f16 v[56:59], v[68:71], v[72:75], v[56:59]
	v_mfma_f32_16x16x32_f16 v[52:55], v[68:71], v[76:79], v[52:55]
	s_waitcnt lgkmcnt(0)
	v_mfma_f32_16x16x32_f16 v[48:51], v[68:71], v[80:83], v[48:51]
	ds_read_b128 v[68:71], v91 offset:2048
	s_waitcnt lgkmcnt(0)
	v_mfma_f32_16x16x32_f16 v[44:47], v[68:71], v[64:67], v[44:47]
	v_mfma_f32_16x16x32_f16 v[40:43], v[68:71], v[72:75], v[40:43]
	v_mfma_f32_16x16x32_f16 v[36:39], v[68:71], v[76:79], v[36:39]
	v_mfma_f32_16x16x32_f16 v[32:35], v[68:71], v[80:83], v[32:35]
	ds_read_b128 v[68:71], v91 offset:4096
	s_waitcnt lgkmcnt(0)
	v_mfma_f32_16x16x32_f16 v[24:27], v[68:71], v[64:67], v[24:27]
	v_mfma_f32_16x16x32_f16 v[20:23], v[68:71], v[72:75], v[20:23]
	v_mfma_f32_16x16x32_f16 v[16:19], v[68:71], v[76:79], v[16:19]
	v_mfma_f32_16x16x32_f16 v[12:15], v[68:71], v[80:83], v[12:15]
	ds_read_b128 v[68:71], v91 offset:6144
	s_waitcnt lgkmcnt(0)
	v_mfma_f32_16x16x32_f16 v[8:11], v[68:71], v[64:67], v[8:11]
	v_mfma_f32_16x16x32_f16 v[4:7], v[68:71], v[72:75], v[4:7]
	v_mfma_f32_16x16x32_f16 v[0:3], v[68:71], v[76:79], v[0:3]
	v_mfma_f32_16x16x32_f16 v[28:31], v[68:71], v[80:83], v[28:31]
	s_cbranch_scc0 .LBB0_650
	v_add_u32_e32 v80, s14, v86
	v_add3_u32 v76, v80, v87, v88
	v_add3_u32 v91, v80, v89, v88
	s_waitcnt vmcnt(0)
	s_barrier
	ds_read_b128 v[64:67], v76
	ds_read_b128 v[68:71], v76 offset:2048
	ds_read_b128 v[72:75], v76 offset:4096
	ds_read_b128 v[76:79], v76 offset:6144
	ds_read_b128 v[80:83], v91 offset:16384
	ds_read_b128 v[92:95], v91 offset:18432
	ds_read_b128 v[96:99], v91 offset:20480
	ds_read_b128 v[100:103], v91 offset:22528
	s_waitcnt lgkmcnt(3)
	v_mfma_f32_16x16x32_f16 v[60:63], v[64:67], v[80:83], v[60:63]
	s_ashr_i32 s2, s0, 31
	s_lshr_b32 s2, s2, 19
	s_add_i32 s2, s0, s2
	s_waitcnt lgkmcnt(2)
	v_mfma_f32_16x16x32_f16 v[56:59], v[64:67], v[92:95], v[56:59]
	s_ashr_i32 s2, s2, 13
	s_add_i32 s2, s2, s10
	s_mul_hi_i32 s3, s2, 0x9000
	s_waitcnt lgkmcnt(1)
	v_mfma_f32_16x16x32_f16 v[52:55], v[64:67], v[96:99], v[52:55]
	s_mul_i32 s2, s2, 0x9000
	s_add_u32 s2, s50, s2
	s_addc_u32 s3, s51, s3
	s_waitcnt lgkmcnt(0)
	v_mfma_f32_16x16x32_f16 v[48:51], v[64:67], v[100:103], v[48:51]
	s_add_i32 s11, s11, s59
	s_cmpk_gt_i32 s11, 0x7ff
	v_mfma_f32_16x16x32_f16 v[64:67], v[68:71], v[80:83], v[44:47]
	v_mfma_f32_16x16x32_f16 v[40:43], v[68:71], v[92:95], v[40:43]
	v_mfma_f32_16x16x32_f16 v[36:39], v[68:71], v[96:99], v[36:39]
	v_mfma_f32_16x16x32_f16 v[32:35], v[68:71], v[100:103], v[32:35]
	v_mfma_f32_16x16x32_f16 v[68:71], v[72:75], v[80:83], v[24:27]
	v_mfma_f32_16x16x32_f16 v[20:23], v[72:75], v[92:95], v[20:23]
	v_mfma_f32_16x16x32_f16 v[16:19], v[72:75], v[96:99], v[16:19]
	v_mfma_f32_16x16x32_f16 v[72:75], v[72:75], v[100:103], v[12:15]
	s_nop 2
	v_add_u32_e32 v12, s14, v90
	v_add3_u32 v13, v12, v87, v88
	v_add3_u32 v12, v12, v89, v88
	v_mfma_f32_16x16x32_f16 v[80:83], v[76:79], v[80:83], v[8:11]
	v_mfma_f32_16x16x32_f16 v[92:95], v[76:79], v[92:95], v[4:7]
	v_mfma_f32_16x16x32_f16 v[0:3], v[76:79], v[96:99], v[0:3]
	v_mfma_f32_16x16x32_f16 v[76:79], v[76:79], v[100:103], v[28:31]
	s_nop 0
	ds_read_b128 v[4:7], v13
	ds_read_b128 v[8:11], v13 offset:2048
	ds_read_b128 v[96:99], v13 offset:4096
	ds_read_b128 v[100:103], v13 offset:6144
	ds_read_b128 v[104:107], v12 offset:16384
	ds_read_b128 v[108:111], v12 offset:18432
	ds_read_b128 v[116:119], v12 offset:20480
	ds_read_b128 v[120:123], v12 offset:22528
	s_waitcnt lgkmcnt(1)
	v_mfma_f32_16x16x32_f16 v[28:31], v[4:7], v[116:119], v[52:55]
	v_mfma_f32_16x16x32_f16 v[52:55], v[8:11], v[104:107], v[64:67]
	s_nop 2
	v_or_b32_e32 v64, s12, v84
	v_ashrrev_i32_e32 v65, 31, v64
	v_mfma_f32_16x16x32_f16 v[60:63], v[4:7], v[104:107], v[60:63]
	v_mfma_f32_16x16x32_f16 v[44:47], v[4:7], v[108:111], v[56:59]
	s_waitcnt lgkmcnt(0)
	v_mfma_f32_16x16x32_f16 v[12:15], v[4:7], v[120:123], v[48:51]
	v_mfma_f32_16x16x32_f16 v[24:27], v[8:11], v[116:119], v[36:39]
	v_mfma_f32_16x16x32_f16 v[56:59], v[96:99], v[104:107], v[68:71]
	v_mfma_f32_16x16x32_f16 v[36:39], v[96:99], v[108:111], v[20:23]
	v_mfma_f32_16x16x32_f16 v[20:23], v[96:99], v[116:119], v[16:19]
	v_mfma_f32_16x16x32_f16 v[4:7], v[96:99], v[120:123], v[72:75]
	v_lshlrev_b64 v[96:97], 2, v[64:65]
	v_lshl_add_u64 v[64:65], s[2:3], 0, v[96:97]
	v_mfma_f32_16x16x32_f16 v[40:43], v[8:11], v[108:111], v[40:43]
	v_mfma_f32_16x16x32_f16 v[8:11], v[8:11], v[120:123], v[32:35]
	v_mfma_f32_16x16x32_f16 v[32:35], v[100:103], v[108:111], v[92:95]
	s_nop 2
	v_add_u32_e32 v92, s0, v85
	s_mov_b32 s0, 0x8000
	v_mfma_f32_16x16x32_f16 v[48:51], v[100:103], v[104:107], v[80:83]
	v_ashrrev_i32_e32 v93, 31, v92
	v_or_b32_e32 v94, 48, v92
	v_ashrrev_i32_e32 v95, 31, v94
	v_add_co_u32_e32 v80, vcc, s0, v64
	v_mfma_f32_16x16x32_f16 v[16:19], v[100:103], v[116:119], v[0:3]
	s_nop 0
	v_addc_co_u32_e32 v81, vcc, 0, v65, vcc
	global_load_dword v64, v[80:81], off
	v_mfma_f32_16x16x32_f16 v[0:3], v[100:103], v[120:123], v[76:79]
	s_waitcnt vmcnt(0)
	v_add_f32_e32 v64, 1.0, v64
	v_mul_f32_e32 v91, 0.5, v64
	v_lshlrev_b64 v[64:65], 12, v[92:93]
	v_lshl_add_u64 v[64:65], s[28:29], 0, v[64:65]
	v_lshl_add_u64 v[82:83], v[64:65], 0, v[96:97]
	global_load_dword v64, v[82:83], off
	v_mul_f32_e32 v60, v60, v91
	s_waitcnt vmcnt(0)
	v_fmac_f32_e32 v60, 0x3fb504f3, v64
	v_or_b32_e32 v64, 1, v92
	v_ashrrev_i32_e32 v65, 31, v64
	v_lshlrev_b64 v[64:65], 12, v[64:65]
	v_lshl_add_u64 v[64:65], s[28:29], 0, v[64:65]
	v_lshl_add_u64 v[76:77], v[64:65], 0, v[96:97]
	global_store_dword v[82:83], v60, off
	global_load_dword v60, v[76:77], off
	s_waitcnt vmcnt(0)
	v_mul_f32_e32 v60, 0x3fb504f3, v60
	v_fmac_f32_e32 v60, v61, v91
	global_store_dword v[76:77], v60, off
	v_or_b32_e32 v60, 2, v92
	v_ashrrev_i32_e32 v61, 31, v60
	v_lshlrev_b64 v[60:61], 12, v[60:61]
	v_lshl_add_u64 v[60:61], s[28:29], 0, v[60:61]
	v_lshl_add_u64 v[78:79], v[60:61], 0, v[96:97]
	global_load_dword v60, v[78:79], off
	s_waitcnt vmcnt(0)
	v_mul_f32_e32 v60, 0x3fb504f3, v60
	v_fmac_f32_e32 v60, v62, v91
	global_store_dword v[78:79], v60, off
	v_or_b32_e32 v60, 3, v92
	v_ashrrev_i32_e32 v61, 31, v60
	v_lshlrev_b64 v[60:61], 12, v[60:61]
	v_lshl_add_u64 v[60:61], s[28:29], 0, v[60:61]
	v_lshl_add_u64 v[72:73], v[60:61], 0, v[96:97]
	global_load_dword v60, v[72:73], off
	s_waitcnt vmcnt(0)
	v_mul_f32_e32 v60, 0x3fb504f3, v60
	v_fmac_f32_e32 v60, v63, v91
	global_store_dword v[72:73], v60, off
	v_or_b32_e32 v60, 16, v92
	v_ashrrev_i32_e32 v61, 31, v60
	v_lshlrev_b64 v[60:61], 12, v[60:61]
	v_lshl_add_u64 v[60:61], s[28:29], 0, v[60:61]
	v_lshl_add_u64 v[74:75], v[60:61], 0, v[96:97]
	global_load_dword v60, v[74:75], off
	s_waitcnt vmcnt(0)
	v_mul_f32_e32 v60, 0x3fb504f3, v60
	v_fmac_f32_e32 v60, v52, v91
	global_store_dword v[74:75], v60, off
	v_or_b32_e32 v60, 17, v92
	v_ashrrev_i32_e32 v61, 31, v60
	v_lshlrev_b64 v[60:61], 12, v[60:61]
	v_lshl_add_u64 v[60:61], s[28:29], 0, v[60:61]
	v_lshl_add_u64 v[68:69], v[60:61], 0, v[96:97]
	global_load_dword v52, v[68:69], off
	s_waitcnt vmcnt(0)
	v_mul_f32_e32 v52, 0x3fb504f3, v52
	v_fmac_f32_e32 v52, v53, v91
	global_store_dword v[68:69], v52, off
	v_or_b32_e32 v52, 18, v92
	v_ashrrev_i32_e32 v53, 31, v52
	v_lshlrev_b64 v[52:53], 12, v[52:53]
	v_lshl_add_u64 v[52:53], s[28:29], 0, v[52:53]
	v_lshl_add_u64 v[70:71], v[52:53], 0, v[96:97]
	global_load_dword v52, v[70:71], off
	s_waitcnt vmcnt(0)
	v_mul_f32_e32 v52, 0x3fb504f3, v52
	v_fmac_f32_e32 v52, v54, v91
	global_store_dword v[70:71], v52, off
	v_or_b32_e32 v52, 19, v92
	v_ashrrev_i32_e32 v53, 31, v52
	v_lshlrev_b64 v[52:53], 12, v[52:53]
	v_lshl_add_u64 v[52:53], s[28:29], 0, v[52:53]
	v_lshl_add_u64 v[64:65], v[52:53], 0, v[96:97]
	global_load_dword v52, v[64:65], off
	s_waitcnt vmcnt(0)
	v_mul_f32_e32 v52, 0x3fb504f3, v52
	v_fmac_f32_e32 v52, v55, v91
	global_store_dword v[64:65], v52, off
	v_or_b32_e32 v52, 32, v92
	v_ashrrev_i32_e32 v53, 31, v52
	v_lshlrev_b64 v[52:53], 12, v[52:53]
	v_lshl_add_u64 v[52:53], s[28:29], 0, v[52:53]
	v_lshl_add_u64 v[66:67], v[52:53], 0, v[96:97]
	global_load_dword v52, v[66:67], off
	s_waitcnt vmcnt(0)
	v_mul_f32_e32 v52, 0x3fb504f3, v52
	v_fmac_f32_e32 v52, v56, v91
	global_store_dword v[66:67], v52, off
	v_or_b32_e32 v52, 33, v92
	v_ashrrev_i32_e32 v53, 31, v52
	v_lshlrev_b64 v[52:53], 12, v[52:53]
	v_lshl_add_u64 v[52:53], s[28:29], 0, v[52:53]
	v_lshl_add_u64 v[60:61], v[52:53], 0, v[96:97]
	global_load_dword v52, v[60:61], off
	s_waitcnt vmcnt(0)
	v_mul_f32_e32 v52, 0x3fb504f3, v52
	v_fmac_f32_e32 v52, v57, v91
	global_store_dword v[60:61], v52, off
	v_or_b32_e32 v52, 34, v92
	v_ashrrev_i32_e32 v53, 31, v52
	v_lshlrev_b64 v[52:53], 12, v[52:53]
	v_lshl_add_u64 v[52:53], s[28:29], 0, v[52:53]
	v_lshl_add_u64 v[62:63], v[52:53], 0, v[96:97]
	global_load_dword v52, v[62:63], off
	s_waitcnt vmcnt(0)
	v_mul_f32_e32 v52, 0x3fb504f3, v52
	v_fmac_f32_e32 v52, v58, v91
	global_store_dword v[62:63], v52, off
	v_or_b32_e32 v52, 35, v92
	v_ashrrev_i32_e32 v53, 31, v52
	v_lshlrev_b64 v[52:53], 12, v[52:53]
	v_lshl_add_u64 v[52:53], s[28:29], 0, v[52:53]
	v_lshl_add_u64 v[56:57], v[52:53], 0, v[96:97]
	global_load_dword v52, v[56:57], off
	s_waitcnt vmcnt(0)
	v_mul_f32_e32 v52, 0x3fb504f3, v52
	v_fmac_f32_e32 v52, v59, v91
	global_store_dword v[56:57], v52, off
	v_lshlrev_b64 v[52:53], 12, v[94:95]
	v_lshl_add_u64 v[52:53], s[28:29], 0, v[52:53]
	v_lshl_add_u64 v[58:59], v[52:53], 0, v[96:97]
	global_load_dword v52, v[58:59], off
	s_waitcnt vmcnt(0)
	v_mul_f32_e32 v52, 0x3fb504f3, v52
	v_fmac_f32_e32 v52, v48, v91
	global_store_dword v[58:59], v52, off
	v_or_b32_e32 v52, 49, v92
	v_ashrrev_i32_e32 v53, 31, v52
	v_lshlrev_b64 v[52:53], 12, v[52:53]
	v_lshl_add_u64 v[52:53], s[28:29], 0, v[52:53]
	v_lshl_add_u64 v[52:53], v[52:53], 0, v[96:97]
	global_load_dword v48, v[52:53], off
	s_waitcnt vmcnt(0)
	v_mul_f32_e32 v48, 0x3fb504f3, v48
	v_fmac_f32_e32 v48, v49, v91
	global_store_dword v[52:53], v48, off
	v_or_b32_e32 v48, 50, v92
	v_ashrrev_i32_e32 v49, 31, v48
	v_lshlrev_b64 v[48:49], 12, v[48:49]
	v_lshl_add_u64 v[48:49], s[28:29], 0, v[48:49]
	v_lshl_add_u64 v[54:55], v[48:49], 0, v[96:97]
	global_load_dword v48, v[54:55], off
	s_waitcnt vmcnt(0)
	v_mul_f32_e32 v48, 0x3fb504f3, v48
	v_fmac_f32_e32 v48, v50, v91
	global_store_dword v[54:55], v48, off
	v_or_b32_e32 v48, 51, v92
	v_ashrrev_i32_e32 v49, 31, v48
	v_lshlrev_b64 v[48:49], 12, v[48:49]
	v_lshl_add_u64 v[48:49], s[28:29], 0, v[48:49]
	v_lshl_add_u64 v[48:49], v[48:49], 0, v[96:97]
	global_load_dword v50, v[48:49], off
	s_waitcnt vmcnt(0)
	v_mul_f32_e32 v50, 0x3fb504f3, v50
	v_fmac_f32_e32 v50, v51, v91
	global_store_dword v[48:49], v50, off
	global_load_dword v50, v[80:81], off offset:64
	s_waitcnt vmcnt(0)
	v_add_f32_e32 v50, 1.0, v50
	global_load_dword v51, v[82:83], off offset:64
	v_mul_f32_e32 v50, 0.5, v50
	v_mul_f32_e32 v44, v44, v50
	s_waitcnt vmcnt(0)
	v_fmac_f32_e32 v44, 0x3fb504f3, v51
	global_store_dword v[82:83], v44, off offset:64
	global_load_dword v44, v[76:77], off offset:64
	s_waitcnt vmcnt(0)
	v_mul_f32_e32 v44, 0x3fb504f3, v44
	v_fmac_f32_e32 v44, v45, v50
	global_store_dword v[76:77], v44, off offset:64
	global_load_dword v44, v[78:79], off offset:64
	s_waitcnt vmcnt(0)
	v_mul_f32_e32 v44, 0x3fb504f3, v44
	v_fmac_f32_e32 v44, v46, v50
	global_store_dword v[78:79], v44, off offset:64
	global_load_dword v44, v[72:73], off offset:64
	s_waitcnt vmcnt(0)
	v_mul_f32_e32 v44, 0x3fb504f3, v44
	v_fmac_f32_e32 v44, v47, v50
	global_store_dword v[72:73], v44, off offset:64
	global_load_dword v44, v[74:75], off offset:64
	s_waitcnt vmcnt(0)
	v_mul_f32_e32 v44, 0x3fb504f3, v44
	v_fmac_f32_e32 v44, v40, v50
	global_load_dword v40, v[68:69], off offset:64
	s_waitcnt vmcnt(0)
	v_mul_f32_e32 v40, 0x3fb504f3, v40
	v_fmac_f32_e32 v40, v41, v50
	global_store_dword v[68:69], v40, off offset:64
	global_load_dword v40, v[70:71], off offset:64
	s_waitcnt vmcnt(0)
	v_mul_f32_e32 v40, 0x3fb504f3, v40
	v_fmac_f32_e32 v40, v42, v50
	global_store_dword v[70:71], v40, off offset:64
	global_load_dword v40, v[64:65], off offset:64
	s_waitcnt vmcnt(0)
	v_mul_f32_e32 v40, 0x3fb504f3, v40
	v_fmac_f32_e32 v40, v43, v50
	global_store_dword v[64:65], v40, off offset:64
	global_load_dword v40, v[66:67], off offset:64
	s_waitcnt vmcnt(0)
	v_mul_f32_e32 v40, 0x3fb504f3, v40
	v_fmac_f32_e32 v40, v36, v50
	global_load_dword v36, v[60:61], off offset:64
	s_waitcnt vmcnt(0)
	v_mul_f32_e32 v36, 0x3fb504f3, v36
	v_fmac_f32_e32 v36, v37, v50
	global_store_dword v[60:61], v36, off offset:64
	global_load_dword v36, v[62:63], off offset:64
	s_waitcnt vmcnt(0)
	v_mul_f32_e32 v36, 0x3fb504f3, v36
	v_fmac_f32_e32 v36, v38, v50
	global_store_dword v[62:63], v36, off offset:64
	global_load_dword v36, v[56:57], off offset:64
	s_waitcnt vmcnt(0)
	v_mul_f32_e32 v36, 0x3fb504f3, v36
	v_fmac_f32_e32 v36, v39, v50
	global_store_dword v[56:57], v36, off offset:64
	global_load_dword v36, v[58:59], off offset:64
	s_waitcnt vmcnt(0)
	v_mul_f32_e32 v36, 0x3fb504f3, v36
	v_fmac_f32_e32 v36, v32, v50
	global_load_dword v32, v[52:53], off offset:64
	s_waitcnt vmcnt(0)
	v_mul_f32_e32 v32, 0x3fb504f3, v32
	v_fmac_f32_e32 v32, v33, v50
	global_store_dword v[52:53], v32, off offset:64
	global_load_dword v32, v[54:55], off offset:64
	s_waitcnt vmcnt(0)
	v_mul_f32_e32 v32, 0x3fb504f3, v32
	v_fmac_f32_e32 v32, v34, v50
	global_store_dword v[54:55], v32, off offset:64
	global_load_dword v32, v[48:49], off offset:64
	s_nop 0
	global_load_dword v33, v[82:83], off offset:128
	s_waitcnt vmcnt(1)
	v_mul_f32_e32 v32, 0x3fb504f3, v32
	v_fmac_f32_e32 v32, v35, v50
	global_store_dword v[74:75], v44, off offset:64
	global_store_dword v[66:67], v40, off offset:64
	global_store_dword v[58:59], v36, off offset:64
	global_store_dword v[48:49], v32, off offset:64
	global_load_dword v32, v[80:81], off offset:128
	s_waitcnt vmcnt(0)
	v_add_f32_e32 v32, 1.0, v32
	v_mul_f32_e32 v32, 0.5, v32
	v_mul_f32_e32 v28, v28, v32
	v_fmac_f32_e32 v28, 0x3fb504f3, v33
	global_store_dword v[82:83], v28, off offset:128
	global_load_dword v28, v[76:77], off offset:128
	s_waitcnt vmcnt(0)
	v_mul_f32_e32 v28, 0x3fb504f3, v28
	v_fmac_f32_e32 v28, v29, v32
	global_store_dword v[76:77], v28, off offset:128
	global_load_dword v28, v[78:79], off offset:128
	s_waitcnt vmcnt(0)
	v_mul_f32_e32 v28, 0x3fb504f3, v28
	v_fmac_f32_e32 v28, v30, v32
	global_store_dword v[78:79], v28, off offset:128
	global_load_dword v28, v[72:73], off offset:128
	s_waitcnt vmcnt(0)
	v_mul_f32_e32 v28, 0x3fb504f3, v28
	v_fmac_f32_e32 v28, v31, v32
	global_store_dword v[72:73], v28, off offset:128
	global_load_dword v28, v[74:75], off offset:128
	s_waitcnt vmcnt(0)
	v_mul_f32_e32 v28, 0x3fb504f3, v28
	v_fmac_f32_e32 v28, v24, v32
	global_load_dword v24, v[68:69], off offset:128
	s_waitcnt vmcnt(0)
	v_mul_f32_e32 v24, 0x3fb504f3, v24
	v_fmac_f32_e32 v24, v25, v32
	global_store_dword v[68:69], v24, off offset:128
	global_load_dword v24, v[70:71], off offset:128
	s_waitcnt vmcnt(0)
	v_mul_f32_e32 v24, 0x3fb504f3, v24
	v_fmac_f32_e32 v24, v26, v32
	global_store_dword v[70:71], v24, off offset:128
	global_load_dword v24, v[64:65], off offset:128
	s_waitcnt vmcnt(0)
	v_mul_f32_e32 v24, 0x3fb504f3, v24
	v_fmac_f32_e32 v24, v27, v32
	global_store_dword v[64:65], v24, off offset:128
	global_load_dword v24, v[66:67], off offset:128
	s_waitcnt vmcnt(0)
	v_mul_f32_e32 v24, 0x3fb504f3, v24
	v_fmac_f32_e32 v24, v20, v32
	global_load_dword v20, v[60:61], off offset:128
	s_waitcnt vmcnt(0)
	v_mul_f32_e32 v20, 0x3fb504f3, v20
	v_fmac_f32_e32 v20, v21, v32
	global_store_dword v[60:61], v20, off offset:128
	global_load_dword v20, v[62:63], off offset:128
	s_waitcnt vmcnt(0)
	v_mul_f32_e32 v20, 0x3fb504f3, v20
	v_fmac_f32_e32 v20, v22, v32
	global_store_dword v[62:63], v20, off offset:128
	global_load_dword v20, v[56:57], off offset:128
	s_waitcnt vmcnt(0)
	v_mul_f32_e32 v20, 0x3fb504f3, v20
	v_fmac_f32_e32 v20, v23, v32
	global_store_dword v[56:57], v20, off offset:128
	global_load_dword v20, v[58:59], off offset:128
	s_waitcnt vmcnt(0)
	v_mul_f32_e32 v20, 0x3fb504f3, v20
	v_fmac_f32_e32 v20, v16, v32
	global_load_dword v16, v[52:53], off offset:128
	s_waitcnt vmcnt(0)
	v_mul_f32_e32 v16, 0x3fb504f3, v16
	v_fmac_f32_e32 v16, v17, v32
	global_store_dword v[52:53], v16, off offset:128
	global_load_dword v16, v[54:55], off offset:128
	s_waitcnt vmcnt(0)
	v_mul_f32_e32 v16, 0x3fb504f3, v16
	v_fmac_f32_e32 v16, v18, v32
	global_store_dword v[54:55], v16, off offset:128
	global_load_dword v16, v[48:49], off offset:128
	s_nop 0
	global_load_dword v17, v[82:83], off offset:192
	s_waitcnt vmcnt(1)
	v_mul_f32_e32 v16, 0x3fb504f3, v16
	v_fmac_f32_e32 v16, v19, v32
	global_store_dword v[74:75], v28, off offset:128
	global_store_dword v[66:67], v24, off offset:128
	global_store_dword v[58:59], v20, off offset:128
	global_store_dword v[48:49], v16, off offset:128
	global_load_dword v16, v[80:81], off offset:192
	s_waitcnt vmcnt(0)
	v_add_f32_e32 v16, 1.0, v16
	v_mul_f32_e32 v16, 0.5, v16
	v_mul_f32_e32 v12, v12, v16
	v_fmac_f32_e32 v12, 0x3fb504f3, v17
	global_store_dword v[82:83], v12, off offset:192
	global_load_dword v12, v[76:77], off offset:192
	s_waitcnt vmcnt(0)
	v_mul_f32_e32 v12, 0x3fb504f3, v12
	v_fmac_f32_e32 v12, v13, v16
	global_store_dword v[76:77], v12, off offset:192
	global_load_dword v12, v[78:79], off offset:192
	s_waitcnt vmcnt(0)
	v_mul_f32_e32 v12, 0x3fb504f3, v12
	v_fmac_f32_e32 v12, v14, v16
	global_store_dword v[78:79], v12, off offset:192
	global_load_dword v12, v[72:73], off offset:192
	s_waitcnt vmcnt(0)
	v_mul_f32_e32 v12, 0x3fb504f3, v12
	v_fmac_f32_e32 v12, v15, v16
	global_store_dword v[72:73], v12, off offset:192
	global_load_dword v12, v[74:75], off offset:192
	s_waitcnt vmcnt(0)
	v_mul_f32_e32 v12, 0x3fb504f3, v12
	v_fmac_f32_e32 v12, v8, v16
	global_load_dword v8, v[68:69], off offset:192
	s_waitcnt vmcnt(0)
	v_mul_f32_e32 v8, 0x3fb504f3, v8
	v_fmac_f32_e32 v8, v9, v16
	global_store_dword v[68:69], v8, off offset:192
	global_load_dword v8, v[70:71], off offset:192
	s_waitcnt vmcnt(0)
	v_mul_f32_e32 v8, 0x3fb504f3, v8
	v_fmac_f32_e32 v8, v10, v16
	global_store_dword v[70:71], v8, off offset:192
	global_load_dword v8, v[64:65], off offset:192
	s_waitcnt vmcnt(0)
	v_mul_f32_e32 v8, 0x3fb504f3, v8
	v_fmac_f32_e32 v8, v11, v16
	global_store_dword v[64:65], v8, off offset:192
	global_load_dword v8, v[66:67], off offset:192
	s_waitcnt vmcnt(0)
	v_mul_f32_e32 v8, 0x3fb504f3, v8
	v_fmac_f32_e32 v8, v4, v16
	global_load_dword v4, v[60:61], off offset:192
	s_waitcnt vmcnt(0)
	v_mul_f32_e32 v4, 0x3fb504f3, v4
	v_fmac_f32_e32 v4, v5, v16
	global_store_dword v[60:61], v4, off offset:192
	global_load_dword v4, v[62:63], off offset:192
	s_waitcnt vmcnt(0)
	v_mul_f32_e32 v4, 0x3fb504f3, v4
	v_fmac_f32_e32 v4, v6, v16
	global_store_dword v[62:63], v4, off offset:192
	global_load_dword v4, v[56:57], off offset:192
	s_waitcnt vmcnt(0)
	v_mul_f32_e32 v4, 0x3fb504f3, v4
	v_fmac_f32_e32 v4, v7, v16
	global_store_dword v[56:57], v4, off offset:192
	global_load_dword v4, v[58:59], off offset:192
	s_waitcnt vmcnt(0)
	v_mul_f32_e32 v4, 0x3fb504f3, v4
	v_fmac_f32_e32 v4, v0, v16
	global_load_dword v0, v[52:53], off offset:192
	s_waitcnt vmcnt(0)
	v_mul_f32_e32 v0, 0x3fb504f3, v0
	v_fmac_f32_e32 v0, v1, v16
	global_store_dword v[52:53], v0, off offset:192
	global_load_dword v0, v[54:55], off offset:192
	s_waitcnt vmcnt(0)
	v_mul_f32_e32 v0, 0x3fb504f3, v0
	v_fmac_f32_e32 v0, v2, v16
	global_store_dword v[54:55], v0, off offset:192
	global_load_dword v0, v[48:49], off offset:192
	s_waitcnt vmcnt(0)
	v_mul_f32_e32 v0, 0x3fb504f3, v0
	v_fmac_f32_e32 v0, v3, v16
	global_store_dword v[74:75], v12, off offset:192
	global_store_dword v[66:67], v8, off offset:192
	global_store_dword v[58:59], v4, off offset:192
	global_store_dword v[48:49], v0, off offset:192
	s_cbranch_scc0 .LBB0_649
